# as version 63 plus packed f32 VALU ops split into single ops in the conv / mixer / final-norm code (bit-identical)
# speedup vs baseline: 1.0032x; 1.0004x over previous
; __device__ __forceinline__ void ssd_scan(const MixP& C, const int wg, const int nwgs, const int tid) {
;     ...
;         const int e = (qi & 2047) * 4, bgh = __builtin_amdgcn_readfirstlane(qi >> 11), hh = bgh & 1, bg = bgh >> 1;
;         float* dp = C.DS + ((size_t)bg * NSC * 2 + hh) * 8192 + e;
;         const float* ep = C.ESC + (size_t)bg * NSC * 2 + hh;
;         f32x4 s = {0.f, 0.f, 0.f, 0.f};
; #pragma unroll 1
;         for (int h0 = 0; h0 < NSC; h0 += NSC / 2) {
;             f32x4 d[NSC / 2]; float E[NSC / 2];
; #pragma unroll
;             for (int k = 0; k < NSC / 2; ++k) { d[k] = *(const f32x4*)(dp + (size_t)(h0 + k) * 2 * 8192); E[k] = ep[(h0 + k) * 2]; }
; #pragma unroll
;             for (int k = 0; k < NSC / 2; ++k) { *(f32x4*)(dp + (size_t)(h0 + k) * 2 * 8192) = s; s = s * E[k] + d[k]; }
;         }
;         const int b = bg >> 1, g = bg & 1;
;         *(f32x4*)(C.out + O_SSMP + (((size_t)C.l * BP + b) * 4 + 2 * g + hh) * 8192 + e) = s;
.LBB0_291:
	s_lshl_b32 s62, s5, 1
	s_lshl_b32 s92, s5, 14
	s_lshl_b64 s[2:3], s[62:63], 2
	s_add_u32 s94, s9, s2
	s_addc_u32 s95, s4, s3
	s_or_b32 s2, s5, 1
	s_lshl_b32 s62, s2, 1
	s_lshl_b32 s88, s2, 14
	s_lshl_b64 s[2:3], s[62:63], 2
	s_add_u32 s90, s9, s2
	s_addc_u32 s91, s4, s3
	s_or_b32 s2, s5, 2
	s_lshl_b32 s62, s2, 1
	s_lshl_b32 s84, s2, 14
	s_lshl_b64 s[2:3], s[62:63], 2
	s_add_u32 s86, s9, s2
	s_addc_u32 s87, s4, s3
	s_or_b32 s2, s5, 3
	s_lshl_b32 s62, s2, 1
	s_lshl_b32 s80, s2, 14
	s_lshl_b64 s[2:3], s[62:63], 2
	s_add_u32 s82, s9, s2
	s_addc_u32 s83, s4, s3
	s_or_b32 s2, s5, 4
	s_lshl_b32 s62, s2, 1
	s_lshl_b32 s30, s2, 14
	s_lshl_b64 s[2:3], s[62:63], 2
	s_add_u32 s22, s9, s2
	s_addc_u32 s23, s4, s3
	s_or_b32 s2, s5, 5
	s_lshl_b32 s62, s2, 1
	s_lshl_b32 s20, s2, 14
	s_lshl_b64 s[2:3], s[62:63], 2
	s_add_u32 s2, s9, s2
	v_cndmask_b32_e64 v5, 0, 1, s[10:11]
	s_addc_u32 s3, s4, s3
	s_or_b32 s10, s5, 6
	s_lshl_b32 s62, s10, 1
	s_lshl_b32 s36, s10, 14
	s_lshl_b64 s[10:11], s[62:63], 2
	s_add_u32 s60, s9, s10
	s_addc_u32 s61, s4, s11
	s_or_b32 s10, s5, 7
	s_lshl_b32 s62, s10, 1
	s_lshl_b32 s26, s10, 14
	s_lshl_b64 s[10:11], s[62:63], 2
	s_add_u32 s24, s9, s10
	s_addc_u32 s25, s4, s11
	s_or_b32 s10, s5, 8
	s_mov_b32 s93, s63
	s_lshl_b32 s62, s10, 1
	v_lshl_add_u64 v[14:15], s[92:93], 2, v[2:3]
	s_lshl_b32 s16, s10, 14
	s_lshl_b64 s[10:11], s[62:63], 2
	global_load_dwordx4 v[10:13], v[14:15], off
	global_load_dword v16, v4, s[94:95]
	s_add_u32 s18, s9, s10
	s_mov_b32 s89, s63
	s_addc_u32 s19, s4, s11
	s_or_b32 s10, s5, 9
	v_lshl_add_u64 v[18:19], s[88:89], 2, v[2:3]
	s_lshl_b32 s62, s10, 1
	global_load_dwordx4 v[18:21], v[18:19], off
	s_nop 0
	global_load_dword v78, v4, s[90:91]
	s_mov_b32 s85, s63
	s_lshl_b32 s12, s10, 14
	s_lshl_b64 s[10:11], s[62:63], 2
	v_lshl_add_u64 v[22:23], s[84:85], 2, v[2:3]
	s_add_u32 s14, s9, s10
	global_load_dwordx4 v[22:25], v[22:23], off
	s_nop 0
	global_load_dword v80, v4, s[86:87]
	s_mov_b32 s81, s63
	s_addc_u32 s15, s4, s11
	s_or_b32 s10, s5, 10
	v_lshl_add_u64 v[26:27], s[80:81], 2, v[2:3]
	s_lshl_b32 s62, s10, 1
	global_load_dwordx4 v[26:29], v[26:27], off
	s_nop 0
	global_load_dword v82, v4, s[82:83]
	s_mov_b32 s31, s63
	s_lshl_b32 s56, s10, 14
	s_lshl_b64 s[10:11], s[62:63], 2
	v_lshl_add_u64 v[30:31], s[30:31], 2, v[2:3]
	s_add_u32 vcc_lo, s9, s10
	global_load_dwordx4 v[30:33], v[30:31], off
	s_nop 0
	global_load_dword v84, v4, s[22:23]
	s_mov_b32 s21, s63
	s_addc_u32 vcc_hi, s4, s11
	s_or_b32 s10, s5, 11
	v_lshl_add_u64 v[34:35], s[20:21], 2, v[2:3]
	s_lshl_b32 s62, s10, 1
	global_load_dwordx4 v[34:37], v[34:35], off
	s_nop 0
	global_load_dword v86, v4, s[2:3]
	s_mov_b32 s37, s63
	s_lshl_b32 s52, s10, 14
	s_lshl_b64 s[10:11], s[62:63], 2
	v_lshl_add_u64 v[38:39], s[36:37], 2, v[2:3]
	s_add_u32 s54, s9, s10
	global_load_dwordx4 v[38:41], v[38:39], off
	s_nop 0
	global_load_dword v88, v4, s[60:61]
	s_mov_b32 s27, s63
	s_addc_u32 s55, s4, s11
	s_or_b32 s10, s5, 12
	v_lshl_add_u64 v[42:43], s[26:27], 2, v[2:3]
	s_lshl_b32 s62, s10, 1
	global_load_dwordx4 v[42:45], v[42:43], off
	s_nop 0
	global_load_dword v90, v4, s[24:25]
	s_mov_b32 s17, s63
	s_lshl_b32 s48, s10, 14
	s_lshl_b64 s[10:11], s[62:63], 2
	v_lshl_add_u64 v[46:47], s[16:17], 2, v[2:3]
	s_add_u32 s50, s9, s10
	global_load_dwordx4 v[46:49], v[46:47], off
	s_nop 0
	global_load_dword v92, v4, s[18:19]
	s_mov_b32 s13, s63
	s_addc_u32 s51, s4, s11
	s_or_b32 s10, s5, 13
	v_lshl_add_u64 v[50:51], s[12:13], 2, v[2:3]
	s_lshl_b32 s62, s10, 1
	global_load_dwordx4 v[50:53], v[50:51], off
	s_nop 0
	global_load_dword v94, v4, s[14:15]
	s_mov_b32 s57, s63
	s_lshl_b32 s44, s10, 14
	s_lshl_b64 s[10:11], s[62:63], 2
	v_lshl_add_u64 v[54:55], s[56:57], 2, v[2:3]
	s_add_u32 s46, s9, s10
	global_load_dwordx4 v[54:57], v[54:55], off
	s_nop 0
	global_load_dword v96, v4, vcc
	s_mov_b32 s53, s63
	s_addc_u32 s47, s4, s11
	s_or_b32 s10, s5, 14
	v_lshl_add_u64 v[58:59], s[52:53], 2, v[2:3]
	s_lshl_b32 s62, s10, 1
	global_load_dwordx4 v[58:61], v[58:59], off
	s_nop 0
	global_load_dword v98, v4, s[54:55]
	s_mov_b32 s49, s63
	s_lshl_b32 s40, s10, 14
	s_lshl_b64 s[10:11], s[62:63], 2
	v_lshl_add_u64 v[62:63], s[48:49], 2, v[2:3]
	s_add_u32 s42, s9, s10
	global_load_dwordx4 v[62:65], v[62:63], off
	s_nop 0
	global_load_dword v100, v4, s[50:51]
	s_mov_b32 s45, s63
	s_addc_u32 s43, s4, s11
	s_or_b32 s5, s5, 15
	v_lshl_add_u64 v[66:67], s[44:45], 2, v[2:3]
	s_lshl_b32 s62, s5, 1
	global_load_dwordx4 v[66:69], v[66:67], off
	s_nop 0
	global_load_dword v102, v4, s[46:47]
	s_mov_b32 s41, s63
	s_lshl_b32 s10, s5, 14
	s_lshl_b64 s[34:35], s[62:63], 2
	v_lshl_add_u64 v[70:71], s[40:41], 2, v[2:3]
	s_mov_b32 s11, s63
	s_add_u32 s34, s9, s34
	global_load_dwordx4 v[70:73], v[70:71], off
	s_nop 0
	global_load_dword v104, v4, s[42:43]
	v_lshl_add_u64 v[74:75], s[10:11], 2, v[2:3]
	s_addc_u32 s35, s4, s35
	global_load_dwordx4 v[74:77], v[74:75], off
	s_nop 0
	global_load_dword v106, v4, s[34:35]
	s_mov_b32 s2, 0xb0000
	global_store_dwordx4 v[14:15], v[6:9], off
	v_cmp_ne_u32_e64 s[38:39], 1, v5
	s_mov_b32 s5, 16
	s_waitcnt vmcnt(31)
	v_fma_f32 v6, v6, v16, v10
	v_fma_f32 v7, v7, v16, v11
	v_add_co_u32_e32 v10, vcc, s8, v14
	v_fma_f32 v8, v8, v16, v12
	v_fma_f32 v9, v9, v16, v13
	s_nop 0
	v_addc_co_u32_e32 v11, vcc, 0, v15, vcc
	global_store_dwordx4 v[10:11], v[6:9], off
	v_add_co_u32_e32 v10, vcc, s6, v14
	s_waitcnt vmcnt(30)
; __device__ __forceinline__ void ssd_scan(const MixP& C, const int wg, const int nwgs, const int tid) {
;     ...
;             for (int k = 0; k < NSC / 2; ++k) { d[k] = *(const f32x4*)(dp + (size_t)(h0 + k) * 2 * 8192); E[k] = ep[(h0 + k) * 2]; }
; #pragma unroll
;             for (int k = 0; k < NSC / 2; ++k) { *(f32x4*)(dp + (size_t)(h0 + k) * 2 * 8192) = s; s = s * E[k] + d[k]; }
;         }
;         const int b = bg >> 1, g = bg & 1;
;         *(f32x4*)(C.out + O_SSMP + (((size_t)C.l * BP + b) * 4 + 2 * g + hh) * 8192 + e) = s;
	v_fma_f32 v8, v8, v78, v20
	v_fma_f32 v9, v9, v78, v21
	v_fma_f32 v6, v6, v78, v18
	v_fma_f32 v7, v7, v78, v19
	v_addc_co_u32_e32 v11, vcc, 0, v15, vcc
	global_store_dwordx4 v[10:11], v[6:9], off
	v_add_co_u32_e32 v10, vcc, s7, v14
	s_waitcnt vmcnt(29)
	v_fma_f32 v8, v8, v80, v24
	v_fma_f32 v9, v9, v80, v25
	v_fma_f32 v6, v6, v80, v22
	v_fma_f32 v7, v7, v80, v23
	v_addc_co_u32_e32 v11, vcc, 0, v15, vcc
	global_store_dwordx4 v[10:11], v[6:9], off
	v_add_co_u32_e32 v10, vcc, s97, v14
	s_waitcnt vmcnt(28)
	v_fma_f32 v8, v8, v82, v28
	v_fma_f32 v9, v9, v82, v29
	v_fma_f32 v6, v6, v82, v26
	v_fma_f32 v7, v7, v82, v27
	v_addc_co_u32_e32 v11, vcc, 0, v15, vcc
	global_store_dwordx4 v[10:11], v[6:9], off
	v_add_co_u32_e32 v10, vcc, s96, v14
	s_waitcnt vmcnt(27)
	v_fma_f32 v8, v8, v84, v32
	v_fma_f32 v9, v9, v84, v33
	v_fma_f32 v6, v6, v84, v30
	v_fma_f32 v7, v7, v84, v31
	v_addc_co_u32_e32 v11, vcc, 0, v15, vcc
	global_store_dwordx4 v[10:11], v[6:9], off
	v_add_co_u32_e32 v10, vcc, s33, v14
	s_waitcnt vmcnt(26)
	v_fma_f32 v8, v8, v86, v36
	v_fma_f32 v9, v9, v86, v37
	v_fma_f32 v6, v6, v86, v34
	v_fma_f32 v7, v7, v86, v35
	v_addc_co_u32_e32 v11, vcc, 0, v15, vcc
	global_store_dwordx4 v[10:11], v[6:9], off
	v_add_co_u32_e32 v10, vcc, s64, v14
	s_waitcnt vmcnt(25)
	v_fma_f32 v8, v8, v88, v40
	v_fma_f32 v9, v9, v88, v41
	v_fma_f32 v6, v6, v88, v38
	v_fma_f32 v7, v7, v88, v39
	v_addc_co_u32_e32 v11, vcc, 0, v15, vcc
	global_store_dwordx4 v[10:11], v[6:9], off
	v_add_co_u32_e32 v10, vcc, s66, v14
	s_waitcnt vmcnt(24)
	v_fma_f32 v8, v8, v90, v44
	v_fma_f32 v9, v9, v90, v45
	v_fma_f32 v6, v6, v90, v42
	v_fma_f32 v7, v7, v90, v43
	v_addc_co_u32_e32 v11, vcc, 0, v15, vcc
	global_store_dwordx4 v[10:11], v[6:9], off
	v_add_co_u32_e32 v10, vcc, s65, v14
	s_waitcnt vmcnt(23)
	v_fma_f32 v8, v8, v92, v48
	v_fma_f32 v9, v9, v92, v49
	v_fma_f32 v6, v6, v92, v46
	v_fma_f32 v7, v7, v92, v47
	v_addc_co_u32_e32 v11, vcc, 0, v15, vcc
	global_store_dwordx4 v[10:11], v[6:9], off
	v_add_co_u32_e32 v10, vcc, s67, v14
	s_waitcnt vmcnt(22)
	v_fma_f32 v8, v8, v94, v52
	v_fma_f32 v9, v9, v94, v53
	v_fma_f32 v6, v6, v94, v50
	v_fma_f32 v7, v7, v94, v51
	v_addc_co_u32_e32 v11, vcc, 0, v15, vcc
	global_store_dwordx4 v[10:11], v[6:9], off
	v_add_co_u32_e32 v10, vcc, s2, v14
	s_waitcnt vmcnt(21)
	v_fma_f32 v8, v8, v96, v56
	v_fma_f32 v9, v9, v96, v57
	v_fma_f32 v6, v6, v96, v54
	v_fma_f32 v7, v7, v96, v55
	v_addc_co_u32_e32 v11, vcc, 0, v15, vcc
	s_mov_b32 s2, 0xc0000
	global_store_dwordx4 v[10:11], v[6:9], off
	v_add_co_u32_e32 v10, vcc, s2, v14
	s_waitcnt vmcnt(20)
	v_fma_f32 v8, v8, v98, v60
	v_fma_f32 v9, v9, v98, v61
	v_fma_f32 v6, v6, v98, v58
	v_fma_f32 v7, v7, v98, v59
	v_addc_co_u32_e32 v11, vcc, 0, v15, vcc
	s_mov_b32 s2, 0xd0000
	global_store_dwordx4 v[10:11], v[6:9], off
	v_add_co_u32_e32 v10, vcc, s2, v14
	s_waitcnt vmcnt(19)
	v_fma_f32 v8, v8, v100, v64
	v_fma_f32 v9, v9, v100, v65
	v_fma_f32 v6, v6, v100, v62
	v_fma_f32 v7, v7, v100, v63
	v_addc_co_u32_e32 v11, vcc, 0, v15, vcc
	s_mov_b32 s2, 0xe0000
	global_store_dwordx4 v[10:11], v[6:9], off
	v_add_co_u32_e32 v10, vcc, s2, v14
	s_waitcnt vmcnt(18)
	v_fma_f32 v8, v8, v102, v68
	v_fma_f32 v9, v9, v102, v69
	v_fma_f32 v6, v6, v102, v66
	v_fma_f32 v7, v7, v102, v67
	v_addc_co_u32_e32 v11, vcc, 0, v15, vcc
	s_mov_b32 s2, 0xf0000
	global_store_dwordx4 v[10:11], v[6:9], off
	v_add_co_u32_e32 v10, vcc, s2, v14
	s_waitcnt vmcnt(17)
	v_fma_f32 v8, v8, v104, v72
	v_fma_f32 v9, v9, v104, v73
	v_fma_f32 v6, v6, v104, v70
	v_fma_f32 v7, v7, v104, v71
	v_addc_co_u32_e32 v11, vcc, 0, v15, vcc
	global_store_dwordx4 v[10:11], v[6:9], off
	s_mov_b64 s[10:11], 0
	s_and_b64 vcc, exec, s[38:39]
	s_waitcnt vmcnt(16)
	v_fma_f32 v8, v8, v106, v76
	v_fma_f32 v9, v9, v106, v77
	v_fma_f32 v6, v6, v106, v74
	v_fma_f32 v7, v7, v106, v75
	s_cbranch_vccz .LBB0_291
	s_ashr_i32 s2, s69, 13
	s_ashr_i32 s3, s2, 31
	s_lshl_b64 s[2:3], s[2:3], 2
	v_readlane_b32 s4, v255, 29
	v_readlane_b32 s5, v255, 30
	s_add_u32 s2, s2, s4
	s_addc_u32 s3, s3, s5
	s_lshl_b32 s4, s76, 1
	s_and_b32 s4, s4, 2
	s_or_b32 s2, s2, s4
	s_or_b64 s[2:3], s[2:3], s[70:71]
	v_readlane_b32 s4, v254, 19
	s_lshl_b64 s[2:3], s[2:3], 15
	v_readlane_b32 s5, v254, 20
	v_readlane_b32 s84, v254, 24
	v_readlane_b32 s86, v254, 28
	v_readlane_b32 s92, v254, 34
	v_readlane_b32 s94, v254, 36
	v_readlane_b32 s34, v254, 50
	v_readlane_b32 s26, v252, 31
	v_readlane_b32 s82, v255, 46
	v_readlane_b32 s76, v255, 48
	v_lshl_add_u64 v[2:3], v[132:133], 0, s[2:3]
	s_mov_b64 s[60:61], s[4:5]
	v_readlane_b32 s90, v254, 63
	v_readlane_b32 s91, v254, 23
	v_readlane_b32 s85, v254, 25
	v_readlane_b32 s87, v254, 29
	v_readlane_b32 s88, v254, 30
	v_readlane_b32 s89, v254, 31
	v_readlane_b32 s93, v254, 35
	v_readlane_b32 s95, v254, 37
	v_readlane_b32 s35, v254, 51
	v_readlane_b32 s27, v252, 32
	s_movk_i32 s30, 0xc0
	s_movk_i32 s31, 0x2000
	s_movk_i32 s55, 0x1a00
	v_readlane_b32 s96, v254, 52
	v_readlane_b32 s33, v254, 53
	s_movk_i32 s64, 0x50
	s_movk_i32 s97, 0xffb4
	s_mov_b32 s80, s75
	v_readlane_b32 s83, v255, 47
	v_readlane_b32 s77, v255, 49
	global_store_dwordx4 v[2:3], v[6:9], off
	v_readlane_b32 s6, v254, 21
	v_readlane_b32 s7, v254, 22

; __device__ __forceinline__ void ssd_scan(const MixP& C, const int wg, const int nwgs, const int tid) {
;     ...
;         const int e = (qi & 2047) * 4, bgh = __builtin_amdgcn_readfirstlane(qi >> 11), hh = bgh & 1, bg = bgh >> 1;
;         float* dp = C.DS + ((size_t)bg * NSC * 2 + hh) * 8192 + e;
;         const float* ep = C.ESC + (size_t)bg * NSC * 2 + hh;
;         f32x4 s = {0.f, 0.f, 0.f, 0.f};
; #pragma unroll 1
;         for (int h0 = 0; h0 < NSC; h0 += NSC / 2) {
;             f32x4 d[NSC / 2]; float E[NSC / 2];
; #pragma unroll
;             for (int k = 0; k < NSC / 2; ++k) { d[k] = *(const f32x4*)(dp + (size_t)(h0 + k) * 2 * 8192); E[k] = ep[(h0 + k) * 2]; }
; #pragma unroll
;             for (int k = 0; k < NSC / 2; ++k) { *(f32x4*)(dp + (size_t)(h0 + k) * 2 * 8192) = s; s = s * E[k] + d[k]; }
;         }
;         const int b = bg >> 1, g = bg & 1;
;         *(f32x4*)(C.out + O_SSMP + (((size_t)C.l * BP + b) * 4 + 2 * g + hh) * 8192 + e) = s;
.LBB0_314:
	s_lshl_b32 s62, s3, 1
	v_cndmask_b32_e64 v5, 0, 1, s[10:11]
	s_lshl_b32 s92, s3, 14
	s_lshl_b64 s[10:11], s[62:63], 2
	s_add_u32 s94, s5, s10
	s_addc_u32 s95, s9, s11
	s_or_b32 s2, s3, 1
	s_lshl_b32 s62, s2, 1
	s_lshl_b32 s88, s2, 14
	s_lshl_b64 s[10:11], s[62:63], 2
	s_add_u32 s90, s5, s10
	s_addc_u32 s91, s9, s11
	s_or_b32 s2, s3, 2
	s_lshl_b32 s62, s2, 1
	s_lshl_b32 s84, s2, 14
	s_lshl_b64 s[10:11], s[62:63], 2
	s_add_u32 s86, s5, s10
	s_addc_u32 s87, s9, s11
	s_or_b32 s2, s3, 3
	s_lshl_b32 s62, s2, 1
	s_lshl_b32 s80, s2, 14
	s_lshl_b64 s[10:11], s[62:63], 2
	s_add_u32 s82, s5, s10
	s_addc_u32 s83, s9, s11
	s_or_b32 s2, s3, 4
	s_lshl_b32 s62, s2, 1
	s_lshl_b32 s22, s2, 14
	s_lshl_b64 s[10:11], s[62:63], 2
	s_add_u32 s34, s5, s10
	s_addc_u32 s35, s9, s11
	s_or_b32 s10, s3, 5
	s_lshl_b32 s62, s10, 1
	s_lshl_b32 s2, s10, 14
	s_lshl_b64 s[10:11], s[62:63], 2
	s_add_u32 s30, s5, s10
	s_addc_u32 s31, s9, s11
	s_or_b32 s10, s3, 6
	s_lshl_b32 s62, s10, 1
	s_lshl_b32 s60, s10, 14
	s_lshl_b64 s[10:11], s[62:63], 2
	s_add_u32 s20, s5, s10
	s_addc_u32 s21, s9, s11
	s_or_b32 s10, s3, 7
	s_lshl_b32 s62, s10, 1
	s_lshl_b32 s26, s10, 14
	s_lshl_b64 s[10:11], s[62:63], 2
	s_add_u32 s36, s5, s10
	s_addc_u32 s37, s9, s11
	s_or_b32 s10, s3, 8
	s_lshl_b32 s62, s10, 1
	s_lshl_b32 s16, s10, 14
	s_lshl_b64 s[10:11], s[62:63], 2
	s_add_u32 s18, s5, s10
	s_addc_u32 s19, s9, s11
	s_or_b32 s10, s3, 9
	s_lshl_b32 s62, s10, 1
	s_lshl_b32 s12, s10, 14
	s_lshl_b64 s[10:11], s[62:63], 2
	s_add_u32 s14, s5, s10
	s_addc_u32 s15, s9, s11
	s_or_b32 s10, s3, 10
	s_lshl_b32 s62, s10, 1
	s_lshl_b32 s56, s10, 14
	s_lshl_b64 s[10:11], s[62:63], 2
	s_add_u32 vcc_lo, s5, s10
	s_addc_u32 vcc_hi, s9, s11
	s_or_b32 s10, s3, 11
	s_lshl_b32 s62, s10, 1
	s_lshl_b32 s52, s10, 14
	s_lshl_b64 s[10:11], s[62:63], 2
	s_add_u32 s54, s5, s10
	s_addc_u32 s55, s9, s11
	s_or_b32 s10, s3, 12
	s_lshl_b32 s62, s10, 1
	s_lshl_b32 s48, s10, 14
	s_lshl_b64 s[10:11], s[62:63], 2
	s_mov_b32 s93, s63
	s_add_u32 s50, s5, s10
	v_lshl_add_u64 v[14:15], s[92:93], 2, v[2:3]
	s_addc_u32 s51, s9, s11
	s_or_b32 s10, s3, 13
	global_load_dwordx4 v[10:13], v[14:15], off
	global_load_dword v16, v4, s[94:95]
	s_lshl_b32 s62, s10, 1
	s_mov_b32 s89, s63
	s_lshl_b32 s44, s10, 14
	s_lshl_b64 s[10:11], s[62:63], 2
	v_lshl_add_u64 v[18:19], s[88:89], 2, v[2:3]
	s_add_u32 s46, s5, s10
	global_load_dwordx4 v[18:21], v[18:19], off
	s_nop 0
	global_load_dword v78, v4, s[90:91]
	s_mov_b32 s85, s63
	s_addc_u32 s47, s9, s11
	s_or_b32 s10, s3, 14
	v_lshl_add_u64 v[22:23], s[84:85], 2, v[2:3]
	s_lshl_b32 s62, s10, 1
	global_load_dwordx4 v[22:25], v[22:23], off
	s_nop 0
	global_load_dword v80, v4, s[86:87]
	s_mov_b32 s81, s63
	s_lshl_b32 s40, s10, 14
	s_lshl_b64 s[10:11], s[62:63], 2
	v_lshl_add_u64 v[26:27], s[80:81], 2, v[2:3]
	s_add_u32 s42, s5, s10
	global_load_dwordx4 v[26:29], v[26:27], off
	s_nop 0
	global_load_dword v82, v4, s[82:83]
	s_mov_b32 s23, s63
	s_addc_u32 s43, s9, s11
	s_or_b32 s3, s3, 15
	v_lshl_add_u64 v[30:31], s[22:23], 2, v[2:3]
	s_lshl_b32 s10, s3, 14
	s_lshl_b32 s62, s3, 1
	global_load_dwordx4 v[30:33], v[30:31], off
	s_nop 0
	global_load_dword v84, v4, s[34:35]
	s_mov_b32 s3, s63
	v_lshl_add_u64 v[34:35], s[2:3], 2, v[2:3]
	global_load_dwordx4 v[34:37], v[34:35], off
	s_nop 0
	global_load_dword v86, v4, s[30:31]
	s_mov_b32 s61, s63
	v_lshl_add_u64 v[38:39], s[60:61], 2, v[2:3]
	global_load_dwordx4 v[38:41], v[38:39], off
	s_nop 0
	global_load_dword v88, v4, s[20:21]
	s_mov_b32 s27, s63
	v_lshl_add_u64 v[42:43], s[26:27], 2, v[2:3]
	global_load_dwordx4 v[42:45], v[42:43], off
	s_nop 0
	global_load_dword v90, v4, s[36:37]
	s_mov_b32 s17, s63
	v_lshl_add_u64 v[46:47], s[16:17], 2, v[2:3]
	global_load_dwordx4 v[46:49], v[46:47], off
	s_nop 0
	global_load_dword v92, v4, s[18:19]
	s_mov_b32 s13, s63
	v_lshl_add_u64 v[50:51], s[12:13], 2, v[2:3]
	global_load_dwordx4 v[50:53], v[50:51], off
	s_nop 0
	global_load_dword v94, v4, s[14:15]
	s_mov_b32 s57, s63
	v_lshl_add_u64 v[54:55], s[56:57], 2, v[2:3]
	global_load_dwordx4 v[54:57], v[54:55], off
	s_nop 0
	global_load_dword v96, v4, vcc
	s_mov_b32 s53, s63
	v_lshl_add_u64 v[58:59], s[52:53], 2, v[2:3]
	global_load_dwordx4 v[58:61], v[58:59], off
	s_nop 0
	global_load_dword v98, v4, s[54:55]
	s_mov_b32 s49, s63
	v_lshl_add_u64 v[62:63], s[48:49], 2, v[2:3]
	global_load_dwordx4 v[62:65], v[62:63], off
	s_nop 0
	global_load_dword v100, v4, s[50:51]
	s_mov_b32 s45, s63
	v_lshl_add_u64 v[66:67], s[44:45], 2, v[2:3]
	global_load_dwordx4 v[66:69], v[66:67], off
	s_nop 0
	global_load_dword v102, v4, s[46:47]
	s_mov_b32 s41, s63
	s_lshl_b64 s[24:25], s[62:63], 2
	v_lshl_add_u64 v[70:71], s[40:41], 2, v[2:3]
	s_mov_b32 s11, s63
	s_add_u32 s24, s5, s24
	global_load_dwordx4 v[70:73], v[70:71], off
	s_nop 0
	global_load_dword v104, v4, s[42:43]
	v_lshl_add_u64 v[74:75], s[10:11], 2, v[2:3]
	s_addc_u32 s25, s9, s25
	global_load_dwordx4 v[74:77], v[74:75], off
	s_nop 0
	global_load_dword v106, v4, s[24:25]
	s_mov_b32 s2, 0xb0000
	global_store_dwordx4 v[14:15], v[6:9], off
	v_cmp_ne_u32_e64 s[38:39], 1, v5
	s_mov_b32 s3, 16
	s_mov_b64 s[10:11], 0
	s_waitcnt vmcnt(31)
	v_fma_f32 v6, v6, v16, v10
	v_fma_f32 v7, v7, v16, v11
	v_add_co_u32_e32 v10, vcc, s4, v14
	v_fma_f32 v8, v8, v16, v12
	v_fma_f32 v9, v9, v16, v13
	s_nop 0
	v_addc_co_u32_e32 v11, vcc, 0, v15, vcc
	global_store_dwordx4 v[10:11], v[6:9], off
	v_add_co_u32_e32 v10, vcc, s6, v14
	s_waitcnt vmcnt(30)
; __device__ __forceinline__ void ssd_scan(const MixP& C, const int wg, const int nwgs, const int tid) {
;     ...
;             for (int k = 0; k < NSC / 2; ++k) { d[k] = *(const f32x4*)(dp + (size_t)(h0 + k) * 2 * 8192); E[k] = ep[(h0 + k) * 2]; }
; #pragma unroll
;             for (int k = 0; k < NSC / 2; ++k) { *(f32x4*)(dp + (size_t)(h0 + k) * 2 * 8192) = s; s = s * E[k] + d[k]; }
;         }
;         const int b = bg >> 1, g = bg & 1;
;         *(f32x4*)(C.out + O_SSMP + (((size_t)C.l * BP + b) * 4 + 2 * g + hh) * 8192 + e) = s;
	v_fma_f32 v8, v8, v78, v20
	v_fma_f32 v9, v9, v78, v21
	v_fma_f32 v6, v6, v78, v18
	v_fma_f32 v7, v7, v78, v19
	v_addc_co_u32_e32 v11, vcc, 0, v15, vcc
	global_store_dwordx4 v[10:11], v[6:9], off
	v_add_co_u32_e32 v10, vcc, s7, v14
	s_waitcnt vmcnt(29)
	v_fma_f32 v8, v8, v80, v24
	v_fma_f32 v9, v9, v80, v25
	v_fma_f32 v6, v6, v80, v22
	v_fma_f32 v7, v7, v80, v23
	v_addc_co_u32_e32 v11, vcc, 0, v15, vcc
	global_store_dwordx4 v[10:11], v[6:9], off
	v_add_co_u32_e32 v10, vcc, s97, v14
	s_waitcnt vmcnt(28)
	v_fma_f32 v8, v8, v82, v28
	v_fma_f32 v9, v9, v82, v29
	v_fma_f32 v6, v6, v82, v26
	v_fma_f32 v7, v7, v82, v27
	v_addc_co_u32_e32 v11, vcc, 0, v15, vcc
	global_store_dwordx4 v[10:11], v[6:9], off
	v_add_co_u32_e32 v10, vcc, s96, v14
	s_waitcnt vmcnt(27)
	v_fma_f32 v8, v8, v84, v32
	v_fma_f32 v9, v9, v84, v33
	v_fma_f32 v6, v6, v84, v30
	v_fma_f32 v7, v7, v84, v31
	v_addc_co_u32_e32 v11, vcc, 0, v15, vcc
	global_store_dwordx4 v[10:11], v[6:9], off
	v_add_co_u32_e32 v10, vcc, s33, v14
	s_waitcnt vmcnt(26)
	v_fma_f32 v8, v8, v86, v36
	v_fma_f32 v9, v9, v86, v37
	v_fma_f32 v6, v6, v86, v34
	v_fma_f32 v7, v7, v86, v35
	v_addc_co_u32_e32 v11, vcc, 0, v15, vcc
	global_store_dwordx4 v[10:11], v[6:9], off
	v_add_co_u32_e32 v10, vcc, s64, v14
	s_waitcnt vmcnt(25)
	v_fma_f32 v8, v8, v88, v40
	v_fma_f32 v9, v9, v88, v41
	v_fma_f32 v6, v6, v88, v38
	v_fma_f32 v7, v7, v88, v39
	v_addc_co_u32_e32 v11, vcc, 0, v15, vcc
	global_store_dwordx4 v[10:11], v[6:9], off
	v_add_co_u32_e32 v10, vcc, s66, v14
	s_waitcnt vmcnt(24)
	v_fma_f32 v8, v8, v90, v44
	v_fma_f32 v9, v9, v90, v45
	v_fma_f32 v6, v6, v90, v42
	v_fma_f32 v7, v7, v90, v43
	v_addc_co_u32_e32 v11, vcc, 0, v15, vcc
	global_store_dwordx4 v[10:11], v[6:9], off
	v_add_co_u32_e32 v10, vcc, s65, v14
	s_waitcnt vmcnt(23)
	v_fma_f32 v8, v8, v92, v48
	v_fma_f32 v9, v9, v92, v49
	v_fma_f32 v6, v6, v92, v46
	v_fma_f32 v7, v7, v92, v47
	v_addc_co_u32_e32 v11, vcc, 0, v15, vcc
	global_store_dwordx4 v[10:11], v[6:9], off
	v_add_co_u32_e32 v10, vcc, s67, v14
	s_waitcnt vmcnt(22)
	v_fma_f32 v8, v8, v94, v52
	v_fma_f32 v9, v9, v94, v53
	v_fma_f32 v6, v6, v94, v50
	v_fma_f32 v7, v7, v94, v51
	v_addc_co_u32_e32 v11, vcc, 0, v15, vcc
	global_store_dwordx4 v[10:11], v[6:9], off
	v_add_co_u32_e32 v10, vcc, s2, v14
	s_waitcnt vmcnt(21)
	v_fma_f32 v8, v8, v96, v56
	v_fma_f32 v9, v9, v96, v57
	v_fma_f32 v6, v6, v96, v54
	v_fma_f32 v7, v7, v96, v55
	v_addc_co_u32_e32 v11, vcc, 0, v15, vcc
	s_mov_b32 s2, 0xc0000
	global_store_dwordx4 v[10:11], v[6:9], off
	v_add_co_u32_e32 v10, vcc, s2, v14
	s_waitcnt vmcnt(20)
	v_fma_f32 v8, v8, v98, v60
	v_fma_f32 v9, v9, v98, v61
	v_fma_f32 v6, v6, v98, v58
	v_fma_f32 v7, v7, v98, v59
	v_addc_co_u32_e32 v11, vcc, 0, v15, vcc
	s_mov_b32 s2, 0xd0000
	global_store_dwordx4 v[10:11], v[6:9], off
	v_add_co_u32_e32 v10, vcc, s2, v14
	s_waitcnt vmcnt(19)
	v_fma_f32 v8, v8, v100, v64
	v_fma_f32 v9, v9, v100, v65
	v_fma_f32 v6, v6, v100, v62
	v_fma_f32 v7, v7, v100, v63
	v_addc_co_u32_e32 v11, vcc, 0, v15, vcc
	s_mov_b32 s2, 0xe0000
	global_store_dwordx4 v[10:11], v[6:9], off
	v_add_co_u32_e32 v10, vcc, s2, v14
	s_waitcnt vmcnt(18)
	v_fma_f32 v8, v8, v102, v68
	v_fma_f32 v9, v9, v102, v69
	v_fma_f32 v6, v6, v102, v66
	v_fma_f32 v7, v7, v102, v67
	v_addc_co_u32_e32 v11, vcc, 0, v15, vcc
	s_mov_b32 s2, 0xf0000
	global_store_dwordx4 v[10:11], v[6:9], off
	v_add_co_u32_e32 v10, vcc, s2, v14
	s_waitcnt vmcnt(17)
	v_fma_f32 v8, v8, v104, v72
	v_fma_f32 v9, v9, v104, v73
	v_fma_f32 v6, v6, v104, v70
	v_fma_f32 v7, v7, v104, v71
	v_addc_co_u32_e32 v11, vcc, 0, v15, vcc
	global_store_dwordx4 v[10:11], v[6:9], off
	s_and_b64 vcc, exec, s[38:39]
	s_waitcnt vmcnt(16)
	v_fma_f32 v8, v8, v106, v76
	v_fma_f32 v9, v9, v106, v77
	v_fma_f32 v6, v6, v106, v74
	v_fma_f32 v7, v7, v106, v75
	s_cbranch_vccz .LBB0_314
	s_ashr_i32 s2, s69, 13
	s_ashr_i32 s3, s2, 31
	s_lshl_b64 s[2:3], s[2:3], 2
	v_readlane_b32 s4, v255, 29
	v_readlane_b32 s5, v255, 30
	s_add_u32 s2, s2, s4
	s_addc_u32 s3, s3, s5
	s_lshl_b32 s4, s76, 1
	s_and_b32 s4, s4, 2
	s_or_b32 s2, s2, s4
	s_or_b64 s[2:3], s[2:3], s[72:73]
	v_readlane_b32 s4, v254, 19
	s_lshl_b64 s[2:3], s[2:3], 15
	v_readlane_b32 s5, v254, 20
	v_readlane_b32 s84, v254, 24
	v_readlane_b32 s86, v254, 28
	v_readlane_b32 s92, v254, 34
	v_readlane_b32 s94, v254, 36
	v_readlane_b32 s34, v254, 50
	v_readlane_b32 s26, v252, 31
	v_readlane_b32 s82, v255, 46
	v_readlane_b32 s36, v255, 48
	v_lshl_add_u64 v[2:3], v[132:133], 0, s[2:3]
	s_mov_b64 s[60:61], s[4:5]
	v_readlane_b32 s90, v254, 63
	v_readlane_b32 s91, v254, 23
	v_readlane_b32 s85, v254, 25
	v_readlane_b32 s87, v254, 29
	v_readlane_b32 s88, v254, 30
	v_readlane_b32 s89, v254, 31
	v_readlane_b32 s93, v254, 35
	v_readlane_b32 s95, v254, 37
	v_readlane_b32 s35, v254, 51
	v_readlane_b32 s27, v252, 32
	s_movk_i32 s30, 0xc0
	s_movk_i32 s31, 0x2000
	s_movk_i32 s55, 0x1a00
	v_readlane_b32 s96, v254, 52
	v_readlane_b32 s33, v254, 53
	s_movk_i32 s64, 0x50
	s_movk_i32 s97, 0xffb4
	s_mov_b32 s80, s75
	v_readlane_b32 s83, v255, 47
	s_mov_b32 s75, s68
	s_mov_b32 s68, s77
	v_readlane_b32 s37, v255, 49
	global_store_dwordx4 v[2:3], v[6:9], off
	v_readlane_b32 s6, v254, 21
	v_readlane_b32 s7, v254, 22

; #define LDS_BARRIER() asm volatile("s_waitcnt lgkmcnt(0)\n\ts_barrier" ::: "memory")
; __device__ __forceinline__ unsigned cvtpk(float lo, float hi) { const f32x2v v = {lo, hi}; return __builtin_bit_cast(unsigned, __builtin_convertvector(v, bf16x2v)); }
; #define MFMA16(a, b, c) __builtin_amdgcn_mfma_f32_16x16x32_bf16((a), (b), (c), 0, 0, 0)
; __device__ __forceinline__ void pool_item(LAS unsigned char* L, const MixP& C, const int tile, const int tid) {
;     ...
;     {
;         const int w8 = __builtin_amdgcn_readfirstlane(tid >> 6), lane = tid & 63, q = lane >> 4, r16 = lane & 15, g = w8 >> 1, dh = w8 & 1;
;         f32x4 acc[2][4];
; #pragma unroll
;         for (int a = 0; a < 2; ++a)
; #pragma unroll
;             for (int b = 0; b < 4; ++b) acc[a][b] = (f32x4){0.f, 0.f, 0.f, 0.f};
; #pragma unroll
;         for (int ks = 0; ks < 2; ++ks) {
;             bf16x8 wa[2], db[4];
; #pragma unroll
;             for (int a = 0; a < 2; ++a) wa[a] = frag16(L + WT_OFF + g * 9216 + (16 * (2 * dh + a) + r16) * 144 + (32 * ks + 8 * q) * 2);
; #pragma unroll
;             for (int b = 0; b < 4; ++b) db[b] = frag16(L + DF_OFF + (16 * b + r16) * 528 + (g * 64 + 32 * ks + 8 * q) * 2);
; #pragma unroll
;             for (int a = 0; a < 2; ++a)
; #pragma unroll
;                 for (int b = 0; b < 4; ++b) acc[a][b] = MFMA16(wa[a], db[b], acc[a][b]);
;         }
; #pragma unroll
;         for (int a = 0; a < 2; ++a) {
;             const int d0 = g * 64 + 16 * (2 * dh + a) + 4 * q;
;             const f32x4 sc = *(const f32x4*)(C.pool_scale + d0);
; #pragma unroll
;             for (int b = 0; b < 4; ++b) { const f32x4 v = acc[a][b] * sc; v2u o; o.x = cvtpk(v[0], v[1]); o.y = cvtpk(v[2], v[3]);
;                 *(v2u*)(C.mixb + (size_t)(m0 + 16 * b + r16) * D + MC_POOL + d0) = o; }
;         }
;     }
;     LDS_BARRIER();
.LBB0_381:
	v_readfirstlane_b32 s0, v134
	s_ashr_i32 s1, s0, 7
	s_lshr_b32 s3, s0, 1
	v_bfe_u32 v2, v134, 4, 2
	v_and_b32_e32 v3, 15, v134
	s_mul_i32 s2, s1, 0x2400
	s_and_b32 s3, s3, 32
	s_and_b32 s0, s0, 0xffffff80
	s_add_i32 s2, s2, 0
	v_or_b32_e32 v5, s3, v3
	v_lshlrev_b32_e32 v14, 4, v2
	s_add_i32 s0, s0, 0
	v_mul_u32_u24_e32 v15, 0x210, v3
	s_add_i32 s2, s2, 0x12400
	v_mul_u32_u24_e32 v5, 0x90, v5
	v_add3_u32 v54, s0, v14, v15
	s_waitcnt lgkmcnt(0)
	s_barrier
	v_add3_u32 v5, s2, v14, v5
	v_add_u32_e32 v58, 0x6300, v54
	ds_read_b128 v[6:9], v5
	ds_read_b128 v[10:13], v5 offset:2304
	ds_read_b128 v[14:17], v54 offset:40960
	ds_read_b128 v[18:21], v54 offset:49408
	ds_read_b128 v[22:25], v54 offset:57856
	ds_read_b128 v[26:29], v58 offset:40960
	s_waitcnt lgkmcnt(3)
	v_mfma_f32_16x16x32_bf16 v[30:33], v[6:9], v[14:17], 0
	v_lshlrev_b32_e32 v2, 2, v2
	v_lshl_or_b32 v2, s1, 6, v2
	v_readlane_b32 s0, v255, 9
	s_waitcnt lgkmcnt(2)
	v_mfma_f32_16x16x32_bf16 v[34:37], v[6:9], v[18:21], 0
	v_readlane_b32 s1, v255, 10
	s_waitcnt lgkmcnt(1)
	v_mfma_f32_16x16x32_bf16 v[38:41], v[6:9], v[22:25], 0
	s_waitcnt lgkmcnt(0)
	v_mfma_f32_16x16x32_bf16 v[6:9], v[6:9], v[26:29], 0
	v_mfma_f32_16x16x32_bf16 v[14:17], v[10:13], v[14:17], 0
	v_mfma_f32_16x16x32_bf16 v[42:45], v[10:13], v[18:21], 0
	v_mfma_f32_16x16x32_bf16 v[22:25], v[10:13], v[22:25], 0
	v_mfma_f32_16x16x32_bf16 v[26:29], v[10:13], v[26:29], 0
	ds_read_b128 v[10:13], v5 offset:64
	ds_read_b128 v[46:49], v5 offset:2368
	ds_read_b128 v[18:21], v54 offset:41024
	ds_read_b128 v[50:53], v54 offset:49472
	ds_read_b128 v[54:57], v54 offset:57920
	ds_read_b128 v[58:61], v58 offset:41024
	v_or_b32_e32 v5, s13, v3
	s_waitcnt lgkmcnt(3)
	v_mfma_f32_16x16x32_bf16 v[30:33], v[10:13], v[18:21], v[30:33]
	s_waitcnt lgkmcnt(2)
	v_mfma_f32_16x16x32_bf16 v[34:37], v[10:13], v[50:53], v[34:37]
	s_waitcnt lgkmcnt(1)
	v_mfma_f32_16x16x32_bf16 v[38:41], v[10:13], v[54:57], v[38:41]
	s_waitcnt lgkmcnt(0)
	v_mfma_f32_16x16x32_bf16 v[62:65], v[10:13], v[58:61], v[6:9]
	v_mfma_f32_16x16x32_bf16 v[10:13], v[46:49], v[54:57], v[22:25]
	s_nop 2
	v_or_b32_e32 v24, s3, v2
	v_ashrrev_i32_e32 v25, 31, v24
	v_lshl_add_u64 v[22:23], v[24:25], 2, s[0:1]
	v_mfma_f32_16x16x32_bf16 v[18:21], v[46:49], v[18:21], v[14:17]
	v_readlane_b32 s0, v254, 26
	v_readlane_b32 s1, v254, 27
	v_mfma_f32_16x16x32_bf16 v[14:17], v[46:49], v[50:53], v[42:45]
	s_nop 2
	global_load_dwordx4 v[42:45], v[22:23], off
	v_mfma_f32_16x16x32_bf16 v[6:9], v[46:49], v[58:61], v[26:29]
	s_waitcnt vmcnt(0)
	v_mul_f32_e32 v2, v32, v44
	v_mul_f32_e32 v3, v33, v45
	s_nop 0
	v_mul_f32_e32 v26, v30, v42
	v_mul_f32_e32 v27, v31, v43
	v_lshlrev_b64 v[32:33], 1, v[24:25]
	v_cvt_pk_bf16_f32 v26, v26, v27
	v_cvt_pk_bf16_f32 v27, v2, v3
	v_lshlrev_b32_e32 v2, 11, v5
	v_mov_b32_e32 v3, v4
	v_lshl_add_u64 v[30:31], s[0:1], 0, v[2:3]
	v_lshl_add_u64 v[28:29], v[30:31], 0, v[32:33]
	global_store_dwordx2 v[28:29], v[26:27], off
	v_mul_f32_e32 v2, v36, v44
	v_mul_f32_e32 v3, v37, v45
	v_mul_f32_e32 v26, v34, v42
	v_mul_f32_e32 v27, v35, v43
	s_mov_b64 s[0:1], 0x8000
	v_cvt_pk_bf16_f32 v26, v26, v27
	v_cvt_pk_bf16_f32 v27, v2, v3
	v_lshl_add_u64 v[2:3], v[30:31], 0, s[0:1]
	v_lshl_add_u64 v[34:35], v[2:3], 0, v[32:33]
	global_store_dwordx2 v[34:35], v[26:27], off
	v_mul_f32_e32 v26, v40, v44
	v_mul_f32_e32 v27, v41, v45
	v_mul_f32_e32 v34, v38, v42
	v_mul_f32_e32 v35, v39, v43
	s_mov_b64 s[0:1], 0x10000
	v_cvt_pk_bf16_f32 v34, v34, v35
	v_cvt_pk_bf16_f32 v35, v26, v27
	v_lshl_add_u64 v[26:27], v[30:31], 0, s[0:1]
	v_lshl_add_u64 v[36:37], v[26:27], 0, v[32:33]
	s_mov_b64 s[0:1], 0x18000
	global_store_dwordx2 v[36:37], v[34:35], off
	v_mul_f32_e32 v34, v64, v44
	v_mul_f32_e32 v35, v65, v45
	v_mul_f32_e32 v36, v62, v42
	v_mul_f32_e32 v37, v63, v43
	v_lshl_add_u64 v[30:31], v[30:31], 0, s[0:1]
	v_cvt_pk_bf16_f32 v36, v36, v37
	v_cvt_pk_bf16_f32 v37, v34, v35
	v_lshl_add_u64 v[32:33], v[30:31], 0, v[32:33]
	global_store_dwordx2 v[32:33], v[36:37], off
	v_or_b32_e32 v32, 16, v24
	global_load_dwordx4 v[22:25], v[22:23], off offset:64
	v_ashrrev_i32_e32 v33, 31, v32
	s_mov_b64 s[0:1], 0
	s_waitcnt vmcnt(0)
	v_mul_f32_e32 v16, v16, v24
	v_mul_f32_e32 v17, v17, v25
	v_mul_f32_e32 v14, v14, v22
	v_mul_f32_e32 v15, v15, v23
	v_mul_f32_e32 v10, v10, v22
	v_mul_f32_e32 v11, v11, v23
	v_cvt_pk_bf16_f32 v14, v14, v15
	v_cvt_pk_bf16_f32 v15, v16, v17
	v_lshlrev_b64 v[16:17], 1, v[32:33]
	v_lshl_add_u64 v[2:3], v[2:3], 0, v[16:17]
	global_store_dwordx2 v[2:3], v[14:15], off
	v_mul_f32_e32 v2, v12, v24
	v_mul_f32_e32 v3, v13, v25
	v_cvt_pk_bf16_f32 v10, v10, v11
	v_cvt_pk_bf16_f32 v11, v2, v3
	v_lshl_add_u64 v[2:3], v[26:27], 0, v[16:17]
	v_mul_f32_e32 v20, v20, v24
	v_mul_f32_e32 v21, v21, v25
	v_mul_f32_e32 v18, v18, v22
	v_mul_f32_e32 v19, v19, v23
	global_store_dwordx2 v[2:3], v[10:11], off
	v_mul_f32_e32 v2, v8, v24
	v_mul_f32_e32 v3, v9, v25
	v_mul_f32_e32 v6, v6, v22
	v_mul_f32_e32 v7, v7, v23
	v_cvt_pk_bf16_f32 v18, v18, v19
	v_cvt_pk_bf16_f32 v19, v20, v21
	v_cvt_pk_bf16_f32 v6, v6, v7
	v_cvt_pk_bf16_f32 v7, v2, v3
	v_lshl_add_u64 v[2:3], v[30:31], 0, v[16:17]
	global_store_dwordx2 v[28:29], v[18:19], off offset:32
	global_store_dwordx2 v[2:3], v[6:7], off
	s_waitcnt lgkmcnt(0)
	s_barrier

; #define LAS __attribute__((address_space(3)))
; __device__ __forceinline__ void s2_ssd_unit(LAS unsigned char* U, f32x4 (&S)[8], const int hh, const int ps, const int lane, const float Dh) {
;     ...
;     const float ci0 = tab[r16], ci1 = tab[16 + r16];
;     const f32x4 cj0 = *(const LAS f32x4*)(tab + 4 * q), cj1 = *(const LAS f32x4*)(tab + 16 + 4 * q);
; #pragma unroll
;     for (int r = 0; r < 4; ++r) {
;         X00[r] = (4 * q + r > r16) ? 0.f : X00[r] * __expf(fminf(ci0 - cj0[r], 0.f));
;         X01[r] = X01[r] * __expf(fminf(ci1 - cj0[r], 0.f));
;         X11[r] = (4 * q + r > r16) ? 0.f : X11[r] * __expf(fminf(ci1 - cj1[r], 0.f));
;     }
;     const bf16x8 a0 = pack_frag(X00, z4), a1 = pack_frag(X01, X11);
;     bf16x8 xb; f32x4 ux0, ux1;
;     { const v2u xl = *(const LAS v2u*)(xrow + (4 * q) * 2), xh_ = *(const LAS v2u*)(xrow + (16 + 4 * q) * 2);
;       const f32x4 d0 = *(const LAS f32x4*)(tab + 64 + 4 * q), d1 = *(const LAS f32x4*)(tab + 64 + 16 + 4 * q);
;       const f32x4 fa = {__builtin_bit_cast(float, xl.x << 16) * d0[0], __builtin_bit_cast(float, xl.x & 0xffff0000u) * d0[1], __builtin_bit_cast(float, xl.y << 16) * d0[2], __builtin_bit_cast(float, xl.y & 0xffff0000u) * d0[3]};
;       const f32x4 fb = {__builtin_bit_cast(float, xh_.x << 16) * d1[0], __builtin_bit_cast(float, xh_.x & 0xffff0000u) * d1[1], __builtin_bit_cast(float, xh_.y << 16) * d1[2], __builtin_bit_cast(float, xh_.y & 0xffff0000u) * d1[3]};
;       xb = pack_frag(fa, fb);
;       ux0 = (f32x4){__builtin_bit_cast(float, xl.x << 16), __builtin_bit_cast(float, xl.x & 0xffff0000u), __builtin_bit_cast(float, xl.y << 16), __builtin_bit_cast(float, xl.y & 0xffff0000u)} * Dh;
;       ux1 = (f32x4){__builtin_bit_cast(float, xh_.x << 16), __builtin_bit_cast(float, xh_.x & 0xffff0000u), __builtin_bit_cast(float, xh_.y << 16), __builtin_bit_cast(float, xh_.y & 0xffff0000u)} * Dh; }
;     const f32x4 y10 = MFMA16(a0, xb, z4), y11 = MFMA16(a1, xb, z4);
;     const f32x4 e0 = *(const LAS f32x4*)(tab + 32 + 4 * q), e1 = *(const LAS f32x4*)(tab + 32 + 16 + 4 * q);
;     LAS float* yb = (LAS float*)(U + SL::OFF_Y);
; #pragma unroll
;     for (int r = 0; r < 4; ++r) { yb[(4 * q + r) * 132 + hh * 64 + p] = y10[r] + e0[r] * y20[r] + ux0[r]; yb[(16 + 4 * q + r) * 132 + hh * 64 + p] = y11[r] + e1[r] * y21[r] + ux1[r]; }
.LBB0_415:
	s_or_b64 exec, exec, s[12:13]
	s_waitcnt lgkmcnt(0)
	v_sub_f32_e32 v2, v3, v124
	v_min_f32_e32 v2, 0, v2
	v_sub_f32_e32 v123, v3, v123
	v_mul_f32_e32 v2, 0x3fb8aa3b, v2
	v_min_f32_e32 v123, 0, v123
	v_exp_f32_e32 v2, v2
	v_mul_f32_e32 v123, 0x3fb8aa3b, v123
	v_exp_f32_e32 v123, v123
	v_cvt_pk_bf16_f32 v38, v38, v39
	v_mul_f32_e32 v2, v120, v2
	v_cndmask_b32_e64 v120, v2, 0, s[48:49]
	v_mul_f32_e32 v2, v119, v123
	v_sub_f32_e32 v119, v3, v122
	v_min_f32_e32 v119, 0, v119
	v_mul_f32_e32 v119, 0x3fb8aa3b, v119
	v_exp_f32_e32 v119, v119
	v_cndmask_b32_e64 v123, 0, v2, s[44:45]
	v_cvt_pk_bf16_f32 v39, v40, v41
	v_cvt_pk_bf16_f32 v40, v42, v43
	v_mul_f32_e32 v2, v118, v119
	v_cndmask_b32_e64 v118, v2, 0, s[0:1]
	v_sub_f32_e32 v2, v3, v114
	v_cvt_pk_bf16_f32 v41, v44, v45
	v_min_f32_e32 v2, 0, v2
	v_mul_f32_e32 v2, 0x3fb8aa3b, v2
	v_mfma_f32_16x16x32_bf16 v[42:45], v[106:109], v[38:41], 0
	v_exp_f32_e32 v114, v2
	v_sub_f32_e32 v2, v3, v115
	v_min_f32_e32 v2, 0, v2
	v_mfma_f32_16x16x32_bf16 v[38:41], v[110:113], v[38:41], 0
	v_cvt_pk_bf16_f32 v18, v18, v19
	v_cvt_pk_bf16_f32 v19, v20, v21
	v_cvt_pk_bf16_f32 v20, v26, v27
	v_cvt_pk_bf16_f32 v21, v28, v29
	v_sub_f32_e32 v122, v3, v125
	v_mul_f32_e32 v2, 0x3fb8aa3b, v2
	v_mfma_f32_16x16x32_bf16 v[26:29], v[102:105], v[18:21], v[42:45]
	v_min_f32_e32 v122, 0, v122
	v_exp_f32_e32 v115, v2
	v_sub_f32_e32 v2, v3, v116
	v_sub_f32_e32 v3, v3, v117
	v_mul_f32_e32 v122, 0x3fb8aa3b, v122
	v_min_f32_e32 v2, 0, v2
	v_min_f32_e32 v3, 0, v3
	v_mfma_f32_16x16x32_bf16 v[18:21], v[98:101], v[18:21], v[38:41]
	v_exp_f32_e32 v122, v122
	v_mul_f32_e32 v2, 0x3fb8aa3b, v2
	v_cvt_pk_bf16_f32 v22, v22, v23
	v_cvt_pk_bf16_f32 v23, v24, v25
	v_cvt_pk_bf16_f32 v24, v34, v35
	v_cvt_pk_bf16_f32 v25, v36, v37
	v_mul_f32_e32 v3, 0x3fb8aa3b, v3
	v_exp_f32_e32 v2, v2
	v_mfma_f32_16x16x32_bf16 v[26:29], v[94:97], v[22:25], v[26:29]
	v_exp_f32_e32 v3, v3
	v_mul_f32_e32 v119, v121, v122
	v_cvt_pk_bf16_f32 v30, v30, v31
	v_mfma_f32_16x16x32_bf16 v[18:21], v[90:93], v[22:25], v[18:21]
	v_cvt_pk_bf16_f32 v31, v32, v33
	v_cvt_pk_bf16_f32 v32, v14, v15
	v_cvt_pk_bf16_f32 v33, v16, v17
	v_mul_f32_e32 v22, v78, v114
	v_mul_f32_e32 v23, v79, v115
	v_mul_f32_e32 v24, v80, v2
	v_mul_f32_e32 v25, v81, v3
	v_mfma_f32_16x16x32_bf16 v[14:17], v[86:89], v[30:33], v[26:29]
	v_cvt_pk_bf16_f32 v22, v22, v23
	v_cvt_pk_bf16_f32 v23, v24, v25
	v_cvt_pk_bf16_f32 v2, v5, v126
	v_cndmask_b32_e64 v26, v119, 0, s[52:53]
	v_cvt_pk_bf16_f32 v25, v120, v26
	v_add_u32_e32 v26, v151, v165
	v_mfma_f32_16x16x32_bf16 v[18:21], v[82:85], v[30:33], v[18:21]
	ds_read_b64 v[34:35], v26 offset:27648
	v_add_u32_e32 v30, v151, v166
	ds_read_b128 v[26:29], v169 offset:38144
	ds_read_b64 v[36:37], v30 offset:27648
	ds_read_b128 v[30:33], v169 offset:38208
	v_cvt_pk_bf16_f32 v3, v127, v128
	v_mov_b32_e32 v5, v4
	v_cvt_pk_bf16_f32 v24, v118, v123
	s_waitcnt lgkmcnt(3)
	v_lshlrev_b32_e32 v38, 16, v34
	v_and_b32_e32 v39, 0xffff0000, v34
	v_lshlrev_b32_e32 v34, 16, v35
	v_and_b32_e32 v35, 0xffff0000, v35
	s_waitcnt lgkmcnt(1)
	v_lshlrev_b32_e32 v40, 16, v36
	v_and_b32_e32 v41, 0xffff0000, v36
	v_lshlrev_b32_e32 v36, 16, v37
	v_and_b32_e32 v37, 0xffff0000, v37
	v_mul_f32_e32 v26, v26, v38
	v_mul_f32_e32 v27, v27, v39
	v_mul_f32_e32 v28, v28, v34
	v_mul_f32_e32 v29, v29, v35
	s_waitcnt lgkmcnt(0)
	v_mul_f32_e32 v30, v30, v40
	v_mul_f32_e32 v31, v31, v41
	v_mul_f32_e32 v32, v32, v36
	v_mul_f32_e32 v33, v33, v37
	v_cvt_pk_bf16_f32 v26, v26, v27
	v_cvt_pk_bf16_f32 v27, v28, v29
	v_cvt_pk_bf16_f32 v28, v30, v31
	v_cvt_pk_bf16_f32 v29, v32, v33
	v_mov_b32_e32 v151, v150
	v_mul_f32_e32 v42, v150, v34
	v_mul_f32_e32 v43, v151, v35
	v_mfma_f32_16x16x32_bf16 v[30:33], v[2:5], v[26:29], 0
	v_mul_f32_e64 v2, v150, v36
	v_mul_f32_e64 v3, v151, v37
	ds_read_b128 v[34:37], v169 offset:38016
	s_add_i32 s23, s23, s22
	v_mfma_f32_16x16x32_bf16 v[22:25], v[22:25], v[26:29], 0
	ds_read_b128 v[26:29], v169 offset:38080
	v_mul_f32_e32 v38, v152, v38
	v_mul_f32_e32 v39, v153, v39
	v_lshl_add_u32 v5, v161, 2, s23
	s_waitcnt lgkmcnt(1)
	v_fma_f32 v14, v14, v34, v30
	v_add_f32_e32 v14, v38, v14
	v_add_u32_e32 v30, v5, v167
	v_mul_f32_e32 v40, v152, v40
	v_mul_f32_e32 v41, v153, v41
	ds_write_b32 v30, v14 offset:39168
	s_waitcnt lgkmcnt(1)
	v_fma_f32 v14, v18, v26, v22
	v_add_f32_e32 v14, v40, v14
	v_add_u32_e32 v5, v5, v168
	ds_write_b32 v5, v14 offset:39168
	v_fma_f32 v5, v15, v35, v31
	v_fma_f32 v15, v16, v36, v32
	v_add_f32_e32 v5, v39, v5
	v_add_f32_e32 v15, v42, v15
	v_add_u32_e32 v16, 0x9a00, v30
	v_fma_f32 v14, v19, v27, v23
	ds_write2_b32 v16, v5, v15 offset0:68 offset1:200
	v_fma_f32 v5, v20, v28, v24
	v_add_f32_e32 v14, v41, v14
	v_add_f32_e32 v2, v2, v5
	v_add_u32_e32 v5, 0xbc00, v30
	v_fmac_f32_e32 v33, v17, v37
	ds_write2_b32 v5, v14, v2 offset0:4 offset1:136
	v_add_f32_e32 v2, v43, v33
	v_fmac_f32_e32 v25, v21, v29
	s_xor_b64 s[12:13], s[2:3], -1
	ds_write_b32 v30, v2 offset:40752
	v_add_f32_e32 v2, v3, v25
	v_mov_b64_e32 v[14:15], v[74:75]
	ds_write_b32 v30, v2 offset:49200
	s_mov_b32 s23, 0xdb00
	s_mov_b64 s[2:3], 0
	s_and_b64 vcc, exec, s[12:13]
	v_mov_b64_e32 v[16:17], v[76:77]
	v_mov_b32_e32 v38, v46
	v_mov_b32_e32 v39, v47
	v_mov_b32_e32 v40, v48
	v_mov_b32_e32 v41, v49
	v_mov_b32_e32 v42, v50
	v_mov_b32_e32 v43, v51
	v_mov_b32_e32 v44, v52
	v_mov_b32_e32 v45, v53
	v_mov_b32_e32 v18, v54
	v_mov_b32_e32 v19, v55
	v_mov_b32_e32 v20, v56
	v_mov_b32_e32 v21, v57
	v_mov_b32_e32 v26, v58
	v_mov_b32_e32 v27, v59
	v_mov_b32_e32 v28, v60
	v_mov_b32_e32 v29, v61
	v_mov_b32_e32 v22, v62
	v_mov_b32_e32 v23, v63
	v_mov_b32_e32 v24, v64
	v_mov_b32_e32 v25, v65
	v_mov_b32_e32 v34, v66
	v_mov_b32_e32 v35, v67
	v_mov_b32_e32 v36, v68
	v_mov_b32_e32 v37, v69
	v_mov_b32_e32 v30, v70
	v_mov_b32_e32 v31, v71
	v_mov_b32_e32 v32, v72
	v_mov_b32_e32 v33, v73
	s_cbranch_vccnz .LBB0_432
; #define LAS __attribute__((address_space(3)))
; #define MFMA16(a, b, c) __builtin_amdgcn_mfma_f32_16x16x32_bf16((a), (b), (c), 0, 0, 0)
; __device__ __forceinline__ void s2_ssd_unit(LAS unsigned char* U, f32x4 (&S)[8], const int hh, const int ps, const int lane, const float Dh) {
;     const int q = lane >> 4, r16 = lane & 15, p = 16 * ps + r16;
;     const f32x4 z4 = {0.f, 0.f, 0.f, 0.f};
;     const LAS float* tab = (const LAS float*)(U + SL::OFF_TAB) + hh * 160;
;     const LAS unsigned char* xrow = U + SL::OFF_XT + hh * 5120 + p * 80;
;     bf16x8 btf[8];
; #pragma unroll
;     for (int nt = 0; nt < 8; ++nt) btf[nt] = frag16(U + SL::OFF_BT + (16 * nt + r16) * 80 + (8 * q) * 2);
;     const v4u xn = *(const LAS v4u*)(xrow + (8 * q) * 2);
;     const f32x4 w0 = *(const LAS f32x4*)(tab + 96 + 8 * q), w1 = *(const LAS f32x4*)(tab + 96 + 8 * q + 4);
;     const float eL = tab[128];
;     bf16x8 cp0[4], cp1[4];
; #pragma unroll
;     for (int s = 0; s < 4; ++s) { const LAS unsigned char* cr0 = U + SL::OFF_C + r16 * 272 + (32 * s + 4 * q) * 2; const LAS unsigned char* cr1 = cr0 + 16 * 272; cp0[s] = frag8x2(cr0, cr0 + 32); cp1[s] = frag8x2(cr1, cr1 + 32); }
;     bf16x8 sb[4];
; #pragma unroll
;     for (int s = 0; s < 4; ++s) sb[s] = pack_frag(S[2 * s], S[2 * s + 1]);
;     const f32x4 xa = {bfe(xn, 0) * w0[0], bfe(xn, 1) * w0[1], bfe(xn, 2) * w0[2], bfe(xn, 3) * w0[3]}, xc = {bfe(xn, 4) * w1[0], bfe(xn, 5) * w1[1], bfe(xn, 6) * w1[2], bfe(xn, 7) * w1[3]};
;     const bf16x8 xh = pack_frag(xa, xc);
; #pragma unroll
;     for (int nt = 0; nt < 8; ++nt) S[nt] = MFMA16(btf[nt], xh, S[nt] * eL);
;     f32x4 X00 = z4, X01 = z4, X11 = z4;
; #pragma unroll
;     for (int s = 0; s < 4; ++s) {
;         const int nb = (32 * s + 8 * q) * 2;
;         const bf16x8 b0 = frag16(U + SL::OFF_B + r16 * 272 + nb), b1 = frag16(U + SL::OFF_B + (16 + r16) * 272 + nb);
;         const bf16x8 c0 = frag16(U + SL::OFF_C + r16 * 272 + nb), c1 = frag16(U + SL::OFF_C + (16 + r16) * 272 + nb);
;         X00 = MFMA16(b0, c0, X00); X01 = MFMA16(b0, c1, X01); X11 = MFMA16(b1, c1, X11);
;     }
;     f32x4 y20 = z4, y21 = z4;
; #pragma unroll
;     for (int s = 0; s < 4; ++s) { y20 = MFMA16(cp0[s], sb[s], y20); y21 = MFMA16(cp1[s], sb[s], y21); }
.LBB0_416:
	s_add_i32 s23, s23, 0
	v_add_u32_e32 v3, s23, v149
	s_add_i32 s13, s23, s19
	v_add_u32_e32 v5, v3, v157
	v_add_u32_e32 v2, v3, v158
	v_add_u32_e32 v151, s13, v156
	s_add_i32 s12, s23, s18
	ds_read_b128 v[46:49], v5 offset:17408
	ds_read_b128 v[50:53], v5 offset:18688
	ds_read_b128 v[54:57], v5 offset:19968
	ds_read_b128 v[58:61], v2 offset:17408
	v_add_u32_e32 v2, v151, v149
	v_add_u32_e32 v70, s12, v163
	ds_read_b128 v[62:65], v2 offset:27648
	ds_read_b128 v[66:69], v70 offset:38272
	v_mov_b32_e32 v2, s12
	ds_read_b128 v[70:73], v70 offset:38288
	ds_read_b32 v2, v2 offset:38400
	v_lshl_add_u32 v169, v145, 2, s12
	s_waitcnt lgkmcnt(3)
	v_lshlrev_b32_e32 v74, 16, v62
	v_and_b32_e32 v75, 0xffff0000, v62
	v_lshlrev_b32_e32 v62, 16, v63
	v_and_b32_e32 v63, 0xffff0000, v63
	s_waitcnt lgkmcnt(2)
	v_mul_f32_e32 v62, v68, v62
	v_mul_f32_e32 v63, v69, v63
	v_lshlrev_b32_e32 v68, 16, v64
	v_and_b32_e32 v69, 0xffff0000, v64
	v_lshlrev_b32_e32 v64, 16, v65
	v_and_b32_e32 v65, 0xffff0000, v65
	v_mul_f32_e32 v66, v66, v74
	v_mul_f32_e32 v67, v67, v75
	s_waitcnt lgkmcnt(1)
	v_mul_f32_e32 v68, v70, v68
	v_mul_f32_e32 v69, v71, v69
	v_mul_f32_e32 v64, v72, v64
	v_mul_f32_e32 v65, v73, v65
	v_cvt_pk_bf16_f32 v74, v66, v67
	v_cvt_pk_bf16_f32 v75, v62, v63
	v_cvt_pk_bf16_f32 v76, v68, v69
	v_cvt_pk_bf16_f32 v77, v64, v65
	s_waitcnt vmcnt(7) lgkmcnt(0)
	v_mul_f32_e32 v64, v40, v2
	v_mul_f32_e32 v65, v41, v2
	v_mul_f32_e32 v62, v38, v2
	v_mul_f32_e32 v63, v39, v2
	s_waitcnt vmcnt(6)
	v_mul_f32_e32 v68, v44, v2
	v_mul_f32_e32 v69, v45, v2
	v_mul_f32_e32 v66, v42, v2
	v_mul_f32_e32 v67, v43, v2
	v_mfma_f32_16x16x32_bf16 v[46:49], v[46:49], v[74:77], v[62:65]
	v_add_u32_e32 v3, v3, v159
	s_waitcnt vmcnt(3)
	v_mul_f32_e32 v72, v24, v2
	v_mul_f32_e32 v73, v25, v2
	v_mul_f32_e32 v70, v22, v2
	v_mul_f32_e32 v71, v23, v2
	ds_read_b128 v[62:65], v5 offset:22528
	ds_read_b128 v[78:81], v3 offset:17408
	v_mfma_f32_16x16x32_bf16 v[50:53], v[50:53], v[74:77], v[66:69]
	s_waitcnt vmcnt(2)
	v_mul_f32_e32 v84, v36, v2
	v_mul_f32_e32 v85, v37, v2
	v_mul_f32_e32 v82, v34, v2
	v_mul_f32_e32 v83, v35, v2
	v_mul_f32_e32 v68, v20, v2
	v_mul_f32_e32 v69, v21, v2
	v_mul_f32_e32 v66, v18, v2
	v_mul_f32_e32 v67, v19, v2
	s_waitcnt lgkmcnt(1)
	v_mfma_f32_16x16x32_bf16 v[62:65], v[62:65], v[74:77], v[70:73]
	s_nop 2
	ds_read_b128 v[70:73], v5 offset:25088
	v_mfma_f32_16x16x32_bf16 v[54:57], v[54:57], v[74:77], v[66:69]
	s_nop 2
	v_mul_f32_e64 v68, v28, v2
	v_mul_f32_e64 v69, v29, v2
	v_mul_f32_e32 v66, v26, v2
	v_mul_f32_e32 v67, v27, v2
	v_add_u32_e32 v3, s23, v164
	s_nop 0
	v_mfma_f32_16x16x32_bf16 v[58:61], v[58:61], v[74:77], v[66:69]
	s_nop 2
	ds_read_b128 v[66:69], v5 offset:23808
	v_add_u32_e32 v5, v3, v149
	ds_read_b128 v[86:89], v5 offset:8704
	s_waitcnt lgkmcnt(1)
	v_mfma_f32_16x16x32_bf16 v[66:69], v[66:69], v[74:77], v[82:85]
	s_waitcnt vmcnt(1)
	s_nop 1
	v_mul_f32_e32 v84, v32, v2
	v_mul_f32_e32 v85, v33, v2
	v_mul_f32_e32 v82, v30, v2
	v_mul_f32_e32 v83, v31, v2
	s_nop 1
	v_mfma_f32_16x16x32_bf16 v[70:73], v[70:73], v[74:77], v[82:85]
	s_waitcnt vmcnt(0)
	s_nop 1
	v_mul_f32_e32 v84, v16, v2
	v_mul_f32_e32 v85, v17, v2
	v_mul_f32_e32 v82, v14, v2
	v_mul_f32_e32 v83, v15, v2
	v_add_u32_e32 v2, v3, v165
	v_add_u32_e32 v3, 0x1000, v2
	v_mfma_f32_16x16x32_bf16 v[74:77], v[78:81], v[74:77], v[82:85]
	s_nop 2
	ds_read_b128 v[82:85], v5 offset:8768
	ds_read_b128 v[90:93], v5 offset:4352
	ds_read_b128 v[94:97], v5 offset:4416
	ds_read_b128 v[98:101], v5 offset:8832
	ds_read_b128 v[114:117], v5 offset:8896
	ds_read_b128 v[118:121], v5 offset:4480
	ds_read_b128 v[170:173], v5 offset:4544
	ds_read_b128 v[102:105], v5
	ds_read_b128 v[110:113], v5 offset:64
	s_waitcnt lgkmcnt(7)
	v_mfma_f32_16x16x32_bf16 v[78:81], v[86:89], v[90:93], 0
	s_waitcnt lgkmcnt(1)
	v_mfma_f32_16x16x32_bf16 v[86:89], v[86:89], v[102:105], 0
	ds_read_b128 v[102:105], v5 offset:13056
	ds_read_b128 v[122:125], v5 offset:13120
	ds_read2_b64 v[106:109], v2 offset1:4
	s_waitcnt lgkmcnt(2)
	v_mfma_f32_16x16x32_bf16 v[90:93], v[102:105], v[90:93], 0
	v_mfma_f32_16x16x32_bf16 v[78:81], v[82:85], v[94:97], v[78:81]
	v_mfma_f32_16x16x32_bf16 v[82:85], v[82:85], v[110:113], v[86:89]
	s_nop 2
	ds_read_b128 v[86:89], v5 offset:13184
	ds_read_b128 v[126:129], v5 offset:128
	s_waitcnt lgkmcnt(3)
	v_mfma_f32_16x16x32_bf16 v[90:93], v[122:125], v[94:97], v[90:93]
	ds_read2_b64 v[110:113], v3 offset0:32 offset1:36
	ds_read2_b64 v[102:105], v2 offset0:8 offset1:12
	ds_read_b128 v[122:125], v5 offset:192
	v_mfma_f32_16x16x32_bf16 v[78:81], v[98:101], v[118:121], v[78:81]
	s_waitcnt lgkmcnt(3)
	v_mfma_f32_16x16x32_bf16 v[126:129], v[98:101], v[126:129], v[82:85]
	ds_read2_b64 v[98:101], v3 offset0:40 offset1:44
	ds_read2_b64 v[94:97], v2 offset0:16 offset1:20
	ds_read_b128 v[174:177], v5 offset:13248
	v_mfma_f32_16x16x32_bf16 v[118:121], v[86:89], v[118:121], v[90:93]
	s_nop 2
	ds_read2_b64 v[90:93], v3 offset0:48 offset1:52
	ds_read2_b64 v[86:89], v2 offset0:24 offset1:28
	ds_read2_b64 v[82:85], v3 offset0:56 offset1:60
	v_lshl_add_u32 v2, v160, 2, s12
	v_add_u32_e32 v2, 0x9400, v2
	v_mfma_f32_16x16x32_bf16 v[78:81], v[114:117], v[170:173], v[78:81]
	ds_read2_b32 v[2:3], v2 offset1:16
	s_waitcnt lgkmcnt(7)
	v_mfma_f32_16x16x32_bf16 v[126:129], v[114:117], v[122:125], v[126:129]
	ds_read_b128 v[114:117], v169 offset:37888
	ds_read_b128 v[122:125], v169 offset:37952
	s_waitcnt lgkmcnt(6)
	v_mfma_f32_16x16x32_bf16 v[118:121], v[174:177], v[170:173], v[118:121]
	s_and_saveexec_b64 s[12:13], s[42:43]
	s_xor_b64 s[12:13], exec, s[12:13]
	s_cbranch_execz .LBB0_418
	s_waitcnt lgkmcnt(1)
	v_sub_f32_e32 v5, v2, v114
	v_min_f32_e32 v5, 0, v5
	v_mul_f32_e32 v5, 0x3fb8aa3b, v5
	v_exp_f32_e32 v5, v5
	s_nop 0
	v_mul_f32_e32 v5, v126, v5

; #define LAS __attribute__((address_space(3)))
; __device__ __forceinline__ void s2_ssd_unit(LAS unsigned char* U, f32x4 (&S)[8], const int hh, const int ps, const int lane, const float Dh) {
;     ...
;     const float ci0 = tab[r16], ci1 = tab[16 + r16];
;     const f32x4 cj0 = *(const LAS f32x4*)(tab + 4 * q), cj1 = *(const LAS f32x4*)(tab + 16 + 4 * q);
; #pragma unroll
;     for (int r = 0; r < 4; ++r) {
;         X00[r] = (4 * q + r > r16) ? 0.f : X00[r] * __expf(fminf(ci0 - cj0[r], 0.f));
;         X01[r] = X01[r] * __expf(fminf(ci1 - cj0[r], 0.f));
;         X11[r] = (4 * q + r > r16) ? 0.f : X11[r] * __expf(fminf(ci1 - cj1[r], 0.f));
;     }
;     const bf16x8 a0 = pack_frag(X00, z4), a1 = pack_frag(X01, X11);
;     bf16x8 xb; f32x4 ux0, ux1;
;     { const v2u xl = *(const LAS v2u*)(xrow + (4 * q) * 2), xh_ = *(const LAS v2u*)(xrow + (16 + 4 * q) * 2);
;       const f32x4 d0 = *(const LAS f32x4*)(tab + 64 + 4 * q), d1 = *(const LAS f32x4*)(tab + 64 + 16 + 4 * q);
;       const f32x4 fa = {__builtin_bit_cast(float, xl.x << 16) * d0[0], __builtin_bit_cast(float, xl.x & 0xffff0000u) * d0[1], __builtin_bit_cast(float, xl.y << 16) * d0[2], __builtin_bit_cast(float, xl.y & 0xffff0000u) * d0[3]};
;       const f32x4 fb = {__builtin_bit_cast(float, xh_.x << 16) * d1[0], __builtin_bit_cast(float, xh_.x & 0xffff0000u) * d1[1], __builtin_bit_cast(float, xh_.y << 16) * d1[2], __builtin_bit_cast(float, xh_.y & 0xffff0000u) * d1[3]};
;       xb = pack_frag(fa, fb);
;       ux0 = (f32x4){__builtin_bit_cast(float, xl.x << 16), __builtin_bit_cast(float, xl.x & 0xffff0000u), __builtin_bit_cast(float, xl.y << 16), __builtin_bit_cast(float, xl.y & 0xffff0000u)} * Dh;
;       ux1 = (f32x4){__builtin_bit_cast(float, xh_.x << 16), __builtin_bit_cast(float, xh_.x & 0xffff0000u), __builtin_bit_cast(float, xh_.y << 16), __builtin_bit_cast(float, xh_.y & 0xffff0000u)} * Dh; }
;     const f32x4 y10 = MFMA16(a0, xb, z4), y11 = MFMA16(a1, xb, z4);
;     const f32x4 e0 = *(const LAS f32x4*)(tab + 32 + 4 * q), e1 = *(const LAS f32x4*)(tab + 32 + 16 + 4 * q);
;     LAS float* yb = (LAS float*)(U + SL::OFF_Y);
; #pragma unroll
;     for (int r = 0; r < 4; ++r) { yb[(4 * q + r) * 132 + hh * 64 + p] = y10[r] + e0[r] * y20[r] + ux0[r]; yb[(16 + 4 * q + r) * 132 + hh * 64 + p] = y11[r] + e1[r] * y21[r] + ux1[r]; }
.LBB0_436:
	s_or_b64 exec, exec, s[2:3]
	s_waitcnt lgkmcnt(0)
	v_sub_f32_e32 v2, v3, v124
	v_min_f32_e32 v2, 0, v2
	v_sub_f32_e32 v123, v3, v123
	v_mul_f32_e32 v2, 0x3fb8aa3b, v2
	v_min_f32_e32 v123, 0, v123
	v_exp_f32_e32 v2, v2
	v_mul_f32_e32 v123, 0x3fb8aa3b, v123
	v_exp_f32_e32 v123, v123
	v_cvt_pk_bf16_f32 v50, v50, v51
	v_mul_f32_e32 v2, v120, v2
	v_cndmask_b32_e64 v120, v2, 0, s[50:51]
	v_mul_f32_e32 v2, v119, v123
	v_sub_f32_e32 v119, v3, v122
	v_min_f32_e32 v119, 0, v119
	v_mul_f32_e32 v119, 0x3fb8aa3b, v119
	v_exp_f32_e32 v119, v119
	v_cndmask_b32_e64 v123, 0, v2, s[46:47]
	v_cvt_pk_bf16_f32 v51, v52, v53
	v_cvt_pk_bf16_f32 v52, v46, v47
	v_mul_f32_e32 v2, v118, v119
	v_cvt_pk_bf16_f32 v53, v48, v49
	v_cndmask_b32_e64 v118, v2, 0, s[42:43]
	v_sub_f32_e32 v2, v3, v114
	v_mfma_f32_16x16x32_bf16 v[46:49], v[106:109], v[50:53], 0
	v_min_f32_e32 v2, 0, v2
	v_mul_f32_e32 v2, 0x3fb8aa3b, v2
	v_exp_f32_e32 v114, v2
	v_mfma_f32_16x16x32_bf16 v[50:53], v[110:113], v[50:53], 0
	v_sub_f32_e32 v2, v3, v115
	v_cvt_pk_bf16_f32 v42, v42, v43
	v_cvt_pk_bf16_f32 v43, v44, v45
	v_cvt_pk_bf16_f32 v44, v38, v39
	v_cvt_pk_bf16_f32 v45, v40, v41
	v_sub_f32_e32 v122, v3, v125
	v_min_f32_e32 v2, 0, v2
	v_mfma_f32_16x16x32_bf16 v[38:41], v[102:105], v[42:45], v[46:49]
	v_min_f32_e32 v122, 0, v122
	v_mul_f32_e32 v2, 0x3fb8aa3b, v2
	v_mul_f32_e32 v122, 0x3fb8aa3b, v122
	v_mfma_f32_16x16x32_bf16 v[42:45], v[98:101], v[42:45], v[50:53]
	v_exp_f32_e32 v115, v2
	v_sub_f32_e32 v2, v3, v116
	v_sub_f32_e32 v3, v3, v117
	v_exp_f32_e32 v122, v122
	v_min_f32_e32 v2, 0, v2
	v_min_f32_e32 v3, 0, v3
	v_cvt_pk_bf16_f32 v34, v34, v35
	v_cvt_pk_bf16_f32 v35, v36, v37
	v_cvt_pk_bf16_f32 v36, v30, v31
	v_cvt_pk_bf16_f32 v37, v32, v33
	v_mul_f32_e32 v2, 0x3fb8aa3b, v2
	v_mul_f32_e32 v3, 0x3fb8aa3b, v3
	v_mfma_f32_16x16x32_bf16 v[30:33], v[90:93], v[34:37], v[38:41]
	v_exp_f32_e32 v2, v2
	v_exp_f32_e32 v3, v3
	v_mul_f32_e32 v119, v121, v122
	v_mfma_f32_16x16x32_bf16 v[34:37], v[86:89], v[34:37], v[42:45]
	v_cvt_pk_bf16_f32 v38, v70, v71
	v_cvt_pk_bf16_f32 v39, v72, v73
	v_cvt_pk_bf16_f32 v40, v74, v75
	v_cvt_pk_bf16_f32 v41, v76, v77
	v_mul_f32_e32 v42, v94, v114
	v_mul_f32_e32 v43, v95, v115
	v_cndmask_b32_e64 v46, v119, 0, s[54:55]
	v_mfma_f32_16x16x32_bf16 v[30:33], v[82:85], v[38:41], v[30:33]
	v_mul_f32_e64 v44, v96, v2
	v_mul_f32_e64 v45, v97, v3
	v_cvt_pk_bf16_f32 v2, v5, v126
	v_cvt_pk_bf16_f32 v3, v127, v128
	v_mfma_f32_16x16x32_bf16 v[34:37], v[78:81], v[38:41], v[34:37]
	v_cvt_pk_bf16_f32 v38, v42, v43
	v_add_u32_e32 v42, v145, v167
	v_cvt_pk_bf16_f32 v41, v120, v46
	ds_read_b64 v[50:51], v42 offset:27648
	v_add_u32_e32 v46, v145, v168
	v_cvt_pk_bf16_f32 v39, v44, v45
	ds_read_b128 v[42:45], v170 offset:38144
	ds_read_b64 v[52:53], v46 offset:27648
	ds_read_b128 v[46:49], v170 offset:38208
	v_mov_b32_e32 v5, v4
	v_cvt_pk_bf16_f32 v40, v118, v123
	s_waitcnt lgkmcnt(3)
	v_lshlrev_b32_e32 v70, 16, v50
	v_and_b32_e32 v71, 0xffff0000, v50
	v_lshlrev_b32_e32 v50, 16, v51
	v_and_b32_e32 v51, 0xffff0000, v51
	s_waitcnt lgkmcnt(1)
	v_lshlrev_b32_e32 v72, 16, v52
	v_and_b32_e32 v73, 0xffff0000, v52
	v_lshlrev_b32_e32 v52, 16, v53
	v_and_b32_e32 v53, 0xffff0000, v53
	v_mul_f32_e32 v42, v42, v70
	v_mul_f32_e32 v43, v43, v71
	v_mul_f32_e32 v44, v44, v50
	v_mul_f32_e32 v45, v45, v51
	s_waitcnt lgkmcnt(0)
	v_mul_f32_e32 v46, v46, v72
	v_mul_f32_e32 v47, v47, v73
	v_mul_f32_e32 v48, v48, v52
	v_mul_f32_e32 v49, v49, v53
	v_cvt_pk_bf16_f32 v42, v42, v43
	v_cvt_pk_bf16_f32 v43, v44, v45
	v_cvt_pk_bf16_f32 v44, v46, v47
	v_cvt_pk_bf16_f32 v45, v48, v49
	v_mov_b32_e32 v147, v146
	v_mul_f32_e32 v74, v146, v50
	v_mul_f32_e32 v75, v147, v51
	v_mfma_f32_16x16x32_bf16 v[46:49], v[2:5], v[42:45], 0
	v_mul_f32_e64 v2, v146, v52
	v_mul_f32_e64 v3, v147, v53
	ds_read_b128 v[50:53], v170 offset:38016
	s_add_i32 s21, s21, s12
	v_mfma_f32_16x16x32_bf16 v[38:41], v[38:41], v[42:45], 0
	ds_read_b128 v[42:45], v170 offset:38080
	v_mul_f32_e32 v70, v150, v70
	v_mul_f32_e32 v71, v151, v71
	v_lshl_add_u32 v5, v161, 2, s21
	s_waitcnt lgkmcnt(1)
	v_fma_f32 v30, v30, v50, v46
	v_add_f32_e32 v30, v70, v30
	v_add_u32_e32 v46, v5, v162
	v_mul_f32_e32 v72, v150, v72
	v_mul_f32_e32 v73, v151, v73
	ds_write_b32 v46, v30 offset:39168
	s_waitcnt lgkmcnt(1)
	v_fma_f32 v30, v34, v42, v38
	v_add_f32_e32 v30, v72, v30
	v_add_u32_e32 v5, v5, v169
	ds_write_b32 v5, v30 offset:39168
	v_fma_f32 v5, v31, v51, v47
	v_fma_f32 v31, v32, v52, v48
	v_add_f32_e32 v5, v71, v5
	v_add_f32_e32 v31, v74, v31
	v_add_u32_e32 v32, 0x9a00, v46
	s_xor_b64 s[2:3], s[0:1], -1
	v_fma_f32 v30, v35, v43, v39
	ds_write2_b32 v32, v5, v31 offset0:68 offset1:200
	v_fma_f32 v5, v36, v44, v40
	v_add_f32_e32 v30, v73, v30
	v_add_f32_e32 v2, v2, v5
	v_add_u32_e32 v5, 0xbc00, v46
	v_fmac_f32_e32 v49, v33, v53
	s_add_u32 s0, s20, s4
	ds_write2_b32 v5, v30, v2 offset0:4 offset1:136
	v_add_f32_e32 v2, v75, v49
	v_fmac_f32_e32 v41, v37, v45
	s_addc_u32 s1, 0, s13
	ds_write_b32 v46, v2 offset:40752
	v_add_f32_e32 v2, v3, v41
	s_lshl_b64 s[0:1], s[0:1], 17
	ds_write_b32 v46, v2 offset:49200
	v_lshl_add_u64 v[2:3], v[152:153], 0, s[0:1]
	s_mov_b32 s20, 1
	s_mov_b64 s[0:1], 0
	s_and_b64 vcc, exec, s[2:3]
	global_store_dwordx4 v[2:3], v[14:17], off
	global_store_dwordx4 v[2:3], v[18:21], off offset:64
	global_store_dwordx4 v[2:3], v[22:25], off offset:128
	global_store_dwordx4 v[2:3], v[26:29], off offset:192
	global_store_dwordx4 v[2:3], v[54:57], off offset:256
	global_store_dwordx4 v[2:3], v[58:61], off offset:320
	global_store_dwordx4 v[2:3], v[62:65], off offset:384
	global_store_dwordx4 v[2:3], v[66:69], off offset:448
	s_cbranch_vccnz .LBB0_451
; __device__ __forceinline__ void s2_ssd_unit(LAS unsigned char* U, f32x4 (&S)[8], const int hh, const int ps, const int lane, const float Dh) {
;     const int q = lane >> 4, r16 = lane & 15, p = 16 * ps + r16;
;     const f32x4 z4 = {0.f, 0.f, 0.f, 0.f};
;     const LAS float* tab = (const LAS float*)(U + SL::OFF_TAB) + hh * 160;
;     const LAS unsigned char* xrow = U + SL::OFF_XT + hh * 5120 + p * 80;
;     bf16x8 btf[8];
; #pragma unroll
;     for (int nt = 0; nt < 8; ++nt) btf[nt] = frag16(U + SL::OFF_BT + (16 * nt + r16) * 80 + (8 * q) * 2);
;     const v4u xn = *(const LAS v4u*)(xrow + (8 * q) * 2);
;     const f32x4 w0 = *(const LAS f32x4*)(tab + 96 + 8 * q), w1 = *(const LAS f32x4*)(tab + 96 + 8 * q + 4);
;     const float eL = tab[128];
;     bf16x8 cp0[4], cp1[4];
; #pragma unroll
;     for (int s = 0; s < 4; ++s) { const LAS unsigned char* cr0 = U + SL::OFF_C + r16 * 272 + (32 * s + 4 * q) * 2; const LAS unsigned char* cr1 = cr0 + 16 * 272; cp0[s] = frag8x2(cr0, cr0 + 32); cp1[s] = frag8x2(cr1, cr1 + 32); }
;     bf16x8 sb[4];
; #pragma unroll
;     for (int s = 0; s < 4; ++s) sb[s] = pack_frag(S[2 * s], S[2 * s + 1]);
;     const f32x4 xa = {bfe(xn, 0) * w0[0], bfe(xn, 1) * w0[1], bfe(xn, 2) * w0[2], bfe(xn, 3) * w0[3]}, xc = {bfe(xn, 4) * w1[0], bfe(xn, 5) * w1[1], bfe(xn, 6) * w1[2], bfe(xn, 7) * w1[3]};
;     const bf16x8 xh = pack_frag(xa, xc);
; #pragma unroll
;     for (int nt = 0; nt < 8; ++nt) S[nt] = MFMA16(btf[nt], xh, S[nt] * eL);
;     f32x4 X00 = z4, X01 = z4, X11 = z4;
; #pragma unroll
;     for (int s = 0; s < 4; ++s) {
;         const int nb = (32 * s + 8 * q) * 2;
;         const bf16x8 b0 = frag16(U + SL::OFF_B + r16 * 272 + nb), b1 = frag16(U + SL::OFF_B + (16 + r16) * 272 + nb);
;         const bf16x8 c0 = frag16(U + SL::OFF_C + r16 * 272 + nb), c1 = frag16(U + SL::OFF_C + (16 + r16) * 272 + nb);
;         X00 = MFMA16(b0, c0, X00); X01 = MFMA16(b0, c1, X01); X11 = MFMA16(b1, c1, X11);
; __device__ __forceinline__ void chain_ssd(LAS unsigned char* L, const MixP& C, const int g, const int b0, const int mode, const int sc0, const int tid) {
;     ...
;             const float* sp = C.s_ssm + (((size_t)(b0 + u) * 4 + h2) * 64 + p2) * 128;
; #pragma unroll
;             for (int nt = 0; nt < 8; ++nt) S[nt] = *(const f32x4*)(sp + 16 * nt + 4 * q2);
;             s2_ssd_unit(L + u * SL::UNIT, S, hh2, ps, lane, (hh2 == 0) ? D0 : D1);
.LBB0_437:
	s_add_i32 s2, s20, s4
	s_ashr_i32 s3, s2, 31
	s_lshl_b64 s[2:3], s[2:3], 17
	v_lshl_add_u64 v[62:63], v[148:149], 0, s[2:3]
	global_load_dwordx4 v[50:53], v[62:63], off
	global_load_dwordx4 v[46:49], v[62:63], off offset:64
	global_load_dwordx4 v[42:45], v[62:63], off offset:128
	global_load_dwordx4 v[38:41], v[62:63], off offset:192
	global_load_dwordx4 v[34:37], v[62:63], off offset:256
	global_load_dwordx4 v[30:33], v[62:63], off offset:320
	s_mul_i32 s2, s20, 0xdb00
	s_add_i32 s21, s2, 0
	s_add_i32 s3, s21, s19
	s_add_i32 s2, s21, s18
	v_add_u32_e32 v2, s21, v164
	v_add_u32_e32 v145, s3, v156
	v_add_u32_e32 v3, s21, v166
	v_add_u32_e32 v5, v2, v157
	v_add_u32_e32 v26, v2, v158
	v_add_u32_e32 v74, v2, v159
	v_add_u32_e32 v64, s2, v165
	v_mov_b32_e32 v2, s2
	v_add_u32_e32 v58, v145, v164
	v_add_u32_e32 v147, v3, v164
	ds_read_b128 v[14:17], v5 offset:17408
	ds_read_b128 v[18:21], v5 offset:18688
	ds_read_b128 v[22:25], v5 offset:19968
	ds_read_b128 v[26:29], v26 offset:17408
	ds_read_b128 v[54:57], v64 offset:38288
	ds_read_b32 v2, v2 offset:38400
	ds_read_b128 v[58:61], v58 offset:27648
	ds_read_b128 v[90:93], v147 offset:8704
	ds_read_b128 v[82:85], v147 offset:8768
	ds_read_b128 v[86:89], v147 offset:4352
	ds_read_b128 v[78:81], v147 offset:4416
	ds_read_b128 v[64:67], v64 offset:38272
	s_waitcnt lgkmcnt(5)
	v_lshlrev_b32_e32 v68, 16, v58
	v_and_b32_e32 v69, 0xffff0000, v58
	v_lshlrev_b32_e32 v70, 16, v60
	v_and_b32_e32 v71, 0xffff0000, v60
	v_lshlrev_b32_e32 v60, 16, v61
	v_and_b32_e32 v61, 0xffff0000, v61
	s_waitcnt lgkmcnt(0)
	v_mul_f32_e32 v64, v64, v68
	v_mul_f32_e32 v65, v65, v69
	v_mul_f32_e32 v68, v54, v70
	v_mul_f32_e32 v69, v55, v71
	v_mul_f32_e32 v60, v56, v60
	v_mul_f32_e32 v61, v57, v61
	v_mfma_f32_16x16x32_bf16 v[54:57], v[90:93], v[86:89], 0
	v_lshlrev_b32_e32 v58, 16, v59
	v_and_b32_e32 v59, 0xffff0000, v59
	v_mul_f32_e32 v58, v66, v58
	v_mul_f32_e32 v59, v67, v59
	v_cvt_pk_bf16_f32 v66, v64, v65
	v_cvt_pk_bf16_f32 v67, v58, v59
	v_cvt_pk_bf16_f32 v68, v68, v69
	v_mfma_f32_16x16x32_bf16 v[94:97], v[82:85], v[78:81], v[54:57]
	v_cvt_pk_bf16_f32 v69, v60, v61
	ds_read_b128 v[98:101], v74 offset:17408
	ds_read_b128 v[102:105], v5 offset:25088
	v_lshl_add_u32 v170, v163, 2, s2
	s_waitcnt vmcnt(5)
	v_mul_f32_e32 v56, v52, v2
	v_mul_f32_e32 v57, v53, v2
	v_mul_f32_e32 v54, v50, v2
	v_mul_f32_e32 v55, v51, v2
	s_waitcnt vmcnt(4)
	v_mul_f32_e32 v60, v48, v2
	v_mul_f32_e32 v61, v49, v2
	v_mul_f32_e32 v58, v46, v2
	v_mul_f32_e32 v59, v47, v2
	v_mfma_f32_16x16x32_bf16 v[14:17], v[14:17], v[66:69], v[54:57]
	s_waitcnt vmcnt(3)
	v_mul_f32_e32 v72, v44, v2
	v_mul_f32_e32 v73, v45, v2
	v_mul_f32_e32 v70, v42, v2
	v_mul_f32_e32 v71, v43, v2
	s_waitcnt vmcnt(1)
	v_mul_f32_e32 v76, v36, v2
	v_mul_f32_e32 v77, v37, v2
	ds_read_b128 v[54:57], v5 offset:22528
	v_mfma_f32_16x16x32_bf16 v[18:21], v[18:21], v[66:69], v[58:61]
	v_mul_f32_e64 v74, v34, v2
	v_mul_f32_e64 v75, v35, v2
	s_nop 0
	ds_read_b128 v[58:61], v5 offset:23808
	v_mfma_f32_16x16x32_bf16 v[22:25], v[22:25], v[66:69], v[70:73]
	s_waitcnt lgkmcnt(1)
	v_mfma_f32_16x16x32_bf16 v[54:57], v[54:57], v[66:69], v[74:77]
	s_nop 0
	v_mul_f32_e64 v72, v40, v2
	v_mul_f32_e64 v73, v41, v2
	v_mul_f32_e32 v70, v38, v2
	v_mul_f32_e32 v71, v39, v2
	s_waitcnt vmcnt(0)
	v_mul_f32_e32 v76, v32, v2
	v_mul_f32_e32 v77, v33, v2
	v_mfma_f32_16x16x32_bf16 v[26:29], v[26:29], v[66:69], v[70:73]
	v_mul_f32_e64 v74, v30, v2
	v_mul_f32_e64 v75, v31, v2
	s_nop 0
	global_load_dwordx4 v[70:73], v[62:63], off offset:384
	s_waitcnt lgkmcnt(0)
	v_mfma_f32_16x16x32_bf16 v[58:61], v[58:61], v[66:69], v[74:77]
	s_nop 2
	global_load_dwordx4 v[74:77], v[62:63], off offset:448
	ds_read_b128 v[114:117], v147 offset:8832
	ds_read_b128 v[118:121], v147 offset:8896
	ds_read_b128 v[122:125], v147 offset:4480
	ds_read_b128 v[172:175], v147 offset:4544
	s_waitcnt lgkmcnt(1)
	v_mfma_f32_16x16x32_bf16 v[94:97], v[114:117], v[122:125], v[94:97]
	s_waitcnt vmcnt(1)
	v_mul_f32_e32 v64, v72, v2
	v_mul_f32_e32 v65, v73, v2
	v_mul_f32_e32 v62, v70, v2
	v_mul_f32_e32 v63, v71, v2
	s_waitcnt lgkmcnt(0)
	v_mfma_f32_16x16x32_bf16 v[94:97], v[118:121], v[172:175], v[94:97]
	v_mfma_f32_16x16x32_bf16 v[62:65], v[102:105], v[66:69], v[62:65]
	s_waitcnt vmcnt(0)
	v_mul_f32_e32 v104, v76, v2
	v_mul_f32_e32 v105, v77, v2
	v_mul_f32_e32 v102, v74, v2
	v_mul_f32_e32 v103, v75, v2
	v_add_u32_e32 v2, v3, v167
	v_add_u32_e32 v3, 0x1000, v2
	v_mfma_f32_16x16x32_bf16 v[66:69], v[98:101], v[66:69], v[102:105]
	ds_read_b128 v[98:101], v147
	s_nop 1
	ds_read_b128 v[102:105], v147 offset:64
	s_waitcnt lgkmcnt(1)
	v_mfma_f32_16x16x32_bf16 v[90:93], v[90:93], v[98:101], 0
	ds_read_b128 v[98:101], v147 offset:13056
	ds_read_b128 v[110:113], v147 offset:13120
	ds_read2_b64 v[106:109], v2 offset1:4
	s_waitcnt lgkmcnt(2)
	v_mfma_f32_16x16x32_bf16 v[86:89], v[98:101], v[86:89], 0
	v_mfma_f32_16x16x32_bf16 v[82:85], v[82:85], v[102:105], v[90:93]
	ds_read_b128 v[126:129], v147 offset:13184
	s_nop 1
	ds_read_b128 v[90:93], v147 offset:128
	s_waitcnt lgkmcnt(3)
	v_mfma_f32_16x16x32_bf16 v[78:81], v[110:113], v[78:81], v[86:89]
	ds_read2_b64 v[110:113], v3 offset0:32 offset1:36
	ds_read2_b64 v[102:105], v2 offset0:8 offset1:12
	ds_read_b128 v[176:179], v147 offset:192
	s_waitcnt lgkmcnt(3)
	v_mfma_f32_16x16x32_bf16 v[114:117], v[114:117], v[90:93], v[82:85]
	ds_read2_b64 v[98:101], v3 offset0:40 offset1:44
	ds_read2_b64 v[90:93], v2 offset0:16 offset1:20
	ds_read_b128 v[180:183], v147 offset:13248
	v_mfma_f32_16x16x32_bf16 v[184:187], v[126:129], v[122:125], v[78:81]
	ds_read2_b64 v[86:89], v3 offset0:48 offset1:52
	ds_read2_b64 v[82:85], v2 offset0:24 offset1:28
	s_nop 0
	ds_read2_b64 v[78:81], v3 offset0:56 offset1:60
	v_lshl_add_u32 v2, v160, 2, s2
	v_add_u32_e32 v2, 0x9400, v2
	s_waitcnt lgkmcnt(6)
	v_mfma_f32_16x16x32_bf16 v[126:129], v[118:121], v[176:179], v[114:117]
	ds_read2_b32 v[2:3], v2 offset1:16
	s_nop 1
	ds_read_b128 v[114:117], v170 offset:37888
	ds_read_b128 v[122:125], v170 offset:37952
	s_waitcnt lgkmcnt(6)
	v_mfma_f32_16x16x32_bf16 v[118:121], v[180:183], v[172:175], v[184:187]
	s_and_saveexec_b64 s[2:3], s[44:45]
	s_xor_b64 s[2:3], exec, s[2:3]
	s_cbranch_execz .LBB0_439
	s_waitcnt lgkmcnt(1)
	v_sub_f32_e32 v5, v2, v114
	v_min_f32_e32 v5, 0, v5
	v_mul_f32_e32 v5, 0x3fb8aa3b, v5
	v_exp_f32_e32 v5, v5
	s_nop 0
	v_mul_f32_e32 v5, v126, v5

; #define LAS __attribute__((address_space(3)))
; #define MFMA16(a, b, c) __builtin_amdgcn_mfma_f32_16x16x32_bf16((a), (b), (c), 0, 0, 0)
; __device__ __forceinline__ bf16x8 pack_frag(const f32x4 a, const f32x4 b) { v4u w; w.x = cvtpk(a[0], a[1]); w.y = cvtpk(a[2], a[3]); w.z = cvtpk(b[0], b[1]); w.w = cvtpk(b[2], b[3]); return __builtin_bit_cast(bf16x8, w); }
; __device__ __forceinline__ void s2_ssd_state(LAS unsigned char* U, f32x4 (&S)[8], const int hh, const int ps, const int lane) {
;     const int q = lane >> 4, r16 = lane & 15, p = 16 * ps + r16;
;     const LAS float* tab = (const LAS float*)(U + SL::OFF_TAB) + hh * 160;
;     const LAS unsigned char* xrow = U + SL::OFF_XT + hh * 5120 + p * 80;
;     bf16x8 btf[8];
; #pragma unroll
;     for (int nt = 0; nt < 8; ++nt) btf[nt] = frag16(U + SL::OFF_BT + (16 * nt + r16) * 80 + (8 * q) * 2);
;     const v4u xn = *(const LAS v4u*)(xrow + (8 * q) * 2);
;     const f32x4 w0 = *(const LAS f32x4*)(tab + 96 + 8 * q), w1 = *(const LAS f32x4*)(tab + 96 + 8 * q + 4);
;     const float eL = tab[128];
;     const f32x4 xa = {bfe(xn, 0) * w0[0], bfe(xn, 1) * w0[1], bfe(xn, 2) * w0[2], bfe(xn, 3) * w0[3]}, xc = {bfe(xn, 4) * w1[0], bfe(xn, 5) * w1[1], bfe(xn, 6) * w1[2], bfe(xn, 7) * w1[3]};
;     const bf16x8 xh = pack_frag(xa, xc);
; #pragma unroll
;     for (int nt = 0; nt < 8; ++nt) S[nt] = MFMA16(btf[nt], xh, S[nt] * eL);
; }
; __device__ __forceinline__ void chain_ssd(LAS unsigned char* L, const MixP& C, const int g, const int b0, const int mode, const int sc0, const int tid) {
;     ...
;         for (int u = 0; u < 2; ++u) s2_ssd_state(L + u * SL::UNIT, S, hh2, ps, lane);
; #pragma unroll
;         for (int nt = 0; nt < 8; ++nt) *(f32x4*)(dsp + 16 * nt + 4 * q2) = S[nt];
;         if (ps == 0 && lane == 0) C.ESC[((size_t)(b0 * 2 + g) * (TP / 64) + sc0) * 2 + hh2] = ((const LAS float*)(L + SL::OFF_TAB))[hh2 * 160 + 128] * ((const LAS float*)(L + SL::UNIT + SL::OFF_TAB))[hh2 * 160 + 128];
.LBB0_454:
	s_add_i32 s2, s2, 0
	s_add_i32 s3, s2, s18
	s_add_i32 s12, s2, s19
	v_add_u32_e32 v5, s2, v2
	v_add_u32_e32 v71, v5, v157
	v_add3_u32 v54, s12, v156, v2
	v_add_u32_e32 v66, s3, v3
	v_mov_b32_e32 v70, s3
	ds_read_b128 v[46:49], v71 offset:17408
	ds_read_b128 v[50:53], v71 offset:18688
	ds_read_b128 v[54:57], v54 offset:27648
	ds_read_b128 v[58:61], v71 offset:19968
	ds_read_b128 v[62:65], v66 offset:38272
	ds_read_b128 v[66:69], v66 offset:38288
	ds_read_b32 v70, v70 offset:38400
	s_waitcnt lgkmcnt(4)
	v_lshlrev_b32_e32 v72, 16, v54
	v_and_b32_e32 v73, 0xffff0000, v54
	v_lshlrev_b32_e32 v54, 16, v55
	v_and_b32_e32 v55, 0xffff0000, v55
	v_lshlrev_b32_e32 v74, 16, v56
	v_and_b32_e32 v75, 0xffff0000, v56
	v_lshlrev_b32_e32 v56, 16, v57
	v_and_b32_e32 v57, 0xffff0000, v57
	s_waitcnt lgkmcnt(2)
	v_mul_f32_e32 v62, v62, v72
	v_mul_f32_e32 v63, v63, v73
	v_mul_f32_e32 v64, v64, v54
	v_mul_f32_e32 v65, v65, v55
	s_waitcnt lgkmcnt(1)
	v_mul_f32_e32 v66, v66, v74
	v_mul_f32_e32 v67, v67, v75
	v_mul_f32_e32 v68, v68, v56
	v_mul_f32_e32 v69, v69, v57
	v_add_u32_e32 v76, v5, v158
	s_waitcnt lgkmcnt(0)
	v_mul_f32_e32 v32, v32, v70
	v_mul_f32_e32 v33, v33, v70
	v_mul_f32_e32 v30, v30, v70
	v_mul_f32_e32 v31, v31, v70
	v_cvt_pk_bf16_f32 v54, v62, v63
	v_cvt_pk_bf16_f32 v55, v64, v65
	v_cvt_pk_bf16_f32 v56, v66, v67
	v_cvt_pk_bf16_f32 v57, v68, v69
	v_mul_f32_e32 v20, v20, v70
	v_mul_f32_e32 v21, v21, v70
	v_mul_f32_e32 v18, v18, v70
	v_mul_f32_e32 v19, v19, v70
	v_mfma_f32_16x16x32_bf16 v[30:33], v[46:49], v[54:57], v[30:33]
	ds_read_b128 v[46:49], v76 offset:17408
	v_add_u32_e32 v5, v5, v159
	v_mul_f32_e32 v28, v28, v70
	v_mul_f32_e32 v29, v29, v70
	v_mfma_f32_16x16x32_bf16 v[18:21], v[50:53], v[54:57], v[18:21]
	ds_read_b128 v[50:53], v71 offset:22528
	v_mul_f32_e32 v26, v26, v70
	v_mul_f32_e32 v27, v27, v70
	v_mul_f32_e32 v24, v24, v70
	v_mul_f32_e32 v25, v25, v70
	v_mul_f32_e32 v22, v22, v70
	v_mul_f32_e32 v23, v23, v70
	v_mul_f32_e32 v36, v36, v70
	v_mul_f32_e32 v37, v37, v70
	v_mul_f32_e32 v34, v34, v70
	v_mul_f32_e32 v35, v35, v70
	v_mfma_f32_16x16x32_bf16 v[26:29], v[58:61], v[54:57], v[26:29]
	ds_read_b128 v[58:61], v5 offset:17408
	v_mul_f32_e32 v40, v40, v70
	v_mul_f32_e32 v41, v41, v70
	v_mul_f32_e32 v38, v38, v70
	v_mul_f32_e32 v39, v39, v70
	s_waitcnt lgkmcnt(2)
	v_mfma_f32_16x16x32_bf16 v[22:25], v[46:49], v[54:57], v[22:25]
	ds_read_b128 v[46:49], v71 offset:23808
	v_mul_f32_e32 v44, v44, v70
	v_mul_f32_e32 v45, v45, v70
	v_mul_f32_e32 v42, v42, v70
	v_mul_f32_e32 v43, v43, v70
	s_waitcnt lgkmcnt(2)
	v_mfma_f32_16x16x32_bf16 v[34:37], v[50:53], v[54:57], v[34:37]
	ds_read_b128 v[50:53], v71 offset:25088
	v_mul_f32_e32 v16, v16, v70
	v_mul_f32_e32 v17, v17, v70
	v_mul_f32_e32 v14, v14, v70
	v_mul_f32_e32 v15, v15, v70
	s_waitcnt lgkmcnt(1)
	v_mfma_f32_16x16x32_bf16 v[38:41], v[46:49], v[54:57], v[38:41]
	s_mov_b32 s2, 0xdb00
	s_andn2_b64 vcc, exec, s[0:1]
	s_mov_b64 s[0:1], 0
	s_waitcnt lgkmcnt(0)
	v_mfma_f32_16x16x32_bf16 v[42:45], v[50:53], v[54:57], v[42:45]
	v_mfma_f32_16x16x32_bf16 v[14:17], v[58:61], v[54:57], v[14:17]
	s_cbranch_vccz .LBB0_454
	v_mov_b32_e32 v145, v4
	v_lshl_add_u64 v[2:3], v[142:143], 0, v[144:145]
	global_store_dwordx4 v[2:3], v[30:33], off
	global_store_dwordx4 v[2:3], v[18:21], off offset:64
	global_store_dwordx4 v[2:3], v[26:29], off offset:128
	global_store_dwordx4 v[2:3], v[22:25], off offset:192
	global_store_dwordx4 v[2:3], v[34:37], off offset:256
	global_store_dwordx4 v[2:3], v[38:41], off offset:320
	global_store_dwordx4 v[2:3], v[42:45], off offset:384
	global_store_dwordx4 v[2:3], v[14:17], off offset:448
	v_or_b32_e32 v2, s17, v139
	v_cmp_eq_u32_e32 vcc, 0, v2
	s_and_saveexec_b64 s[0:1], vcc
	s_cbranch_execz .LBB0_457
	s_add_i32 s2, s18, 0
	v_mov_b32_e32 v2, s2
	s_add_i32 s2, s2, 0x17100
	v_mov_b32_e32 v3, s2
	ds_read_b32 v2, v2 offset:38400
	ds_read_b32 v3, v3
	s_lshl_b64 s[2:3], s[10:11], 2
	v_readlane_b32 s10, v252, 4
	s_add_u32 s2, s10, s2
	v_readlane_b32 s10, v252, 5
	s_waitcnt lgkmcnt(0)
	v_mul_f32_e32 v2, v2, v3
	s_addc_u32 s3, s10, s3
	global_store_dword v4, v2, s[2:3]

; #define LAS __attribute__((address_space(3)))
; __device__ __forceinline__ unsigned cvtpk(float lo, float hi) { const f32x2v v = {lo, hi}; return __builtin_bit_cast(unsigned, __builtin_convertvector(v, bf16x2v)); }
; __device__ __forceinline__ float oct_sum(float v) { v = quad_sum(v); v += dpp_sel<0x141, 0xf>(0.f, v); return v; }
; __device__ __forceinline__ void chain_ssd(LAS unsigned char* L, const MixP& C, const int g, const int b0, const int mode, const int sc0, const int tid) {
;     ...
;     if (mode != 2) {
;         const LAS float* yb = (const LAS float*)(L + u3 * SL::UNIT + SL::OFF_Y) + i3 * 132 + 16 * c83;
;         float y[16]; float ss = 0.f;
; #pragma unroll
;         for (int j = 0; j < 4; ++j) { const f32x4 v = *(const LAS f32x4*)(yb + 4 * j);
; #pragma unroll
;             for (int e = 0; e < 4; ++e) { const int ee = 4 * j + e; const float zv = (ee < 8) ? bfe(zz0, ee) : bfe(zz1, ee - 8); y[ee] = v[e] * zv; ss += y[ee] * y[ee]; } }
;         ss = oct_sum(ss);
;         const float r = rsqrtf(ss * (1.0f / 128.0f) + 1e-6f);
;         if (valid3) {
;             float nwv[16];
; #pragma unroll
;             for (int j = 0; j < 4; ++j) { const f32x4 t = *(const LAS f32x4*)(cst + 16 * c83 + 4 * j); nwv[4 * j] = t[0]; nwv[4 * j + 1] = t[1]; nwv[4 * j + 2] = t[2]; nwv[4 * j + 3] = t[3]; }
;             v4u w0, w1;
;             w0.x = cvtpk(y[0] * r * nwv[0], y[1] * r * nwv[1]); w0.y = cvtpk(y[2] * r * nwv[2], y[3] * r * nwv[3]); w0.z = cvtpk(y[4] * r * nwv[4], y[5] * r * nwv[5]); w0.w = cvtpk(y[6] * r * nwv[6], y[7] * r * nwv[7]);
;             w1.x = cvtpk(y[8] * r * nwv[8], y[9] * r * nwv[9]); w1.y = cvtpk(y[10] * r * nwv[10], y[11] * r * nwv[11]); w1.z = cvtpk(y[12] * r * nwv[12], y[13] * r * nwv[13]); w1.w = cvtpk(y[14] * r * nwv[14], y[15] * r * nwv[15]);
;             bf16* mo = C.mixb + (size_t)row3 * D + MC_SSM + 128 * g + 16 * c83;
;             *(v4u*)mo = w0; *(v4u*)(mo + 8) = w1;
;         }
.LBB0_458:
	s_waitcnt lgkmcnt(0)
	s_barrier
	s_cmp_eq_u32 s15, 2
	s_cbranch_scc1 .LBB0_462
	v_mul_u32_u24_e32 v2, 0x210, v155
	v_lshlrev_b32_e32 v3, 2, v135
	v_add3_u32 v2, v140, v2, v3
	ds_read_b128 v[14:17], v2 offset:39168
	ds_read_b128 v[18:21], v2 offset:39184
	ds_read_b128 v[22:25], v2 offset:39200
	ds_read_b128 v[26:29], v2 offset:39216
	s_waitcnt vmcnt(1)
	v_lshlrev_b32_e32 v2, 16, v10
	v_and_b32_e32 v3, 0xffff0000, v10
	s_waitcnt lgkmcnt(3)
	v_mul_f32_e32 v2, v14, v2
	v_mul_f32_e32 v3, v15, v3
	v_lshlrev_b32_e32 v10, 16, v11
	v_and_b32_e32 v11, 0xffff0000, v11
	v_mul_f32_e32 v30, v2, v2
	v_mul_f32_e32 v31, v3, v3
	v_mul_f32_e32 v10, v16, v10
	v_mul_f32_e32 v11, v17, v11
	v_lshlrev_b32_e32 v14, 16, v12
	v_mul_f32_e32 v32, v10, v10
	v_mul_f32_e32 v33, v11, v11
	v_and_b32_e32 v15, 0xffff0000, v12
	v_add_f32_e32 v5, v30, v31
	s_waitcnt lgkmcnt(2)
	v_mul_f32_e32 v14, v18, v14
	v_mul_f32_e32 v15, v19, v15
	v_add_f32_e32 v5, v32, v5
	v_mul_f32_e32 v34, v14, v14
	v_mul_f32_e32 v35, v15, v15
	v_lshlrev_b32_e32 v12, 16, v13
	v_and_b32_e32 v13, 0xffff0000, v13
	v_add_f32_e32 v5, v33, v5
	v_mul_f32_e32 v16, v20, v12
	v_mul_f32_e32 v17, v21, v13
	v_add_f32_e32 v5, v34, v5
	v_mul_f32_e32 v20, v16, v16
	v_mul_f32_e32 v21, v17, v17
	s_waitcnt vmcnt(0)
	v_lshlrev_b32_e32 v12, 16, v6
	v_and_b32_e32 v13, 0xffff0000, v6
	v_add_f32_e32 v5, v35, v5
	s_waitcnt lgkmcnt(1)
	v_mul_f32_e32 v12, v22, v12
	v_mul_f32_e32 v13, v23, v13
	v_add_f32_e32 v5, v20, v5
	v_mul_f32_e32 v22, v12, v12
	v_mul_f32_e32 v23, v13, v13
	v_lshlrev_b32_e32 v6, 16, v7
	v_and_b32_e32 v7, 0xffff0000, v7
	v_add_f32_e32 v5, v21, v5
	v_mul_f32_e32 v6, v24, v6
	v_mul_f32_e32 v7, v25, v7
	v_add_f32_e32 v5, v22, v5
	v_mul_f32_e32 v24, v6, v6
	v_mul_f32_e32 v25, v7, v7
	v_lshlrev_b32_e32 v18, 16, v8
	v_and_b32_e32 v19, 0xffff0000, v8
	v_add_f32_e32 v5, v23, v5
	s_waitcnt lgkmcnt(0)
	v_mul_f32_e32 v18, v26, v18
	v_mul_f32_e32 v19, v27, v19
	v_add_f32_e32 v5, v24, v5
	v_mul_f32_e32 v26, v18, v18
	v_mul_f32_e32 v27, v19, v19
	v_lshlrev_b32_e32 v8, 16, v9
	v_and_b32_e32 v9, 0xffff0000, v9
	v_add_f32_e32 v5, v25, v5
	v_mul_f32_e32 v8, v28, v8
	v_mul_f32_e32 v9, v29, v9
	v_add_f32_e32 v5, v26, v5
	v_mul_f32_e32 v28, v8, v8
	v_mul_f32_e32 v29, v9, v9
	v_add_f32_e32 v5, v27, v5
	v_add_f32_e32 v5, v28, v5
	v_add_f32_e32 v5, v29, v5
	v_mov_b32_e32 v20, v4
	s_or_b64 s[2:3], s[38:39], s[40:41]
	v_add_f32_dpp v5, v5, v5 quad_perm:[1,0,3,2] row_mask:0xf bank_mask:0xf bound_ctrl:1
	s_nop 1
	v_add_f32_dpp v5, v5, v5 quad_perm:[2,3,0,1] row_mask:0xf bank_mask:0xf bound_ctrl:1
	s_nop 1
	v_mov_b32_dpp v20, v5 row_half_mirror row_mask:0xf bank_mask:0xf
	s_and_saveexec_b64 s[0:1], s[2:3]
	s_cbranch_execz .LBB0_461
	v_add_f32_e32 v5, v5, v20
	v_fmamk_f32 v5, v5, 0x3c000000, v231
	s_mov_b32 s2, 0x800000
	v_mul_f32_e32 v20, 0x4b800000, v5
	v_cmp_gt_f32_e32 vcc, s2, v5
	v_readlane_b32 s2, v254, 26
	v_readlane_b32 s3, v254, 27
	v_cndmask_b32_e32 v5, v5, v20, vcc
	v_rsq_f32_e32 v5, v5
	v_lshl_add_u32 v20, v135, 2, 0
	v_add_u32_e32 v32, 0x1bc00, v20
	s_lshl_b32 s62, s16, 1
	v_mul_f32_e32 v20, 0x45800000, v5
	v_cndmask_b32_e32 v36, v5, v20, vcc
	ds_read_b128 v[20:23], v32
	ds_read_b128 v[24:27], v32 offset:16
	ds_read_b128 v[28:31], v32 offset:32
	ds_read_b128 v[32:35], v32 offset:48
	v_mul_f32_e32 v2, v2, v36
	v_mul_f32_e32 v3, v3, v36
	v_mov_b32_e32 v139, v4
	s_waitcnt lgkmcnt(3)
	v_mul_f32_e32 v2, v2, v20
	v_mul_f32_e32 v3, v3, v21
	s_nop 0
	v_cvt_pk_bf16_f32 v20, v2, v3
	v_mul_f32_e32 v2, v10, v36
	v_mul_f32_e32 v3, v11, v36
	s_nop 0
	v_mul_f32_e32 v2, v2, v22
	v_mul_f32_e32 v3, v3, v23
	s_nop 0
	v_cvt_pk_bf16_f32 v21, v2, v3
	v_mul_f32_e32 v2, v14, v36
	v_mul_f32_e32 v3, v15, v36
	s_waitcnt lgkmcnt(2)
	v_mul_f32_e32 v2, v2, v24
	v_mul_f32_e32 v3, v3, v25
	s_nop 0
	v_cvt_pk_bf16_f32 v22, v2, v3
	v_mul_f32_e32 v2, v16, v36
	v_mul_f32_e32 v3, v17, v36
	s_nop 0
	v_mul_f32_e32 v2, v2, v26
	v_mul_f32_e32 v3, v3, v27
	s_nop 0
	v_cvt_pk_bf16_f32 v23, v2, v3
	v_mul_f32_e32 v2, v12, v36
	v_mul_f32_e32 v3, v13, v36
	s_waitcnt lgkmcnt(1)
	v_mul_f32_e32 v2, v2, v28
	v_mul_f32_e32 v3, v3, v29
	s_nop 0
	v_cvt_pk_bf16_f32 v10, v2, v3
	v_mul_f32_e32 v2, v6, v36
	v_mul_f32_e32 v3, v7, v36
	s_nop 0
	v_mul_f32_e32 v2, v2, v30
	v_mul_f32_e32 v3, v3, v31
	s_nop 0
	v_cvt_pk_bf16_f32 v11, v2, v3
	v_mul_f32_e32 v2, v18, v36
	v_mul_f32_e32 v3, v19, v36
	s_waitcnt lgkmcnt(0)
	v_mul_f32_e32 v2, v2, v32
	v_mul_f32_e32 v3, v3, v33
	s_nop 0
	v_cvt_pk_bf16_f32 v12, v2, v3
	v_mul_f32_e32 v2, v8, v36
	v_mul_f32_e32 v3, v9, v36
	s_nop 0
	v_mul_f32_e32 v2, v2, v34
	v_mul_f32_e32 v3, v3, v35
	s_nop 0
	v_cvt_pk_bf16_f32 v13, v2, v3
	v_lshlrev_b64 v[2:3], 11, v[136:137]
	v_lshl_add_u64 v[2:3], s[2:3], 0, v[2:3]
	v_lshl_add_u64 v[2:3], v[2:3], 0, s[62:63]
	v_lshl_add_u64 v[2:3], v[2:3], 0, v[138:139]
	global_store_dwordx4 v[2:3], v[20:23], off offset:1536
	global_store_dwordx4 v[2:3], v[10:13], off offset:1552

; #define LAS __attribute__((address_space(3)))
; __device__ __forceinline__ float logsigmoid_f(float x) { return fminf(x, 0.f) - lse0_f(x); }
; template <int MT>
; __device__ __forceinline__ void chain_gh(LAS unsigned char* L, const MixP& C, const int h, const int b0, const bool smp, const int tid) {
;     ...
;                 const v4u gq = rw0, gk = rw1, lr0 = rw2, lr1 = rw3;
;                 float lg[NK];
; #pragma unroll
;                 for (int e = 0; e < NK; ++e) lg[e] = cst[512 + 8 * kg + e];
; #pragma unroll
;                 for (int j = 0; j < 16; ++j) { const float lv = (j < 8) ? bfe(lr0, j) : bfe(lr1, j - 8);
;                     const f32x4 w0 = *(const LAS f32x4*)(cst + j * 32 + 8 * kg), w1 = *(const LAS f32x4*)(cst + j * 32 + 8 * kg + 4);
;                     lg[0] += lv * w0[0]; lg[1] += lv * w0[1]; lg[2] += lv * w0[2]; lg[3] += lv * w0[3]; lg[4] += lv * w1[0]; lg[5] += lv * w1[1]; lg[6] += lv * w1[2]; lg[7] += lv * w1[3]; }
; #pragma unroll
;                 for (int e = 0; e < NK; ++e) { f[e] = __expf(logsigmoid_f(lg[e]) * (1.0f / 16.0f)); kk[e] = bfe(gk, e); qq[e] = bfe(gq, e) * 0.17677669529663687f; }
.LBB0_474:
	s_waitcnt vmcnt(6)
	ds_read_b128 v[38:41], v71
	ds_read_b128 v[42:45], v71 offset:2048
	ds_read_b128 v[46:49], v71 offset:2064
	s_waitcnt vmcnt(3)
	v_lshlrev_b32_e32 v2, 16, v34
	ds_read_b128 v[50:53], v71 offset:16
	s_waitcnt vmcnt(2)
	v_and_b32_e32 v3, 0xffff0000, v31
	s_waitcnt lgkmcnt(2)
	v_fma_f32 v5, v38, v2, v42
	v_fma_f32 v42, v39, v2, v43
	v_fma_f32 v43, v40, v2, v44
	v_fmac_f32_e32 v45, v41, v2
	ds_read_b128 v[38:41], v71 offset:128
	s_waitcnt lgkmcnt(1)
	v_fma_f32 v44, v50, v2, v46
	v_fma_f32 v46, v51, v2, v47
	v_fma_f32 v47, v52, v2, v48
	v_fmac_f32_e32 v49, v53, v2
	v_and_b32_e32 v2, 0xffff0000, v34
	ds_read_b128 v[50:53], v71 offset:144
	s_waitcnt lgkmcnt(1)
	v_fmac_f32_e32 v5, v38, v2
	v_fmac_f32_e32 v42, v39, v2
	v_fmac_f32_e32 v43, v40, v2
	v_fmac_f32_e32 v45, v41, v2
	ds_read_b128 v[38:41], v71 offset:256
	s_waitcnt lgkmcnt(1)
	v_fmac_f32_e32 v44, v50, v2
	v_fmac_f32_e32 v46, v51, v2
	v_fmac_f32_e32 v47, v52, v2
	v_fmac_f32_e32 v49, v53, v2
	v_lshlrev_b32_e32 v2, 16, v35
	ds_read_b128 v[50:53], v71 offset:272
	s_waitcnt lgkmcnt(1)
	v_fmac_f32_e32 v5, v38, v2
	v_fmac_f32_e32 v42, v39, v2
	v_fmac_f32_e32 v43, v40, v2
	v_fmac_f32_e32 v45, v41, v2
	ds_read_b128 v[38:41], v71 offset:384
	s_waitcnt lgkmcnt(1)
	v_fmac_f32_e32 v44, v50, v2
	v_fmac_f32_e32 v46, v51, v2
	v_fmac_f32_e32 v47, v52, v2
	v_fmac_f32_e32 v49, v53, v2
	v_and_b32_e32 v2, 0xffff0000, v35
	ds_read_b128 v[50:53], v71 offset:400
	s_waitcnt lgkmcnt(1)
	v_fmac_f32_e32 v5, v38, v2
	v_fmac_f32_e32 v42, v39, v2
	v_fmac_f32_e32 v43, v40, v2
	v_fmac_f32_e32 v45, v41, v2
	ds_read_b128 v[38:41], v71 offset:512
	s_waitcnt lgkmcnt(1)
	v_fmac_f32_e32 v44, v50, v2
	v_fmac_f32_e32 v46, v51, v2
	v_fmac_f32_e32 v47, v52, v2
	v_fmac_f32_e32 v49, v53, v2
	v_lshlrev_b32_e32 v2, 16, v36
	ds_read_b128 v[50:53], v71 offset:528
	s_waitcnt lgkmcnt(1)
	v_fmac_f32_e32 v5, v38, v2
	v_fmac_f32_e32 v42, v39, v2
	v_fmac_f32_e32 v43, v40, v2
	v_fmac_f32_e32 v45, v41, v2
	ds_read_b128 v[38:41], v71 offset:640
	s_waitcnt lgkmcnt(1)
	v_fmac_f32_e32 v44, v50, v2
	v_fmac_f32_e32 v46, v51, v2
	v_fmac_f32_e32 v47, v52, v2
	v_fmac_f32_e32 v49, v53, v2
	v_and_b32_e32 v2, 0xffff0000, v36
	ds_read_b128 v[50:53], v71 offset:656
	s_waitcnt lgkmcnt(1)
	v_fmac_f32_e32 v5, v38, v2
	v_fmac_f32_e32 v42, v39, v2
	v_fmac_f32_e32 v43, v40, v2
	v_fmac_f32_e32 v45, v41, v2
	ds_read_b128 v[38:41], v71 offset:768
	s_waitcnt lgkmcnt(1)
	v_fmac_f32_e32 v44, v50, v2
	v_fmac_f32_e32 v46, v51, v2
	v_fmac_f32_e32 v47, v52, v2
	v_fmac_f32_e32 v49, v53, v2
	v_lshlrev_b32_e32 v2, 16, v37
	ds_read_b128 v[50:53], v71 offset:784
	s_waitcnt lgkmcnt(1)
	v_fmac_f32_e32 v5, v38, v2
	v_fmac_f32_e32 v42, v39, v2
	v_fmac_f32_e32 v43, v40, v2
	v_fmac_f32_e32 v45, v41, v2
	ds_read_b128 v[38:41], v71 offset:896
	s_waitcnt lgkmcnt(1)
	v_fmac_f32_e32 v44, v50, v2
	v_fmac_f32_e32 v46, v51, v2
	v_fmac_f32_e32 v47, v52, v2
	v_fmac_f32_e32 v49, v53, v2
	v_and_b32_e32 v2, 0xffff0000, v37
	ds_read_b128 v[34:37], v71 offset:912
	s_waitcnt lgkmcnt(1)
	v_fmac_f32_e32 v5, v38, v2
	v_fmac_f32_e32 v42, v39, v2
	v_fmac_f32_e32 v43, v40, v2
	v_fmac_f32_e32 v45, v41, v2
	ds_read_b128 v[38:41], v71 offset:1024
	s_waitcnt lgkmcnt(1)
	v_fmac_f32_e32 v44, v34, v2
	v_fmac_f32_e32 v46, v35, v2
	v_fmac_f32_e32 v47, v36, v2
	v_fmac_f32_e32 v49, v37, v2
	v_lshlrev_b32_e32 v2, 16, v30
	ds_read_b128 v[34:37], v71 offset:1040
	s_waitcnt lgkmcnt(1)
	v_fmac_f32_e32 v5, v38, v2
	v_fmac_f32_e32 v42, v39, v2
	v_fmac_f32_e32 v43, v40, v2
	v_fmac_f32_e32 v45, v41, v2
	ds_read_b128 v[38:41], v71 offset:1152
	s_waitcnt lgkmcnt(1)
	v_fmac_f32_e32 v44, v34, v2
	v_fmac_f32_e32 v46, v35, v2
	v_fmac_f32_e32 v47, v36, v2
	v_fmac_f32_e32 v49, v37, v2
	v_and_b32_e32 v2, 0xffff0000, v30
	ds_read_b128 v[34:37], v71 offset:1168
	s_waitcnt lgkmcnt(1)
	v_fmac_f32_e32 v5, v38, v2
	v_fmac_f32_e32 v42, v39, v2
	v_fmac_f32_e32 v43, v40, v2
	v_fmac_f32_e32 v45, v41, v2
	ds_read_b128 v[38:41], v71 offset:1280
	ds_read_b128 v[50:53], v71 offset:1296
	ds_read_b128 v[54:57], v71 offset:1408
	ds_read_b128 v[58:61], v71 offset:1424
	s_waitcnt lgkmcnt(4)
	v_fmac_f32_e32 v44, v34, v2
	v_fmac_f32_e32 v46, v35, v2
	v_fmac_f32_e32 v47, v36, v2
	v_fmac_f32_e32 v49, v37, v2
	v_lshlrev_b32_e32 v2, 16, v31
	s_waitcnt lgkmcnt(3)
	v_mov_b32_e32 v34, v38
	s_waitcnt lgkmcnt(1)
	v_mov_b32_e32 v35, v54
	v_mul_f32_e32 v34, v34, v2
	v_mul_f32_e32 v35, v35, v3
	v_mov_b32_e32 v54, v39
	v_add_f32_e32 v5, v5, v34
	v_add_f32_e32 v5, v5, v35
	v_mul_f32_e32 v34, v54, v2
	v_mul_f32_e32 v35, v55, v3
	v_mov_b32_e32 v30, v53
	v_add_f32_e32 v34, v42, v34
	v_add_f32_e32 v54, v34, v35
	v_mov_b32_e32 v34, v40
	v_mov_b32_e32 v35, v56
	v_mul_f32_e32 v34, v34, v2
	v_mul_f32_e32 v35, v35, v3
	v_mov_b32_e32 v56, v41
	v_add_f32_e32 v34, v43, v34
	v_add_f32_e32 v55, v34, v35
	v_mul_f32_e32 v34, v56, v2
	v_mul_f32_e32 v35, v57, v3
	s_waitcnt lgkmcnt(0)
	v_mov_b32_e32 v31, v61
	v_add_f32_e32 v34, v45, v34
	v_add_f32_e32 v56, v34, v35
	v_mov_b32_e32 v34, v50
	v_mov_b32_e32 v35, v58
	v_mul_f32_e32 v34, v34, v2
	v_mul_f32_e32 v35, v35, v3
	v_mov_b32_e32 v58, v51
	v_add_f32_e32 v34, v44, v34
	v_add_f32_e32 v57, v34, v35
	v_mul_f32_e32 v34, v58, v2
	v_mul_f32_e32 v35, v59, v3
	v_mov_b32_e32 v53, v60
	v_mul_f32_e32 v30, v30, v2
	v_mul_f32_e32 v31, v31, v3
	v_add_f32_e32 v34, v46, v34
	v_mul_f32_e32 v2, v52, v2
	v_mul_f32_e32 v3, v53, v3
	v_add_f32_e32 v30, v49, v30
	v_add_f32_e32 v58, v34, v35
	v_add_f32_e32 v2, v47, v2
	ds_read_b128 v[34:37], v71 offset:1536
	ds_read_b128 v[38:41], v71 offset:1552
	ds_read_b128 v[42:45], v71 offset:1664
	ds_read_b128 v[46:49], v71 offset:1680
	v_add_f32_e32 v52, v2, v3
	v_add_f32_e32 v50, v30, v31
	v_lshlrev_b32_e32 v2, 16, v32
	v_and_b32_e32 v3, 0xffff0000, v32
	s_waitcnt lgkmcnt(2)
; #define LAS __attribute__((address_space(3)))
; __device__ __forceinline__ float sigmoid_f(float x) { return __builtin_amdgcn_rcpf(1.0f + __expf(-x)); }
; __device__ __forceinline__ float logsigmoid_f(float x) { return fminf(x, 0.f) - lse0_f(x); }
; template <int MT>
; __device__ __forceinline__ void chain_gh(LAS unsigned char* L, const MixP& C, const int h, const int b0, const bool smp, const int tid) {
;     ...
;                 for (int j = 0; j < 16; ++j) { const float lv = (j < 8) ? bfe(lr0, j) : bfe(lr1, j - 8);
;                     const f32x4 w0 = *(const LAS f32x4*)(cst + j * 32 + 8 * kg), w1 = *(const LAS f32x4*)(cst + j * 32 + 8 * kg + 4);
;                     lg[0] += lv * w0[0]; lg[1] += lv * w0[1]; lg[2] += lv * w0[2]; lg[3] += lv * w0[3]; lg[4] += lv * w1[0]; lg[5] += lv * w1[1]; lg[6] += lv * w1[2]; lg[7] += lv * w1[3]; }
; #pragma unroll
;                 for (int e = 0; e < NK; ++e) { f[e] = __expf(logsigmoid_f(lg[e]) * (1.0f / 16.0f)); kk[e] = bfe(gk, e); qq[e] = bfe(gq, e) * 0.17677669529663687f; }
;             } else {
;                 const v4u rq0 = rw0, rq1 = rw1, rf0 = rw2, rf1 = rw3;
; #pragma unroll
;                 for (int e = 0; e < NK; ++e) { const float z = (e < 8) ? bfe(rf0, e) : bfe(rf1, e - 8), qv = (e < 8) ? bfe(rq0, e) : bfe(rq1, e - 8);
;                     const float lb = cst[16 * kg + e], sg = sigmoid_f(z);
;                     f[e] = lb + (1.f - lb) * sg; kk[e] = (1.f - lb) * (1.f - sg); qq[e] = qv; }
;             }
;             if (!valid) {
; #pragma unroll
;                 for (int e = 0; e < NK; ++e) { f[e] = 1.f; kk[e] = 0.f; qq[e] = 0.f; }
;                 vraw0 = (v4u){0u, 0u, 0u, 0u}; vraw1 = vraw0;
;             }
	v_mov_b32_e32 v30, v41
	s_waitcnt lgkmcnt(0)
	v_mov_b32_e32 v31, v49
	v_mul_f32_e32 v30, v30, v2
	v_mul_f32_e32 v31, v31, v3
	v_mov_b32_e32 v51, v42
	v_mov_b32_e32 v42, v35
	v_add_f32_e32 v30, v50, v30
	v_mov_b32_e32 v50, v34
	v_mul_f32_e32 v34, v42, v2
	v_mul_f32_e32 v35, v43, v3
	v_mul_f32_e32 v50, v50, v2
	v_mul_f32_e32 v51, v51, v3
	v_add_f32_e32 v32, v54, v34
	v_add_f32_e32 v5, v5, v50
	v_add_f32_e32 v50, v32, v35
	v_mov_b32_e32 v34, v36
	v_mov_b32_e32 v35, v44
	v_mul_f32_e32 v34, v34, v2
	v_mul_f32_e32 v35, v35, v3
	v_mov_b32_e32 v44, v37
	v_add_f32_e32 v32, v55, v34
	v_add_f32_e32 v5, v5, v51
	v_add_f32_e32 v51, v32, v35
	v_mul_f32_e32 v34, v44, v2
	v_mul_f32_e32 v35, v45, v3
	v_mov_b32_e32 v41, v48
	v_add_f32_e32 v32, v56, v34
	v_add_f32_e32 v53, v32, v35
	v_mov_b32_e32 v34, v38
	v_mov_b32_e32 v35, v46
	v_mul_f32_e32 v34, v34, v2
	v_mul_f32_e32 v35, v35, v3
	v_mov_b32_e32 v46, v39
	v_add_f32_e32 v32, v57, v34
	v_add_f32_e32 v54, v32, v35
	v_mul_f32_e32 v34, v46, v2
	v_mul_f32_e32 v35, v47, v3
	v_mul_f32_e32 v2, v40, v2
	v_mul_f32_e32 v3, v41, v3
	v_add_f32_e32 v32, v58, v34
	v_add_f32_e32 v55, v32, v35
	ds_read_b128 v[34:37], v71 offset:1792
	ds_read_b128 v[38:41], v71 offset:1808
	ds_read_b128 v[42:45], v71 offset:1920
	ds_read_b128 v[46:49], v71 offset:1936
	v_add_f32_e32 v2, v52, v2
	v_add_f32_e32 v52, v2, v3
	v_add_f32_e32 v32, v30, v31
	v_lshlrev_b32_e32 v2, 16, v33
	v_and_b32_e32 v3, 0xffff0000, v33
	s_waitcnt lgkmcnt(2)
	v_mov_b32_e32 v30, v41
	s_waitcnt lgkmcnt(0)
	v_mov_b32_e32 v31, v49
	v_mul_f32_e32 v30, v30, v2
	v_mul_f32_e32 v31, v31, v3
	v_mov_b32_e32 v33, v42
	v_add_f32_e32 v30, v32, v30
	v_mov_b32_e32 v32, v34
	v_mul_f32_e32 v32, v32, v2
	v_mul_f32_e32 v33, v33, v3
	v_mov_b32_e32 v42, v35
	v_add_f32_e32 v5, v5, v32
	v_add_f32_e32 v5, v5, v33
	v_mul_f32_e32 v32, v42, v2
	v_mul_f32_e32 v33, v43, v3
	s_mov_b32 s2, 0xbfb8aa3b
	v_add_f32_e32 v32, v50, v32
	v_add_f32_e32 v34, v32, v33
	v_mov_b32_e32 v32, v36
	v_mov_b32_e32 v33, v44
	v_mul_f32_e32 v32, v32, v2
	v_mul_f32_e32 v33, v33, v3
	v_mov_b32_e32 v44, v37
	v_add_f32_e32 v32, v51, v32
	v_add_f32_e32 v36, v32, v33
	v_mul_f32_e32 v32, v44, v2
	v_mul_f32_e32 v33, v45, v3
	v_mov_b32_e32 v41, v48
	v_add_f32_e32 v32, v53, v32
	v_add_f32_e32 v37, v32, v33
	v_mov_b32_e32 v32, v38
	v_mov_b32_e32 v33, v46
	v_mul_f32_e32 v32, v32, v2
	v_mul_f32_e32 v33, v33, v3
	v_mov_b32_e32 v46, v39
	v_add_f32_e32 v32, v54, v32
	v_add_f32_e32 v42, v32, v33
	v_mul_f32_e32 v32, v46, v2
	v_mul_f32_e32 v33, v47, v3
	v_mul_f32_e32 v2, v40, v2
	v_mul_f32_e32 v3, v41, v3
	v_add_f32_e32 v32, v55, v32
	v_add_f32_e32 v43, v32, v33
	v_mul_f32_e64 v32, |v5|, s2
	v_exp_f32_e32 v32, v32
	v_add_f32_e32 v2, v52, v2
	v_add_f32_e32 v46, v2, v3
	v_mul_f32_e64 v3, |v34|, s2
	v_add_f32_e32 v2, 1.0, v32
	v_exp_f32_e32 v3, v3
	v_log_f32_e32 v2, v2
	v_min_f32_e32 v5, 0, v5
	v_add_f32_e32 v31, v30, v31
	v_add_f32_e32 v3, 1.0, v3
	v_fmac_f32_e32 v5, 0xbf317218, v2
	v_log_f32_e32 v3, v3
	v_mul_f32_e32 v2, 0x3d800000, v5
	v_mul_f32_e32 v2, 0x3fb8aa3b, v2
	v_exp_f32_e32 v30, v2
	v_min_f32_e32 v2, 0, v34
	v_fmac_f32_e32 v2, 0xbf317218, v3
	v_mul_f32_e32 v2, 0x3d800000, v2
	v_mul_f32_e32 v2, 0x3fb8aa3b, v2
	v_exp_f32_e32 v5, v2
	v_mul_f32_e64 v2, |v36|, s2
	v_lshlrev_b32_e32 v34, 16, v18
	v_and_b32_e32 v35, 0xffff0000, v18
	v_exp_f32_e32 v18, v2
	v_lshlrev_b32_e32 v2, 16, v14
	v_and_b32_e32 v3, 0xffff0000, v14
	s_mov_b32 s22, 0x3e3504f3
	v_pk_mul_f32 v[32:33], v[2:3], s[22:23] op_sel_hi:[1,0]
	v_mul_f32_e64 v3, |v37|, s2
	v_exp_f32_e32 v3, v3
	v_add_f32_e32 v2, 1.0, v18
	v_log_f32_e32 v2, v2
	v_min_f32_e32 v14, 0, v36
	v_add_f32_e32 v3, 1.0, v3
	v_log_f32_e32 v3, v3
	v_fmac_f32_e32 v14, 0xbf317218, v2
	v_mul_f32_e32 v2, 0x3d800000, v14
	v_min_f32_e32 v14, 0, v37
	v_fmac_f32_e32 v14, 0xbf317218, v3
	v_mul_f32_e32 v3, 0x3d800000, v14
	v_mul_f32_e32 v3, 0x3fb8aa3b, v3
	v_exp_f32_e32 v44, v3
	v_mul_f32_e64 v3, |v42|, s2
	v_exp_f32_e32 v3, v3
	v_lshlrev_b32_e32 v14, 16, v15
	v_and_b32_e32 v15, 0xffff0000, v15
	v_pk_mul_f32 v[38:39], v[14:15], s[22:23] op_sel_hi:[1,0]
	v_add_f32_e32 v3, 1.0, v3
	v_mul_f32_e64 v14, |v43|, s2
	v_log_f32_e32 v3, v3
	v_exp_f32_e32 v14, v14
	v_min_f32_e32 v15, 0, v42
	v_lshlrev_b32_e32 v40, 16, v16
	v_fmac_f32_e32 v15, 0xbf317218, v3
	v_add_f32_e32 v14, 1.0, v14
	v_mul_f32_e32 v3, 0x3d800000, v15
	v_log_f32_e32 v15, v14
	v_mul_f32_e32 v3, 0x3fb8aa3b, v3
	v_exp_f32_e32 v14, v3
	v_min_f32_e32 v3, 0, v43
	v_fmac_f32_e32 v3, 0xbf317218, v15
	v_mul_f32_e32 v3, 0x3d800000, v3
	v_mul_f32_e32 v3, 0x3fb8aa3b, v3
	v_exp_f32_e32 v45, v3
	v_mul_f32_e64 v3, |v46|, s2
	v_exp_f32_e32 v3, v3
	v_mul_f32_e64 v15, |v31|, s2
	v_exp_f32_e32 v15, v15
	v_and_b32_e32 v41, 0xffff0000, v16
	v_add_f32_e32 v3, 1.0, v3
	v_log_f32_e32 v3, v3
	v_min_f32_e32 v16, 0, v46
	v_add_f32_e32 v15, 1.0, v15
	v_log_f32_e32 v15, v15
	v_fmac_f32_e32 v16, 0xbf317218, v3
	v_mul_f32_e32 v3, 0x3d800000, v16
	v_mul_f32_e32 v3, 0x3fb8aa3b, v3
	v_exp_f32_e32 v16, v3
	v_min_f32_e32 v3, 0, v31
	v_fmac_f32_e32 v3, 0xbf317218, v15
	v_mul_f32_e32 v3, 0x3d800000, v3
	v_mul_f32_e32 v2, 0x3fb8aa3b, v2
	v_mul_f32_e32 v3, 0x3fb8aa3b, v3
	v_exp_f32_e32 v2, v2
	v_exp_f32_e32 v46, v3
	v_lshlrev_b32_e32 v42, 16, v17
	v_and_b32_e32 v43, 0xffff0000, v17
	v_lshlrev_b32_e32 v18, 16, v19
	v_and_b32_e32 v19, 0xffff0000, v19
	v_lshlrev_b32_e32 v36, 16, v20
	v_and_b32_e32 v37, 0xffff0000, v20
	v_pk_mul_f32 v[40:41], v[40:41], s[22:23] op_sel_hi:[1,0]
	v_lshlrev_b32_e32 v20, 16, v21
	v_and_b32_e32 v21, 0xffff0000, v21
	v_pk_mul_f32 v[42:43], v[42:43], s[22:23] op_sel_hi:[1,0]
	s_and_saveexec_b64 s[2:3], s[0:1]
	s_cbranch_execz .LBB0_476
	v_mov_b32_e32 v5, v4
	v_mov_b32_e32 v2, v4
	v_mov_b32_e32 v3, v4
	v_mov_b32_e32 v32, 0
	s_waitcnt vmcnt(0)
	v_mov_b64_e32 v[8:9], v[4:5]
	v_mov_b64_e32 v[12:13], v[4:5]
	v_mov_b32_e32 v30, 1.0
	v_mov_b64_e32 v[6:7], v[2:3]
	v_mov_b64_e32 v[10:11], v[2:3]
	v_mov_b32_e32 v5, 1.0
	v_mov_b32_e32 v2, 1.0
	v_mov_b32_e32 v44, 1.0
	v_mov_b32_e32 v14, 1.0
	v_mov_b32_e32 v45, 1.0
	v_mov_b32_e32 v16, 1.0
	v_mov_b32_e32 v46, 1.0
	v_mov_b32_e32 v33, v32
	v_mov_b32_e32 v38, v32
	v_mov_b32_e32 v39, v32
	v_mov_b32_e32 v40, v32
	v_mov_b32_e32 v41, v32
	v_mov_b32_e32 v42, v32
	v_mov_b32_e32 v43, v32
	v_mov_b32_e32 v34, v32
	v_mov_b32_e32 v35, v32
	v_mov_b32_e32 v20, v32
	v_mov_b32_e32 v21, v32
	v_mov_b32_e32 v36, v32
	v_mov_b32_e32 v37, v32
	v_mov_b32_e32 v18, v32
	v_mov_b32_e32 v19, v32
; #define LAS __attribute__((address_space(3)))
; __device__ __forceinline__ unsigned cvtpk(float lo, float hi) { const f32x2v v = {lo, hi}; return __builtin_bit_cast(unsigned, __builtin_convertvector(v, bf16x2v)); }
; __device__ __forceinline__ unsigned short bfbits(const v4u w, const int e) { const unsigned x = w[e >> 1]; return (unsigned short)((e & 1) ? (x >> 16) : (x & 0xffffu)); }
; template <int MT>
; __device__ __forceinline__ void chain_gh(LAS unsigned char* L, const MixP& C, const int h, const int b0, const bool smp, const int tid) {
;     ...
; #pragma unroll
;             for (int e8 = 0; e8 < NK; e8 += 8) gh_scan8(f[e8 + 0], f[e8 + 1], f[e8 + 2], f[e8 + 3], f[e8 + 4], f[e8 + 5], f[e8 + 6], f[e8 + 7]);
;             float qt[NK], kt_[NK];
; #pragma unroll
;             for (int e = 0; e < NK; ++e) { qt[e] = qq[e] * f[e]; kt_[e] = kk[e] * __builtin_amdgcn_rcpf(fmaxf(f[e], 1e-30f)); }
; #pragma unroll
;             for (int e8 = 0; e8 < NK; e8 += 8) {
;                 v4u wq, wk;
;                 wq.x = cvtpk(qt[e8 + 0], qt[e8 + 1]); wq.y = cvtpk(qt[e8 + 2], qt[e8 + 3]); wq.z = cvtpk(qt[e8 + 4], qt[e8 + 5]); wq.w = cvtpk(qt[e8 + 6], qt[e8 + 7]);
;                 wk.x = cvtpk(kt_[e8 + 0], kt_[e8 + 1]); wk.y = cvtpk(kt_[e8 + 2], kt_[e8 + 3]); wk.z = cvtpk(kt_[e8 + 4], kt_[e8 + 5]); wk.w = cvtpk(kt_[e8 + 6], kt_[e8 + 7]);
;                 *(LAS v4u*)(U + G::OFF_Q + t1 * G::RS + (NK * kg + e8) * 2) = wq;
;                 *(LAS v4u*)(U + G::OFF_K + t1 * G::RS + (NK * kg + e8) * 2) = wk;
; #pragma unroll
;                 for (int e = 0; e < 8; ++e) *(LAS unsigned short*)(U + G::OFF_KT + (NK * kg + e8 + e) * 80 + t1 * 2) = bfbits(wk, e);
;             }
; #pragma unroll
;             for (int e = 0; e < 16; ++e) *(LAS unsigned short*)(U + G::OFF_VT + (16 * kg + e) * 80 + t1 * 2) = (e < 8) ? bfbits(vraw0, e) : bfbits(vraw1, e - 8);
;             if (t1 == 31) {
; #pragma unroll
;                 for (int e = 0; e < NK; ++e) *(LAS float*)(U + G::OFF_E + (NK * kg + e) * 4) = f[e];
;             }
.LBB0_476:
	s_or_b64 exec, exec, s[2:3]
	s_nop 1
	v_mul_f32_dpp v30, v30, v30 row_shr:1 row_mask:0xf bank_mask:0xf
	v_mul_f32_dpp v5, v5, v5 row_shr:1 row_mask:0xf bank_mask:0xf
	v_mul_f32_dpp v2, v2, v2 row_shr:1 row_mask:0xf bank_mask:0xf
	v_mul_f32_dpp v44, v44, v44 row_shr:1 row_mask:0xf bank_mask:0xf
	v_mul_f32_dpp v14, v14, v14 row_shr:1 row_mask:0xf bank_mask:0xf
	v_mul_f32_dpp v45, v45, v45 row_shr:1 row_mask:0xf bank_mask:0xf
	v_mul_f32_dpp v16, v16, v16 row_shr:1 row_mask:0xf bank_mask:0xf
	v_mul_f32_dpp v46, v46, v46 row_shr:1 row_mask:0xf bank_mask:0xf
	v_mul_f32_dpp v30, v30, v30 row_shr:2 row_mask:0xf bank_mask:0xf
	v_mul_f32_dpp v5, v5, v5 row_shr:2 row_mask:0xf bank_mask:0xf
	v_mul_f32_dpp v2, v2, v2 row_shr:2 row_mask:0xf bank_mask:0xf
	v_mul_f32_dpp v44, v44, v44 row_shr:2 row_mask:0xf bank_mask:0xf
	v_mul_f32_dpp v14, v14, v14 row_shr:2 row_mask:0xf bank_mask:0xf
	v_mul_f32_dpp v45, v45, v45 row_shr:2 row_mask:0xf bank_mask:0xf
	v_mul_f32_dpp v16, v16, v16 row_shr:2 row_mask:0xf bank_mask:0xf
	v_mul_f32_dpp v46, v46, v46 row_shr:2 row_mask:0xf bank_mask:0xf
	v_mul_f32_dpp v30, v30, v30 row_shr:4 row_mask:0xf bank_mask:0xf
	v_mul_f32_dpp v5, v5, v5 row_shr:4 row_mask:0xf bank_mask:0xf
	v_mul_f32_dpp v2, v2, v2 row_shr:4 row_mask:0xf bank_mask:0xf
	v_mul_f32_dpp v44, v44, v44 row_shr:4 row_mask:0xf bank_mask:0xf
	v_mul_f32_dpp v14, v14, v14 row_shr:4 row_mask:0xf bank_mask:0xf
	v_mul_f32_dpp v45, v45, v45 row_shr:4 row_mask:0xf bank_mask:0xf
	v_mul_f32_dpp v16, v16, v16 row_shr:4 row_mask:0xf bank_mask:0xf
	v_mul_f32_dpp v46, v46, v46 row_shr:4 row_mask:0xf bank_mask:0xf
	v_mul_f32_dpp v30, v30, v30 row_shr:8 row_mask:0xf bank_mask:0xf
	v_mul_f32_dpp v5, v5, v5 row_shr:8 row_mask:0xf bank_mask:0xf
	v_mul_f32_dpp v2, v2, v2 row_shr:8 row_mask:0xf bank_mask:0xf
	v_mul_f32_dpp v44, v44, v44 row_shr:8 row_mask:0xf bank_mask:0xf
	v_mul_f32_dpp v14, v14, v14 row_shr:8 row_mask:0xf bank_mask:0xf
	v_mul_f32_dpp v45, v45, v45 row_shr:8 row_mask:0xf bank_mask:0xf
	v_mul_f32_dpp v16, v16, v16 row_shr:8 row_mask:0xf bank_mask:0xf
	v_mul_f32_dpp v46, v46, v46 row_shr:8 row_mask:0xf bank_mask:0xf
	v_mul_f32_dpp v30, v30, v30 row_bcast:15 row_mask:0xa bank_mask:0xf
	v_mul_f32_dpp v5, v5, v5 row_bcast:15 row_mask:0xa bank_mask:0xf
	v_mul_f32_dpp v2, v2, v2 row_bcast:15 row_mask:0xa bank_mask:0xf
	v_mul_f32_dpp v44, v44, v44 row_bcast:15 row_mask:0xa bank_mask:0xf
	v_mul_f32_dpp v14, v14, v14 row_bcast:15 row_mask:0xa bank_mask:0xf
	v_mul_f32_dpp v45, v45, v45 row_bcast:15 row_mask:0xa bank_mask:0xf
	v_mul_f32_dpp v16, v16, v16 row_bcast:15 row_mask:0xa bank_mask:0xf
	v_mul_f32_dpp v46, v46, v46 row_bcast:15 row_mask:0xa bank_mask:0xf
	s_nop 1
	s_nop 0
	v_max_f32_e32 v3, v30, v30
	v_max_f32_e32 v3, 0xda24260, v3
	v_rcp_f32_e32 v48, v3
	v_max_f32_e32 v3, v5, v5
	v_max_f32_e32 v3, 0xda24260, v3
	v_rcp_f32_e32 v49, v3
	v_max_f32_e32 v3, v2, v2
	v_mov_b32_e32 v31, v5
	v_max_f32_e32 v3, 0xda24260, v3
	v_mul_f32_e32 v50, v32, v30
	v_mul_f32_e32 v51, v33, v31
	v_rcp_f32_e32 v32, v3
	v_mov_b32_e32 v3, v44
	v_mul_f32_e32 v48, v34, v48
	v_mul_f32_e32 v49, v35, v49
	v_mul_f32_e32 v34, v38, v2
	v_mul_f32_e32 v35, v39, v3
	v_max_f32_e32 v3, v44, v44
	v_max_f32_e32 v3, 0xda24260, v3
	v_rcp_f32_e32 v33, v3
	v_max_f32_e32 v3, v14, v14
	v_max_f32_e32 v3, 0xda24260, v3
	v_mov_b32_e32 v15, v45
	v_mul_f32_e32 v32, v18, v32
	v_mul_f32_e32 v33, v19, v33
	v_rcp_f32_e32 v18, v3
	v_max_f32_e32 v3, v45, v45
	v_max_f32_e32 v3, 0xda24260, v3
	v_rcp_f32_e32 v19, v3
	v_max_f32_e32 v3, v16, v16
	v_max_f32_e32 v3, 0xda24260, v3
	v_mov_b32_e32 v17, v46
	v_mul_f32_e32 v36, v36, v18
	v_mul_f32_e32 v37, v37, v19
	v_rcp_f32_e32 v18, v3
	v_max_f32_e32 v3, v46, v46
	v_max_f32_e32 v3, 0xda24260, v3
	v_rcp_f32_e32 v19, v3
	v_mul_f32_e32 v38, v40, v14
	v_mul_f32_e32 v39, v41, v15
	v_mul_f32_e32 v40, v42, v16
	v_mul_f32_e32 v41, v43, v17
	v_cvt_pk_bf16_f32 v33, v32, v33
	v_mul_f32_e32 v42, v20, v18
	v_mul_f32_e32 v43, v21, v19
	v_cvt_pk_bf16_f32 v19, v34, v35
	v_cvt_pk_bf16_f32 v34, v36, v37
	v_cvt_pk_bf16_f32 v35, v42, v43
	v_cvt_pk_bf16_f32 v32, v48, v49
	v_cvt_pk_bf16_f32 v20, v38, v39
	v_cvt_pk_bf16_f32 v21, v40, v41
	v_cvt_pk_bf16_f32 v18, v50, v51
	ds_write_b16 v101, v32 offset:5120
	ds_write_b16_d16_hi v102, v32 offset:5120
	ds_write_b16 v102, v33 offset:5200
	ds_write_b16_d16_hi v102, v33 offset:5280
	ds_write_b16 v102, v34 offset:5360
	ds_write_b16_d16_hi v102, v34 offset:5440
	ds_write_b16 v102, v35 offset:5520
	ds_write_b16_d16_hi v102, v35 offset:5600
	ds_write_b128 v103, v[18:21]
	ds_write_b128 v104, v[32:35] offset:2560
	s_waitcnt vmcnt(1)
	ds_write_b16 v105, v10 offset:7680
	ds_write_b16_d16_hi v105, v10 offset:7760
	ds_write_b16 v105, v11 offset:7840
	ds_write_b16_d16_hi v105, v11 offset:7920
	ds_write_b16 v105, v12 offset:8000
	ds_write_b16_d16_hi v105, v12 offset:8080
	ds_write_b16 v105, v13 offset:8160
	ds_write_b16_d16_hi v105, v13 offset:8240
	s_waitcnt vmcnt(0)
	ds_write_b16 v105, v6 offset:8320
	ds_write_b16_d16_hi v105, v6 offset:8400
	ds_write_b16 v105, v7 offset:8480
	ds_write_b16_d16_hi v105, v7 offset:8560
	ds_write_b16 v105, v8 offset:8640
	ds_write_b16_d16_hi v105, v8 offset:8720
	ds_write_b16 v105, v9 offset:8800
	ds_write_b16_d16_hi v105, v9 offset:8880
	s_and_saveexec_b64 s[2:3], s[38:39]
	s_cbranch_execz .LBB0_478
	v_add_u32_e32 v3, v65, v64
	v_mov_b32_e32 v31, v5
	v_mov_b32_e32 v32, v2
	v_mov_b32_e32 v33, v44
	v_mov_b32_e32 v15, v45
	v_mov_b32_e32 v17, v46
	ds_write_b128 v3, v[30:33] offset:12800
	ds_write_b128 v106, v[14:17] offset:12800

; #define LAS __attribute__((address_space(3)))
; template <int K>
; __device__ __forceinline__ void s2_gh_unit(LAS unsigned char* U, f32x4 (&S)[K / 16], const int cs, const int lane) {
;     typedef GHL<K> G; constexpr int NS = K / 32, KT = K / 16;
;     const int q = lane >> 4, r16 = lane & 15, c = 16 * cs + r16;
;     const f32x4 z4 = {0.f, 0.f, 0.f, 0.f};
;     const LAS unsigned char* vrow = U + G::OFF_VT + c * 80;
;     bf16x8 kf0[NS], kf1[NS], qf0[NS], qf1[NS], qp0[NS], qp1[NS], ktf[KT]; f32x4 e4[KT];
; #pragma unroll
;     for (int kt = 0; kt < KT; ++kt) { ktf[kt] = frag16(U + G::OFF_KT + (16 * kt + r16) * 80 + (8 * q) * 2); e4[kt] = *(const LAS f32x4*)(U + G::OFF_E + (16 * kt + 4 * q) * 4); }
;     const bf16x8 vn = frag16(vrow + (8 * q) * 2);
; #pragma unroll
;     for (int s = 0; s < NS; ++s) {
;         const LAS unsigned char* qr0 = U + G::OFF_Q + r16 * G::RS + (32 * s + 4 * q) * 2; const LAS unsigned char* qr1 = qr0 + 16 * G::RS;
;         qp0[s] = frag8x2(qr0, qr0 + 32); qp1[s] = frag8x2(qr1, qr1 + 32);
;     }
; #pragma unroll
;     for (int s = 0; s < NS; ++s) {
;         const int kb = (32 * s + 8 * q) * 2;
;         kf0[s] = frag16(U + G::OFF_K + r16 * G::RS + kb); kf1[s] = frag16(U + G::OFF_K + (16 + r16) * G::RS + kb);
;         qf0[s] = frag16(U + G::OFF_Q + r16 * G::RS + kb); qf1[s] = frag16(U + G::OFF_Q + (16 + r16) * G::RS + kb);
;     }
;     const bf16x8 vb = frag8x2(vrow + (4 * q) * 2, vrow + (16 + 4 * q) * 2);
;     bf16x8 sb[NS];
; #pragma unroll
;     for (int s = 0; s < NS; ++s) sb[s] = pack_frag(S[2 * s], S[2 * s + 1]);
; #pragma unroll
;     for (int kt = 0; kt < KT; ++kt) { S[kt] = MFMA16(ktf[kt], vn, S[kt]); S[kt] = S[kt] * e4[kt]; }
;     f32x4 X00 = z4, X01 = z4, X11 = z4;
; #pragma unroll
;     for (int s = 0; s < NS; ++s) { X00 = MFMA16(kf0[s], qf0[s], X00); X01 = MFMA16(kf0[s], qf1[s], X01); X11 = MFMA16(kf1[s], qf1[s], X11); }
;     f32x4 o0 = z4, o1 = z4;
; #pragma unroll
;     for (int s = 0; s < NS; ++s) { o0 = MFMA16(qp0[s], sb[s], o0); o1 = MFMA16(qp1[s], sb[s], o1); }
; #pragma unroll
;     for (int r = 0; r < 4; ++r) if (4 * q + r > r16) { X00[r] = 0.f; X11[r] = 0.f; }
;     const bf16x8 a0 = pack_frag(X00, z4), a1 = pack_frag(X01, X11);
;     o0 = MFMA16(a0, vb, o0); o1 = MFMA16(a1, vb, o1);
;     LAS float* ob = (LAS float*)(U + G::OFF_O);
; #pragma unroll
.LBB0_481:
	v_add_u32_e32 v59, s2, v99
	v_add_u32_e32 v60, s2, v97
	ds_read_b128 v[108:111], v59 offset:5120
	ds_read_b128 v[112:115], v59 offset:6400
	ds_read_b128 v[116:119], v60
	v_cvt_pk_bf16_f32 v54, v50, v51
	v_cvt_pk_bf16_f32 v55, v52, v53
	v_cvt_pk_bf16_f32 v56, v46, v47
	v_cvt_pk_bf16_f32 v57, v48, v49
	s_waitcnt lgkmcnt(0)
	v_mfma_f32_16x16x32_bf16 v[50:53], v[108:111], v[116:119], v[50:53]
	ds_read_b128 v[108:111], v59 offset:2560
	ds_read_b128 v[120:123], v59 offset:3840
	v_add_u32_e32 v61, s2, v100
	v_mov_b32_e32 v2, s63
	v_mfma_f32_16x16x32_bf16 v[46:49], v[112:115], v[116:119], v[46:49]
	ds_read_b128 v[112:115], v59
	ds_read_b128 v[116:119], v59 offset:1280
	ds_read2_b64 v[124:127], v61 offset1:4
	v_add_u32_e32 v3, s2, v98
	s_waitcnt lgkmcnt(2)
	v_mfma_f32_16x16x32_bf16 v[112:115], v[108:111], v[112:115], 0
	v_mov_b32_e32 v58, s63
	v_add_u32_e32 v81, s2, v96
	ds_read2_b64 v[136:139], v61 offset0:160 offset1:164
	ds_read_b128 v[142:145], v3 offset:12800
	ds_read_b128 v[146:149], v3 offset:12864
	s_waitcnt lgkmcnt(4)
	v_mfma_f32_16x16x32_bf16 v[120:123], v[120:123], v[116:119], 0
	s_nop 0
	v_cndmask_b32_e64 v2, v112, v2, s[40:41]
	v_cndmask_b32_e64 v60, 0, v113, s[42:43]
	v_cndmask_b32_e64 v61, v114, 0, s[44:45]
	v_mfma_f32_16x16x32_bf16 v[108:111], v[108:111], v[116:119], 0
	v_cndmask_b32_e64 v115, v115, 0, s[46:47]
	s_nop 1
	v_cndmask_b32_e64 v3, v120, v58, s[40:41]
	v_cndmask_b32_e64 v2, v2, v112, s[42:43]
	v_mov_b32_e32 v5, v4
	ds_read2_b64 v[116:119], v81 offset1:4
	v_cndmask_b32_e64 v113, 0, v121, s[42:43]
	v_cndmask_b32_e64 v114, v122, 0, s[44:45]
	v_cndmask_b32_e64 v121, v123, 0, s[46:47]
	v_cndmask_b32_e64 v112, v3, v120, s[42:43]
	v_cvt_pk_bf16_f32 v3, v61, v115
	v_cvt_pk_bf16_f32 v2, v2, v60
	s_waitcnt lgkmcnt(4)
	v_mfma_f32_16x16x32_bf16 v[124:127], v[124:127], v[54:57], 0
	v_cvt_pk_bf16_f32 v58, v108, v109
	v_cvt_pk_bf16_f32 v59, v110, v111
	v_cvt_pk_bf16_f32 v61, v114, v121
	v_cvt_pk_bf16_f32 v60, v112, v113
	s_waitcnt lgkmcnt(3)
	v_mfma_f32_16x16x32_bf16 v[54:57], v[136:139], v[54:57], 0
	v_add_u32_e32 v83, s2, v94
	v_add_u32_e32 v107, s2, v95
	s_addk_i32 s2, 0x5480
	s_waitcnt lgkmcnt(0)
	v_mfma_f32_16x16x32_bf16 v[108:111], v[2:5], v[116:119], v[124:127]
	s_cmp_eq_u32 s2, 0x15200
	v_mul_f32_e32 v52, v144, v52
	v_mul_f32_e32 v53, v145, v53
	v_mul_f32_e32 v50, v142, v50
	v_mul_f32_e32 v51, v143, v51
	v_mfma_f32_16x16x32_bf16 v[54:57], v[58:61], v[116:119], v[54:57]
	v_mul_f32_e64 v48, v148, v48
	v_mul_f32_e64 v49, v149, v49
	v_mul_f32_e32 v46, v146, v46
	v_mul_f32_e32 v47, v147, v47
	v_add_u32_e32 v81, 0x1000, v83
	ds_write_b32 v83, v108
	s_nop 2
	ds_write_b32 v107, v54
	ds_write2_b32 v83, v109, v110 offset0:68 offset1:136
	ds_write2_b32 v81, v55, v56 offset0:132 offset1:200
	ds_write_b32 v83, v111 offset:816
	ds_write_b32 v83, v57 offset:5168
	s_cbranch_scc0 .LBB0_481

; template <int K>
; __device__ __forceinline__ void s2_gh_unit(LAS unsigned char* U, f32x4 (&S)[K / 16], const int cs, const int lane) {
;     typedef GHL<K> G; constexpr int NS = K / 32, KT = K / 16;
;     const int q = lane >> 4, r16 = lane & 15, c = 16 * cs + r16;
;     const f32x4 z4 = {0.f, 0.f, 0.f, 0.f};
;     const LAS unsigned char* vrow = U + G::OFF_VT + c * 80;
;     bf16x8 kf0[NS], kf1[NS], qf0[NS], qf1[NS], qp0[NS], qp1[NS], ktf[KT]; f32x4 e4[KT];
; #pragma unroll
;     for (int kt = 0; kt < KT; ++kt) { ktf[kt] = frag16(U + G::OFF_KT + (16 * kt + r16) * 80 + (8 * q) * 2); e4[kt] = *(const LAS f32x4*)(U + G::OFF_E + (16 * kt + 4 * q) * 4); }
;     const bf16x8 vn = frag16(vrow + (8 * q) * 2);
; #pragma unroll
;     for (int s = 0; s < NS; ++s) {
;         const LAS unsigned char* qr0 = U + G::OFF_Q + r16 * G::RS + (32 * s + 4 * q) * 2; const LAS unsigned char* qr1 = qr0 + 16 * G::RS;
;         qp0[s] = frag8x2(qr0, qr0 + 32); qp1[s] = frag8x2(qr1, qr1 + 32);
;     }
; #pragma unroll
;     for (int s = 0; s < NS; ++s) {
;         const int kb = (32 * s + 8 * q) * 2;
;         kf0[s] = frag16(U + G::OFF_K + r16 * G::RS + kb); kf1[s] = frag16(U + G::OFF_K + (16 + r16) * G::RS + kb);
;         qf0[s] = frag16(U + G::OFF_Q + r16 * G::RS + kb); qf1[s] = frag16(U + G::OFF_Q + (16 + r16) * G::RS + kb);
;     }
;     const bf16x8 vb = frag8x2(vrow + (4 * q) * 2, vrow + (16 + 4 * q) * 2);
;     bf16x8 sb[NS];
; template <int MT>
; __device__ __forceinline__ void chain_gh(LAS unsigned char* L, const MixP& C, const int h, const int b0, const bool smp, const int tid) {
;     ...
; #pragma unroll 1
;             for (int job = w; job < 16; job += 8) {
;                 const int u = job >> 2, cs = job & 3, q = lane >> 4, c = 16 * cs + (lane & 15);
;                 const size_t sb = ((size_t)(b0 + u) * 4 + h) * K * 64;
; #pragma unroll
;                 for (int kt = 0; kt < KT; ++kt)
; #pragma unroll
;                     for (int r = 0; r < 4; ++r) S[kt][r] = sin[sb + (size_t)(16 * kt + 4 * q + r) * 64 + c];
;                 s2_gh_unit<K>(L + u * G::UNIT, S, cs, lane);
;                 float* so = C.out + o_s + (((size_t)C.l * BS + b0 + u) * 4 + h) * K * 64;
; #pragma unroll
;                 for (int kt = 0; kt < KT; ++kt)
; #pragma unroll
;                     for (int r = 0; r < 4; ++r) so[(size_t)(16 * kt + 4 * q + r) * 64 + c] = S[kt][r];
;             }
.LBB0_485:
	s_ashr_i32 s2, s22, 2
	s_add_i32 s24, s2, s4
	s_ashr_i32 s25, s24, 31
	s_lshl_b64 s[24:25], s[24:25], 15
	v_and_or_b32 v54, s21, 48, v73
	s_add_u32 s24, s15, s24
	s_addc_u32 s25, s16, s25
	v_lshlrev_b32_e32 v2, 2, v54
	v_mov_b32_e32 v3, v4
	v_lshl_add_u64 v[2:3], s[24:25], 0, v[2:3]
	v_lshlrev_b32_e32 v22, 2, v66
	v_mov_b32_e32 v23, v4
	v_lshl_add_u64 v[26:27], v[2:3], 0, v[22:23]
	global_load_dword v22, v[26:27], off
	global_load_dword v23, v[26:27], off offset:256
	global_load_dword v24, v[26:27], off offset:512
	global_load_dword v25, v[26:27], off offset:768
	v_lshlrev_b32_e32 v26, 2, v68
	v_mov_b32_e32 v27, v4
	v_lshlrev_b32_e32 v28, 2, v70
	v_mov_b32_e32 v29, v4
	v_lshl_add_u64 v[26:27], v[2:3], 0, v[26:27]
	v_lshl_add_u64 v[28:29], v[2:3], 0, v[28:29]
	global_load_dword v26, v[26:27], off
	v_lshlrev_b32_e32 v46, 2, v74
	global_load_dword v27, v[28:29], off
	v_lshlrev_b32_e32 v28, 2, v72
	v_mov_b32_e32 v29, v4
	v_mov_b32_e32 v47, v4
	v_lshl_add_u64 v[28:29], v[2:3], 0, v[28:29]
	v_lshl_add_u64 v[2:3], v[2:3], 0, v[46:47]
	global_load_dword v28, v[28:29], off
	s_mul_i32 s3, s2, 0x5480
	global_load_dword v29, v[2:3], off
	s_add_i32 s3, s3, 0
	v_add_u32_e32 v2, s3, v85
	v_add_u32_e32 v3, v2, v86
	ds_read_b128 v[50:53], v3 offset:5120
	ds_read_b128 v[56:59], v2 offset:12800
	ds_read_b128 v[108:111], v3 offset:6400
	ds_read_b128 v[112:115], v2 offset:12864
	v_mov_b32_e32 v2, s3
	v_mad_u32_u24 v55, v54, s64, v2
	v_add_u32_e32 v2, v55, v85
	ds_read_b128 v[116:119], v2 offset:7680
	v_add_u32_e32 v2, s3, v86
	v_add_u32_e32 v5, v2, v87
	v_add_u32_e32 v2, v2, v85
	ds_read2_b64 v[120:123], v5 offset1:4
	ds_read2_b64 v[124:127], v5 offset0:160 offset1:164
	ds_read_b128 v[136:139], v2 offset:2560
	ds_read_b128 v[142:145], v2 offset:3840
	ds_read_b128 v[146:149], v3
	ds_read_b128 v[150:153], v3 offset:1280
	v_add_u32_e32 v2, v55, v87
	v_add_u32_e32 v3, v55, v88
	ds_read_b64 v[46:47], v2 offset:7680
	ds_read_b64 v[48:49], v3 offset:7680
	v_mov_b32_e32 v2, s63
	v_mov_b32_e32 v60, s63
	s_ashr_i32 s3, s2, 31
	s_add_u32 s2, s17, s2
	s_addc_u32 s3, s18, s3
	s_lshl_b64 s[2:3], s[2:3], 15
	s_add_u32 s2, s19, s2
	s_addc_u32 s3, s20, s3
	s_addk_i32 s21, 0x80
	s_waitcnt vmcnt(6)
	v_cvt_pk_bf16_f32 v156, v22, v23
	s_waitcnt vmcnt(4)
	v_cvt_pk_bf16_f32 v157, v24, v25
	s_waitcnt lgkmcnt(8)
	v_mfma_f32_16x16x32_bf16 v[22:25], v[50:53], v[116:119], v[22:25]
	s_waitcnt vmcnt(2)
	v_cvt_pk_bf16_f32 v158, v26, v27
	s_nop 5
	v_mul_f32_e32 v24, v58, v24
	v_mul_f32_e32 v25, v59, v25
	v_mul_f32_e32 v22, v56, v22
	v_mul_f32_e32 v23, v57, v23
	s_waitcnt lgkmcnt(3)
	v_mfma_f32_16x16x32_bf16 v[56:59], v[136:139], v[146:149], 0
	s_waitcnt vmcnt(0)
	v_cvt_pk_bf16_f32 v159, v28, v29
	v_mfma_f32_16x16x32_bf16 v[26:29], v[108:111], v[116:119], v[26:29]
	s_nop 4
	v_cndmask_b32_e64 v2, v56, v2, s[40:41]
	v_cndmask_b32_e64 v2, v2, v56, s[42:43]
	v_cndmask_b32_e64 v5, 0, v57, s[42:43]
	s_waitcnt lgkmcnt(2)
	v_mfma_f32_16x16x32_bf16 v[108:111], v[142:145], v[150:153], 0
	v_cndmask_b32_e64 v83, v59, 0, s[46:47]
	v_cvt_pk_bf16_f32 v2, v2, v5
	v_mov_b32_e32 v5, v4
	v_mfma_f32_16x16x32_bf16 v[50:53], v[120:123], v[156:159], 0
	v_mul_f32_e64 v26, v112, v26
	v_mul_f32_e64 v27, v113, v27
	s_nop 1
	v_cndmask_b32_e64 v3, v108, v60, s[40:41]
	v_cndmask_b32_e64 v60, v3, v108, s[42:43]
	v_cndmask_b32_e64 v3, v58, 0, s[44:45]
	v_mfma_f32_16x16x32_bf16 v[56:59], v[136:139], v[150:153], 0
	v_cndmask_b32_e64 v61, 0, v109, s[42:43]
	v_cndmask_b32_e64 v81, v110, 0, s[44:45]
	v_cndmask_b32_e64 v107, v111, 0, s[46:47]
	v_cvt_pk_bf16_f32 v3, v3, v83
	v_mfma_f32_16x16x32_bf16 v[108:111], v[124:127], v[156:159], 0
	s_nop 2
	v_cvt_pk_bf16_f32 v56, v56, v57
	v_cvt_pk_bf16_f32 v57, v58, v59
	v_cvt_pk_bf16_f32 v58, v60, v61
	v_cvt_pk_bf16_f32 v59, v81, v107
	s_waitcnt lgkmcnt(0)
	v_mfma_f32_16x16x32_bf16 v[50:53], v[2:5], v[46:49], v[50:53]
	v_mad_i32_i24 v2, v54, s97, v55
	v_add_u32_e32 v3, v2, v89
	v_add_u32_e32 v2, v2, v90
	v_mfma_f32_16x16x32_bf16 v[46:49], v[56:59], v[46:49], v[108:111]
	v_mul_f32_e64 v28, v114, v28
	v_mul_f32_e64 v29, v115, v29
	s_nop 1
	ds_write_b32 v3, v50 offset:12928
	s_nop 2
	ds_write_b32 v2, v46 offset:12928
	v_add_u32_e32 v2, 0x3200, v3
	ds_write2_b32 v2, v51, v52 offset0:100 offset1:168
	v_add_u32_e32 v2, 0x4400, v3
	ds_write2_b32 v2, v47, v48 offset0:36 offset1:104
	ds_write_b32 v3, v53 offset:13744
	ds_write_b32 v3, v49 offset:18096
	v_or_b32_e32 v2, v54, v66
	v_lshlrev_b32_e32 v2, 2, v2
	global_store_dword v2, v22, s[2:3]
	v_add_lshl_u32 v2, v54, v66, 2
	global_store_dword v2, v23, s[2:3] offset:256
	global_store_dword v2, v24, s[2:3] offset:512
	global_store_dword v2, v25, s[2:3] offset:768
	v_or_b32_e32 v2, v54, v68
	v_lshlrev_b32_e32 v2, 2, v2
	global_store_dword v2, v26, s[2:3]
	v_or_b32_e32 v2, v54, v70
	v_lshlrev_b32_e32 v2, 2, v2
	global_store_dword v2, v27, s[2:3]
	v_or_b32_e32 v2, v54, v72
	v_lshlrev_b32_e32 v2, 2, v2
	global_store_dword v2, v28, s[2:3]
	v_or_b32_e32 v2, v54, v74
	v_lshlrev_b32_e32 v2, 2, v2
	global_store_dword v2, v29, s[2:3]
	s_add_i32 s2, s22, 8
	s_cmp_gt_i32 s22, 7
	s_mov_b32 s22, s2
	s_cbranch_scc0 .LBB0_485

; #define LAS __attribute__((address_space(3)))
; __device__ __forceinline__ unsigned cvtpk(float lo, float hi) { const f32x2v v = {lo, hi}; return __builtin_bit_cast(unsigned, __builtin_convertvector(v, bf16x2v)); }
; __device__ __forceinline__ float quad_sum(float v) { v += dpp_sel<0xB1, 0xf>(0.f, v); v += dpp_sel<0x4E, 0xf>(0.f, v); return v; }
; template <int MT>
; __device__ __forceinline__ void chain_gh(LAS unsigned char* L, const MixP& C, const int h, const int b0, const bool smp, const int tid) {
;     ...
;             const LAS float* ob = (const LAS float*)(L + u3 * G::UNIT + G::OFF_O) + i3 * 68 + 16 * cq3;
;             f32x4 o[4]; float ss = 0.f;
; #pragma unroll
;             for (int j = 0; j < 4; ++j) { o[j] = *(const LAS f32x4*)(ob + 4 * j); ss += (o[j][0] * o[j][0] + o[j][1] * o[j][1]) + (o[j][2] * o[j][2] + o[j][3] * o[j][3]); }
;             ss = quad_sum(ss);
;             const float r = rsqrtf(ss * (1.0f / 64.0f) + 1e-6f);
;             float res[16], nwv[16];
; #pragma unroll
;             for (int j = 0; j < 4; ++j) { const f32x4 t = *(const LAS f32x4*)(cst + 600 + 16 * cq3 + 4 * j); nwv[4 * j] = t[0]; nwv[4 * j + 1] = t[1]; nwv[4 * j + 2] = t[2]; nwv[4 * j + 3] = t[3]; }
; #pragma unroll
;             for (int e = 0; e < 16; ++e) { const float gv = (e < 8) ? bfe(gg0, e) : bfe(gg1, e - 8); res[e] = o[e >> 2][e & 3] * r * nwv[e] * gv; }
;             if (valid3) {
;                 v4u w0, w1;
;                 w0.x = cvtpk(res[0], res[1]); w0.y = cvtpk(res[2], res[3]); w0.z = cvtpk(res[4], res[5]); w0.w = cvtpk(res[6], res[7]);
;                 w1.x = cvtpk(res[8], res[9]); w1.y = cvtpk(res[10], res[11]); w1.z = cvtpk(res[12], res[13]); w1.w = cvtpk(res[14], res[15]);
;                 bf16* mo = C.mixb + (size_t)row3 * D + ((MT == 0) ? MC_GLA : MC_HGRN) + h * 64 + 16 * cq3;
;                 *(v4u*)mo = w0; *(v4u*)(mo + 8) = w1;
;             }
.LBB0_487:
	s_waitcnt lgkmcnt(0)
	s_barrier
	ds_read_b128 v[22:25], v91 offset:12928
	ds_read_b128 v[26:29], v91 offset:12944
	ds_read_b128 v[54:57], v91 offset:12960
	ds_read_b128 v[58:61], v91 offset:12976
	s_waitcnt lgkmcnt(3)
	v_mul_f32_e32 v2, v24, v24
	v_mul_f32_e32 v3, v25, v25
	v_mul_f32_e32 v108, v22, v22
	v_mul_f32_e32 v109, v23, v23
	s_waitcnt lgkmcnt(0)
	v_mul_f32_e32 v5, v58, v58
	v_pk_mov_b32 v[110:111], v[108:109], v[2:3] op_sel:[1,0]
	v_mov_b32_e32 v109, v3
	v_add_f32_e32 v2, v110, v108
	v_add_f32_e32 v3, v111, v109
	v_mul_f32_e32 v108, v28, v28
	v_mul_f32_e32 v109, v29, v29
	v_mul_f32_e32 v110, v26, v26
	v_mul_f32_e32 v111, v27, v27
	v_mul_f32_e32 v81, v59, v59
	v_pk_mov_b32 v[112:113], v[110:111], v[108:109] op_sel:[1,0]
	v_mov_b32_e32 v111, v109
	v_add_f32_e32 v108, v112, v110
	v_add_f32_e32 v109, v113, v111
	v_pk_add_f32 v[2:3], v[2:3], v[2:3] op_sel:[0,1] op_sel_hi:[1,0]
	v_pk_add_f32 v[108:109], v[108:109], v[108:109] op_sel:[0,1] op_sel_hi:[1,0]
	v_mov_b32_e32 v3, v5
	v_mov_b32_e32 v109, v81
	v_add_f32_e32 v2, v2, v108
	v_add_f32_e32 v3, v3, v109
	v_mul_f32_e32 v108, v55, v55
	v_mul_f32_e32 v110, v57, v57
	v_mul_f32_e32 v83, v60, v60
	v_mul_f32_e32 v107, v61, v61
	v_fma_f32 v109, v55, v55, v108
	v_fma_f32 v108, v54, v54, v108
	v_fma_f32 v111, v57, v57, v110
	v_fma_f32 v110, v56, v56, v110
	v_mov_b32_e32 v109, v83
	v_mov_b32_e32 v111, v107
	v_add_f32_e32 v108, v108, v110
	v_add_f32_e32 v109, v109, v111
	s_nop 0
	v_add_f32_e32 v2, v2, v108
	v_add_f32_e32 v3, v3, v109
	s_nop 0
	v_add_f32_e32 v2, v2, v3
	v_mov_b32_e32 v3, v4
	s_nop 0
	v_add_f32_dpp v2, v2, v2 quad_perm:[1,0,3,2] row_mask:0xf bank_mask:0xf bound_ctrl:1
	s_nop 1
	v_mov_b32_dpp v3, v2 quad_perm:[2,3,0,1] row_mask:0xf bank_mask:0xf
	s_and_saveexec_b64 s[2:3], s[48:49]
	s_cbranch_execz .LBB0_489
	v_add_f32_e32 v2, v2, v3
	v_fmamk_f32 v2, v2, 0x3c800000, v231
	s_mov_b32 s21, 0x800000
	v_mul_f32_e32 v3, 0x4b800000, v2
	v_cmp_gt_f32_e32 vcc, s21, v2
	ds_read_b128 v[108:111], v92 offset:32
	ds_read_b128 v[112:115], v92 offset:48
	ds_read_b128 v[116:119], v92
	ds_read_b128 v[120:123], v92 offset:16
	v_cndmask_b32_e32 v2, v2, v3, vcc
	v_rsq_f32_e32 v2, v2
	v_ashrrev_i32_e32 v83, 31, v82
	v_mul_f32_e32 v3, 0x45800000, v2
	v_cndmask_b32_e32 v2, v2, v3, vcc
	v_mul_f32_e32 v58, v58, v2
	v_mul_f32_e32 v59, v59, v2
	v_mul_f32_e32 v60, v60, v2
	v_mul_f32_e32 v61, v61, v2
	s_waitcnt lgkmcnt(2)
	v_mul_f32_e32 v58, v112, v58
	v_mul_f32_e32 v59, v113, v59
	s_waitcnt vmcnt(7)
	v_lshlrev_b32_e32 v112, 16, v44
	v_and_b32_e32 v113, 0xffff0000, v44
	v_mul_f32_e32 v56, v56, v2
	v_mul_f32_e32 v57, v57, v2
	v_mul_f32_e32 v60, v114, v60
	v_mul_f32_e32 v61, v115, v61
	v_lshlrev_b32_e32 v114, 16, v45
	v_and_b32_e32 v115, 0xffff0000, v45
	v_mul_f32_e32 v44, v58, v112
	v_mul_f32_e32 v45, v59, v113
	v_mul_f32_e32 v56, v110, v56
	v_mul_f32_e32 v57, v111, v57
	v_lshlrev_b32_e32 v58, 16, v43
	v_and_b32_e32 v59, 0xffff0000, v43
	v_mul_f32_e32 v54, v54, v2
	v_mul_f32_e32 v55, v55, v2
	v_mul_f32_e32 v56, v56, v58
	v_mul_f32_e32 v57, v57, v59
	v_mul_f32_e32 v54, v108, v54
	v_mul_f32_e32 v55, v109, v55
	v_lshlrev_b32_e32 v58, 16, v42
	v_and_b32_e32 v59, 0xffff0000, v42
	v_mul_f32_e32 v28, v28, v2
	v_mul_f32_e32 v29, v29, v2
	v_mul_f32_e32 v42, v54, v58
	v_mul_f32_e32 v43, v55, v59
	s_waitcnt lgkmcnt(0)
	v_mul_f32_e32 v28, v122, v28
	v_mul_f32_e32 v29, v123, v29
	s_waitcnt vmcnt(6)
	v_lshlrev_b32_e32 v54, 16, v41
	v_and_b32_e32 v55, 0xffff0000, v41
	v_mul_f32_e32 v26, v26, v2
	v_mul_f32_e32 v27, v27, v2
	v_mul_f32_e32 v24, v24, v2
	v_mul_f32_e32 v25, v25, v2
	v_mul_f32_e32 v3, v23, v2
	v_mul_f32_e32 v2, v22, v2
	v_mul_f32_e32 v28, v28, v54
	v_mul_f32_e32 v29, v29, v55
	v_mul_f32_e32 v26, v120, v26
	v_mul_f32_e32 v27, v121, v27
	v_lshlrev_b32_e32 v54, 16, v40
	v_and_b32_e32 v55, 0xffff0000, v40
	v_mul_f32_e32 v24, v118, v24
	v_mul_f32_e32 v25, v119, v25
	v_lshlrev_b32_e32 v40, 16, v39
	v_and_b32_e32 v41, 0xffff0000, v39
	v_mul_f32_e32 v2, v116, v2
	v_mul_f32_e32 v3, v117, v3
	v_lshlrev_b32_e32 v22, 16, v38
	v_and_b32_e32 v23, 0xffff0000, v38
	v_mul_f32_e32 v26, v26, v54
	v_mul_f32_e32 v27, v27, v55
	v_mul_f32_e32 v24, v24, v40
	v_mul_f32_e32 v25, v25, v41
	v_mul_f32_e32 v2, v2, v22
	v_mul_f32_e32 v3, v3, v23
	v_lshlrev_b64 v[38:39], 11, v[82:83]
	v_mul_f32_e32 v60, v60, v114
	v_mul_f32_e32 v61, v61, v115
	v_cvt_pk_bf16_f32 v22, v2, v3
	v_cvt_pk_bf16_f32 v23, v24, v25
	v_cvt_pk_bf16_f32 v24, v26, v27
	v_cvt_pk_bf16_f32 v25, v28, v29
	v_lshl_add_u64 v[2:3], v[78:79], 0, v[38:39]
	v_cvt_pk_bf16_f32 v26, v42, v43
	v_cvt_pk_bf16_f32 v27, v56, v57
	v_cvt_pk_bf16_f32 v28, v44, v45
	v_cvt_pk_bf16_f32 v29, v60, v61
	global_store_dwordx4 v[2:3], v[22:25], off offset:512
	global_store_dwordx4 v[2:3], v[26:29], off offset:528

; __device__ __forceinline__ float sigmoid_f(float x) { return __builtin_amdgcn_rcpf(1.0f + __expf(-x)); }
; template <int MT>
; __device__ __forceinline__ void chain_gh(LAS unsigned char* L, const MixP& C, const int h, const int b0, const bool smp, const int tid) {
;     ...
;                 const v4u rq0 = rw0, rq1 = rw1, rf0 = rw2, rf1 = rw3;
; #pragma unroll
;                 for (int e = 0; e < NK; ++e) { const float z = (e < 8) ? bfe(rf0, e) : bfe(rf1, e - 8), qv = (e < 8) ? bfe(rq0, e) : bfe(rq1, e - 8);
;                     const float lb = cst[16 * kg + e], sg = sigmoid_f(z);
;                     f[e] = lb + (1.f - lb) * sg; kk[e] = (1.f - lb) * (1.f - sg); qq[e] = qv; }
;             }
;             if (!valid) {
; #pragma unroll
;                 for (int e = 0; e < NK; ++e) { f[e] = 1.f; kk[e] = 0.f; qq[e] = 0.f; }
;                 vraw0 = (v4u){0u, 0u, 0u, 0u}; vraw1 = vraw0;
;             }
.LBB0_506:
	s_waitcnt vmcnt(2)
	v_lshlrev_b32_e32 v2, 16, v26
	v_mul_f32_e32 v2, 0xbfb8aa3b, v2
	v_and_b32_e32 v3, 0xffff0000, v26
	v_exp_f32_e32 v2, v2
	v_mul_f32_e32 v3, 0xbfb8aa3b, v3
	v_exp_f32_e32 v3, v3
	ds_read_b128 v[62:65], v89
	v_add_f32_e32 v2, 1.0, v2
	v_rcp_f32_e32 v32, v2
	v_add_f32_e32 v2, 1.0, v3
	v_lshlrev_b32_e32 v5, 16, v27
	v_rcp_f32_e32 v33, v2
	v_mul_f32_e32 v5, 0xbfb8aa3b, v5
	v_exp_f32_e32 v5, v5
	s_waitcnt lgkmcnt(0)
	v_pk_add_f32 v[50:51], v[62:63], 1.0 op_sel_hi:[1,0] neg_lo:[1,0] neg_hi:[1,0]
	v_pk_add_f32 v[2:3], v[32:33], 1.0 op_sel_hi:[1,0] neg_lo:[1,0] neg_hi:[1,0]
	v_lshlrev_b32_e32 v38, 16, v24
	v_mul_f32_e32 v30, v2, v50
	v_mul_f32_e32 v31, v3, v51
	v_add_f32_e32 v2, 1.0, v5
	v_lshlrev_b32_e32 v5, 16, v28
	v_mul_f32_e32 v5, 0xbfb8aa3b, v5
	v_and_b32_e32 v28, 0xffff0000, v28
	v_exp_f32_e32 v5, v5
	v_mul_f32_e32 v28, 0xbfb8aa3b, v28
	v_exp_f32_e32 v28, v28
	v_and_b32_e32 v39, 0xffff0000, v24
	v_add_f32_e32 v5, 1.0, v5
	v_rcp_f32_e32 v60, v5
	v_add_f32_e32 v5, 1.0, v28
	v_rcp_f32_e32 v61, v5
	v_lshlrev_b32_e32 v5, 16, v29
	v_mul_f32_e32 v5, 0xbfb8aa3b, v5
	v_and_b32_e32 v24, 0xffff0000, v29
	v_exp_f32_e32 v5, v5
	v_mul_f32_e32 v24, 0xbfb8aa3b, v24
	v_exp_f32_e32 v24, v24
	v_lshlrev_b32_e32 v52, 16, v14
	v_add_f32_e32 v5, 1.0, v5
	v_rcp_f32_e32 v156, v5
	v_add_f32_e32 v5, 1.0, v24
	v_rcp_f32_e32 v157, v5
	v_lshlrev_b32_e32 v5, 16, v18
	v_mul_f32_e32 v5, 0xbfb8aa3b, v5
	v_and_b32_e32 v18, 0xffff0000, v18
	v_exp_f32_e32 v5, v5
	v_mul_f32_e32 v18, 0xbfb8aa3b, v18
	v_exp_f32_e32 v18, v18
	v_and_b32_e32 v53, 0xffff0000, v14
	v_add_f32_e32 v5, 1.0, v5
	v_rcp_f32_e32 v158, v5
	v_add_f32_e32 v5, 1.0, v18
	v_rcp_f32_e32 v159, v5
	v_lshlrev_b32_e32 v5, 16, v19
	v_mul_f32_e32 v5, 0xbfb8aa3b, v5
	v_and_b32_e32 v14, 0xffff0000, v19
	v_exp_f32_e32 v5, v5
	v_mul_f32_e32 v14, 0xbfb8aa3b, v14
	v_exp_f32_e32 v14, v14
	v_and_b32_e32 v18, 0xffff0000, v20
	v_add_f32_e32 v5, 1.0, v5
	v_rcp_f32_e32 v162, v5
	v_add_f32_e32 v5, 1.0, v14
	v_rcp_f32_e32 v163, v5
	v_lshlrev_b32_e32 v5, 16, v20
	v_mul_f32_e32 v5, 0xbfb8aa3b, v5
	v_exp_f32_e32 v5, v5
	v_mul_f32_e32 v18, 0xbfb8aa3b, v18
	v_exp_f32_e32 v18, v18
	v_lshlrev_b32_e32 v36, 16, v22
	v_add_f32_e32 v5, 1.0, v5
	v_rcp_f32_e32 v166, v5
	v_add_f32_e32 v5, 1.0, v18
	v_rcp_f32_e32 v167, v5
	v_lshlrev_b32_e32 v5, 16, v21
	v_and_b32_e32 v37, 0xffff0000, v22
	v_and_b32_e32 v22, 0xffff0000, v27
	v_lshlrev_b32_e32 v44, 16, v16
	v_and_b32_e32 v45, 0xffff0000, v16
	v_mul_f32_e32 v5, 0xbfb8aa3b, v5
	v_and_b32_e32 v16, 0xffff0000, v21
	v_mul_f32_e32 v22, 0xbfb8aa3b, v22
	v_exp_f32_e32 v5, v5
	v_mul_f32_e32 v16, 0xbfb8aa3b, v16
	v_exp_f32_e32 v22, v22
	v_exp_f32_e32 v16, v16
	v_add_f32_e32 v5, 1.0, v5
	ds_read_b128 v[66:69], v89 offset:16
	ds_read_b128 v[70:73], v89 offset:32
	ds_read_b128 v[74:77], v89 offset:48
	v_rcp_f32_e32 v26, v2
	v_add_f32_e32 v2, 1.0, v22
	v_rcp_f32_e32 v170, v5
	v_add_f32_e32 v5, 1.0, v16
	v_rcp_f32_e32 v27, v2
	v_rcp_f32_e32 v171, v5
	s_waitcnt lgkmcnt(2)
	v_pk_add_f32 v[128:129], v[66:67], 1.0 op_sel_hi:[1,0] neg_lo:[1,0] neg_hi:[1,0]
	v_pk_add_f32 v[34:35], v[60:61], 1.0 op_sel_hi:[1,0] neg_lo:[1,0] neg_hi:[1,0]
	s_waitcnt lgkmcnt(1)
	v_pk_add_f32 v[160:161], v[70:71], 1.0 op_sel_hi:[1,0] neg_lo:[1,0] neg_hi:[1,0]
	v_mul_f32_e32 v40, v34, v128
	v_mul_f32_e32 v41, v35, v129
	v_pk_add_f32 v[34:35], v[158:159], 1.0 op_sel_hi:[1,0] neg_lo:[1,0] neg_hi:[1,0]
	v_lshlrev_b32_e32 v58, 16, v15
	v_and_b32_e32 v59, 0xffff0000, v15
	v_pk_add_f32 v[164:165], v[72:73], 1.0 op_sel_hi:[1,0] neg_lo:[1,0] neg_hi:[1,0]
	v_pk_add_f32 v[14:15], v[162:163], 1.0 op_sel_hi:[1,0] neg_lo:[1,0] neg_hi:[1,0]
	v_lshlrev_b32_e32 v56, 16, v23
	v_and_b32_e32 v57, 0xffff0000, v23
	v_pk_add_f32 v[22:23], v[64:65], 1.0 op_sel_hi:[1,0] neg_lo:[1,0] neg_hi:[1,0]
	v_pk_add_f32 v[2:3], v[26:27], 1.0 op_sel_hi:[1,0] neg_lo:[1,0] neg_hi:[1,0]
	v_lshlrev_b32_e32 v48, 16, v25
	v_and_b32_e32 v49, 0xffff0000, v25
	v_pk_add_f32 v[24:25], v[68:69], 1.0 op_sel_hi:[1,0] neg_lo:[1,0] neg_hi:[1,0]
	v_pk_add_f32 v[28:29], v[156:157], 1.0 op_sel_hi:[1,0] neg_lo:[1,0] neg_hi:[1,0]
	v_mul_f32_e32 v42, v34, v160
	v_mul_f32_e32 v43, v35, v161
	v_mul_f32_e32 v34, v14, v164
	v_mul_f32_e32 v35, v15, v165
	s_waitcnt lgkmcnt(0)
	v_pk_add_f32 v[168:169], v[74:75], 1.0 op_sel_hi:[1,0] neg_lo:[1,0] neg_hi:[1,0]
	v_pk_add_f32 v[14:15], v[166:167], 1.0 op_sel_hi:[1,0] neg_lo:[1,0] neg_hi:[1,0]
	v_lshlrev_b32_e32 v54, 16, v17
	v_and_b32_e32 v55, 0xffff0000, v17
	v_pk_add_f32 v[16:17], v[76:77], 1.0 op_sel_hi:[1,0] neg_lo:[1,0] neg_hi:[1,0]
	v_pk_add_f32 v[172:173], v[170:171], 1.0 op_sel_hi:[1,0] neg_lo:[1,0] neg_hi:[1,0]
	v_mul_f32_e32 v2, v2, v22
	v_mul_f32_e32 v3, v3, v23
	v_mul_f32_e32 v28, v28, v24
	v_mul_f32_e32 v29, v29, v25
	v_mul_f32_e32 v46, v14, v168
	v_mul_f32_e32 v47, v15, v169
	v_fma_f32 v62, v32, v50, v62
	v_fma_f32 v63, v33, v51, v63
	v_fma_f32 v18, v26, v22, v64
	v_fma_f32 v19, v27, v23, v65
	v_fma_f32 v14, v60, v128, v66
	v_fma_f32 v15, v61, v129, v67
	v_fma_f32 v24, v156, v24, v68
	v_fma_f32 v25, v157, v25, v69
	v_fma_f32 v26, v158, v160, v70
	v_fma_f32 v27, v159, v161, v71
	v_fma_f32 v20, v162, v164, v72
	v_fma_f32 v21, v163, v165, v73
	v_fma_f32 v50, v166, v168, v74
	v_fma_f32 v51, v167, v169, v75
	v_fma_f32 v22, v170, v16, v76
	v_fma_f32 v23, v171, v17, v77
	v_mul_f32_e32 v32, v172, v16
	v_mul_f32_e32 v33, v173, v17
	s_and_saveexec_b64 s[2:3], s[0:1]
	s_cbranch_execz .LBB0_508
	v_mov_b32_e32 v5, v4
	v_mov_b32_e32 v2, v4
	v_mov_b32_e32 v3, v4
	v_mov_b32_e32 v30, 0
	v_mov_b32_e32 v62, 1.0
	s_waitcnt vmcnt(0)
	v_mov_b64_e32 v[8:9], v[4:5]
	v_mov_b64_e32 v[12:13], v[4:5]
	v_mov_b64_e32 v[6:7], v[2:3]
	v_mov_b64_e32 v[10:11], v[2:3]
	v_mov_b32_e32 v63, v62
	v_mov_b32_e32 v18, v62
	v_mov_b32_e32 v19, v62
	v_mov_b32_e32 v14, v62
	v_mov_b32_e32 v15, v62
	v_mov_b32_e32 v24, v62
	v_mov_b32_e32 v25, v62
	v_mov_b32_e32 v26, v62
	v_mov_b32_e32 v27, v62
	v_mov_b32_e32 v20, v62
	v_mov_b32_e32 v21, v62
	v_mov_b32_e32 v50, v62
	v_mov_b32_e32 v51, v62
	v_mov_b32_e32 v22, v62
	v_mov_b32_e32 v23, v62
	v_mov_b32_e32 v31, v30
	v_mov_b32_e32 v2, v30
	v_mov_b32_e32 v3, v30
	v_mov_b32_e32 v40, v30
	v_mov_b32_e32 v41, v30
	v_mov_b32_e32 v28, v30
	v_mov_b32_e32 v29, v30
	v_mov_b32_e32 v42, v30
	v_mov_b32_e32 v43, v30
	v_mov_b32_e32 v34, v30
	v_mov_b32_e32 v35, v30
	v_mov_b32_e32 v46, v30
	v_mov_b32_e32 v47, v30
	v_mov_b32_e32 v32, v30
	v_mov_b32_e32 v33, v30
	v_mov_b32_e32 v48, v30
	v_mov_b32_e32 v49, v30
	v_mov_b32_e32 v38, v30
	v_mov_b32_e32 v39, v30
	v_mov_b32_e32 v56, v30
	v_mov_b32_e32 v57, v30
	v_mov_b32_e32 v36, v30
	v_mov_b32_e32 v37, v30
	v_mov_b32_e32 v54, v30
	v_mov_b32_e32 v55, v30
	v_mov_b32_e32 v44, v30
	v_mov_b32_e32 v45, v30
	v_mov_b32_e32 v58, v30
	v_mov_b32_e32 v59, v30
	v_mov_b32_e32 v52, v30
	v_mov_b32_e32 v53, v30
; template <int MT>
; __device__ __forceinline__ void chain_gh(LAS unsigned char* L, const MixP& C, const int h, const int b0, const bool smp, const int tid) {
;     ...
; #pragma unroll
;             for (int e8 = 0; e8 < NK; e8 += 8) gh_scan8(f[e8 + 0], f[e8 + 1], f[e8 + 2], f[e8 + 3], f[e8 + 4], f[e8 + 5], f[e8 + 6], f[e8 + 7]);
;             float qt[NK], kt_[NK];
; #pragma unroll
;             for (int e = 0; e < NK; ++e) { qt[e] = qq[e] * f[e]; kt_[e] = kk[e] * __builtin_amdgcn_rcpf(fmaxf(f[e], 1e-30f)); }
.LBB0_508:
	s_or_b64 exec, exec, s[2:3]
	v_mov_b32_e32 v60, v24
	v_mov_b32_e32 v5, v19
	v_mov_b32_e32 v61, v15
	v_mov_b32_e32 v16, v62
	s_nop 1
	v_mul_f32_dpp v16, v16, v16 row_shr:1 row_mask:0xf bank_mask:0xf
	v_mul_f32_dpp v63, v63, v63 row_shr:1 row_mask:0xf bank_mask:0xf
	v_mul_f32_dpp v18, v18, v18 row_shr:1 row_mask:0xf bank_mask:0xf
	v_mul_f32_dpp v5, v5, v5 row_shr:1 row_mask:0xf bank_mask:0xf
	v_mul_f32_dpp v14, v14, v14 row_shr:1 row_mask:0xf bank_mask:0xf
	v_mul_f32_dpp v61, v61, v61 row_shr:1 row_mask:0xf bank_mask:0xf
	v_mul_f32_dpp v60, v60, v60 row_shr:1 row_mask:0xf bank_mask:0xf
	v_mul_f32_dpp v25, v25, v25 row_shr:1 row_mask:0xf bank_mask:0xf
	v_mul_f32_dpp v16, v16, v16 row_shr:2 row_mask:0xf bank_mask:0xf
	v_mul_f32_dpp v63, v63, v63 row_shr:2 row_mask:0xf bank_mask:0xf
	v_mul_f32_dpp v18, v18, v18 row_shr:2 row_mask:0xf bank_mask:0xf
	v_mul_f32_dpp v5, v5, v5 row_shr:2 row_mask:0xf bank_mask:0xf
	v_mul_f32_dpp v14, v14, v14 row_shr:2 row_mask:0xf bank_mask:0xf
	v_mul_f32_dpp v61, v61, v61 row_shr:2 row_mask:0xf bank_mask:0xf
	v_mul_f32_dpp v60, v60, v60 row_shr:2 row_mask:0xf bank_mask:0xf
	v_mul_f32_dpp v25, v25, v25 row_shr:2 row_mask:0xf bank_mask:0xf
	v_mul_f32_dpp v16, v16, v16 row_shr:4 row_mask:0xf bank_mask:0xf
	v_mul_f32_dpp v63, v63, v63 row_shr:4 row_mask:0xf bank_mask:0xf
	v_mul_f32_dpp v18, v18, v18 row_shr:4 row_mask:0xf bank_mask:0xf
	v_mul_f32_dpp v5, v5, v5 row_shr:4 row_mask:0xf bank_mask:0xf
	v_mul_f32_dpp v14, v14, v14 row_shr:4 row_mask:0xf bank_mask:0xf
	v_mul_f32_dpp v61, v61, v61 row_shr:4 row_mask:0xf bank_mask:0xf
	v_mul_f32_dpp v60, v60, v60 row_shr:4 row_mask:0xf bank_mask:0xf
	v_mul_f32_dpp v25, v25, v25 row_shr:4 row_mask:0xf bank_mask:0xf
	v_mul_f32_dpp v16, v16, v16 row_shr:8 row_mask:0xf bank_mask:0xf
	v_mul_f32_dpp v63, v63, v63 row_shr:8 row_mask:0xf bank_mask:0xf
	v_mul_f32_dpp v18, v18, v18 row_shr:8 row_mask:0xf bank_mask:0xf
	v_mul_f32_dpp v5, v5, v5 row_shr:8 row_mask:0xf bank_mask:0xf
	v_mul_f32_dpp v14, v14, v14 row_shr:8 row_mask:0xf bank_mask:0xf
	v_mul_f32_dpp v61, v61, v61 row_shr:8 row_mask:0xf bank_mask:0xf
	v_mul_f32_dpp v60, v60, v60 row_shr:8 row_mask:0xf bank_mask:0xf
	v_mul_f32_dpp v25, v25, v25 row_shr:8 row_mask:0xf bank_mask:0xf
	v_mul_f32_dpp v16, v16, v16 row_bcast:15 row_mask:0xa bank_mask:0xf
	v_mul_f32_dpp v63, v63, v63 row_bcast:15 row_mask:0xa bank_mask:0xf
	v_mul_f32_dpp v18, v18, v18 row_bcast:15 row_mask:0xa bank_mask:0xf
	v_mul_f32_dpp v5, v5, v5 row_bcast:15 row_mask:0xa bank_mask:0xf
	v_mul_f32_dpp v14, v14, v14 row_bcast:15 row_mask:0xa bank_mask:0xf
	v_mul_f32_dpp v61, v61, v61 row_bcast:15 row_mask:0xa bank_mask:0xf
	v_mul_f32_dpp v60, v60, v60 row_bcast:15 row_mask:0xa bank_mask:0xf
	v_mul_f32_dpp v25, v25, v25 row_bcast:15 row_mask:0xa bank_mask:0xf
	s_nop 1
	v_mov_b32_e32 v24, v26
	v_max_f32_e32 v15, v16, v16
	v_max_f32_e32 v15, 0xda24260, v15
	v_rcp_f32_e32 v62, v15
	v_max_f32_e32 v15, v63, v63
	v_max_f32_e32 v15, 0xda24260, v15
	v_mov_b32_e32 v17, v63
	v_rcp_f32_e32 v63, v15
	v_max_f32_e32 v15, v18, v18
	v_mov_b32_e32 v19, v5
	v_max_f32_e32 v5, v5, v5
	v_max_f32_e32 v15, 0xda24260, v15
	v_max_f32_e32 v5, 0xda24260, v5
	v_mul_f32_e32 v62, v30, v62
	v_mul_f32_e32 v63, v31, v63
	v_rcp_f32_e32 v30, v15
	v_rcp_f32_e32 v31, v5
	v_max_f32_e32 v5, v14, v14
	v_max_f32_e32 v5, 0xda24260, v5
	v_mov_b32_e32 v68, v23
	v_mul_f32_e32 v2, v2, v30
	v_mul_f32_e32 v3, v3, v31
	v_rcp_f32_e32 v30, v5
	v_max_f32_e32 v5, v61, v61
	v_max_f32_e32 v5, 0xda24260, v5
	v_rcp_f32_e32 v31, v5
	v_max_f32_e32 v5, v60, v60
	v_max_f32_e32 v5, 0xda24260, v5
	v_mov_b32_e32 v26, v20
	v_mul_f32_e32 v40, v40, v30
	v_mul_f32_e32 v41, v41, v31
	v_rcp_f32_e32 v30, v5
	v_max_f32_e32 v5, v25, v25
	v_max_f32_e32 v5, 0xda24260, v5
	v_rcp_f32_e32 v31, v5
	v_mov_b32_e32 v20, v50
	s_nop 1
	v_mul_f32_dpp v24, v24, v24 row_shr:1 row_mask:0xf bank_mask:0xf
	v_mul_f32_dpp v27, v27, v27 row_shr:1 row_mask:0xf bank_mask:0xf
	v_mul_f32_dpp v26, v26, v26 row_shr:1 row_mask:0xf bank_mask:0xf
	v_mul_f32_dpp v21, v21, v21 row_shr:1 row_mask:0xf bank_mask:0xf
	v_mul_f32_dpp v20, v20, v20 row_shr:1 row_mask:0xf bank_mask:0xf
	v_mul_f32_dpp v51, v51, v51 row_shr:1 row_mask:0xf bank_mask:0xf
	v_mul_f32_dpp v22, v22, v22 row_shr:1 row_mask:0xf bank_mask:0xf
	v_mul_f32_dpp v68, v68, v68 row_shr:1 row_mask:0xf bank_mask:0xf
	v_mul_f32_dpp v24, v24, v24 row_shr:2 row_mask:0xf bank_mask:0xf
	v_mul_f32_dpp v27, v27, v27 row_shr:2 row_mask:0xf bank_mask:0xf
	v_mul_f32_dpp v26, v26, v26 row_shr:2 row_mask:0xf bank_mask:0xf
	v_mul_f32_dpp v21, v21, v21 row_shr:2 row_mask:0xf bank_mask:0xf
	v_mul_f32_dpp v20, v20, v20 row_shr:2 row_mask:0xf bank_mask:0xf
	v_mul_f32_dpp v51, v51, v51 row_shr:2 row_mask:0xf bank_mask:0xf
	v_mul_f32_dpp v22, v22, v22 row_shr:2 row_mask:0xf bank_mask:0xf
	v_mul_f32_dpp v68, v68, v68 row_shr:2 row_mask:0xf bank_mask:0xf
	v_mul_f32_dpp v24, v24, v24 row_shr:4 row_mask:0xf bank_mask:0xf
	v_mul_f32_dpp v27, v27, v27 row_shr:4 row_mask:0xf bank_mask:0xf
	v_mul_f32_dpp v26, v26, v26 row_shr:4 row_mask:0xf bank_mask:0xf
	v_mul_f32_dpp v21, v21, v21 row_shr:4 row_mask:0xf bank_mask:0xf
	v_mul_f32_dpp v20, v20, v20 row_shr:4 row_mask:0xf bank_mask:0xf
; #define LAS __attribute__((address_space(3)))
; __device__ __forceinline__ unsigned cvtpk(float lo, float hi) { const f32x2v v = {lo, hi}; return __builtin_bit_cast(unsigned, __builtin_convertvector(v, bf16x2v)); }
; __device__ __forceinline__ unsigned short bfbits(const v4u w, const int e) { const unsigned x = w[e >> 1]; return (unsigned short)((e & 1) ? (x >> 16) : (x & 0xffffu)); }
; template <int MT>
; __device__ __forceinline__ void chain_gh(LAS unsigned char* L, const MixP& C, const int h, const int b0, const bool smp, const int tid) {
;     ...
; #pragma unroll
;             for (int e8 = 0; e8 < NK; e8 += 8) gh_scan8(f[e8 + 0], f[e8 + 1], f[e8 + 2], f[e8 + 3], f[e8 + 4], f[e8 + 5], f[e8 + 6], f[e8 + 7]);
;             float qt[NK], kt_[NK];
; #pragma unroll
;             for (int e = 0; e < NK; ++e) { qt[e] = qq[e] * f[e]; kt_[e] = kk[e] * __builtin_amdgcn_rcpf(fmaxf(f[e], 1e-30f)); }
; #pragma unroll
;             for (int e8 = 0; e8 < NK; e8 += 8) {
;                 v4u wq, wk;
;                 wq.x = cvtpk(qt[e8 + 0], qt[e8 + 1]); wq.y = cvtpk(qt[e8 + 2], qt[e8 + 3]); wq.z = cvtpk(qt[e8 + 4], qt[e8 + 5]); wq.w = cvtpk(qt[e8 + 6], qt[e8 + 7]);
;                 wk.x = cvtpk(kt_[e8 + 0], kt_[e8 + 1]); wk.y = cvtpk(kt_[e8 + 2], kt_[e8 + 3]); wk.z = cvtpk(kt_[e8 + 4], kt_[e8 + 5]); wk.w = cvtpk(kt_[e8 + 6], kt_[e8 + 7]);
;                 *(LAS v4u*)(U + G::OFF_Q + t1 * G::RS + (NK * kg + e8) * 2) = wq;
;                 *(LAS v4u*)(U + G::OFF_K + t1 * G::RS + (NK * kg + e8) * 2) = wk;
; #pragma unroll
;                 for (int e = 0; e < 8; ++e) *(LAS unsigned short*)(U + G::OFF_KT + (NK * kg + e8 + e) * 80 + t1 * 2) = bfbits(wk, e);
;             }
; #pragma unroll
;             for (int e = 0; e < 16; ++e) *(LAS unsigned short*)(U + G::OFF_VT + (16 * kg + e) * 80 + t1 * 2) = (e < 8) ? bfbits(vraw0, e) : bfbits(vraw1, e - 8);
;             if (t1 == 31) {
; #pragma unroll
;                 for (int e = 0; e < NK; ++e) *(LAS float*)(U + G::OFF_E + (NK * kg + e) * 4) = f[e];
;             }
	v_mul_f32_dpp v51, v51, v51 row_shr:4 row_mask:0xf bank_mask:0xf
	v_mul_f32_dpp v22, v22, v22 row_shr:4 row_mask:0xf bank_mask:0xf
	v_mul_f32_dpp v68, v68, v68 row_shr:4 row_mask:0xf bank_mask:0xf
	v_mul_f32_dpp v24, v24, v24 row_shr:8 row_mask:0xf bank_mask:0xf
	v_mul_f32_dpp v27, v27, v27 row_shr:8 row_mask:0xf bank_mask:0xf
	v_mul_f32_dpp v26, v26, v26 row_shr:8 row_mask:0xf bank_mask:0xf
	v_mul_f32_dpp v21, v21, v21 row_shr:8 row_mask:0xf bank_mask:0xf
	v_mul_f32_dpp v20, v20, v20 row_shr:8 row_mask:0xf bank_mask:0xf
	v_mul_f32_dpp v51, v51, v51 row_shr:8 row_mask:0xf bank_mask:0xf
	v_mul_f32_dpp v22, v22, v22 row_shr:8 row_mask:0xf bank_mask:0xf
	v_mul_f32_dpp v68, v68, v68 row_shr:8 row_mask:0xf bank_mask:0xf
	v_mul_f32_dpp v24, v24, v24 row_bcast:15 row_mask:0xa bank_mask:0xf
	v_mul_f32_dpp v27, v27, v27 row_bcast:15 row_mask:0xa bank_mask:0xf
	v_mul_f32_dpp v26, v26, v26 row_bcast:15 row_mask:0xa bank_mask:0xf
	v_mul_f32_dpp v21, v21, v21 row_bcast:15 row_mask:0xa bank_mask:0xf
	v_mul_f32_dpp v20, v20, v20 row_bcast:15 row_mask:0xa bank_mask:0xf
	v_mul_f32_dpp v51, v51, v51 row_bcast:15 row_mask:0xa bank_mask:0xf
	v_mul_f32_dpp v22, v22, v22 row_bcast:15 row_mask:0xa bank_mask:0xf
	v_mul_f32_dpp v68, v68, v68 row_bcast:15 row_mask:0xa bank_mask:0xf
	s_nop 1
	v_mov_b32_e32 v15, v61
	v_max_f32_e32 v5, v24, v24
	v_max_f32_e32 v5, 0xda24260, v5
	v_mul_f32_e32 v64, v28, v30
	v_mul_f32_e32 v65, v29, v31
	v_rcp_f32_e32 v28, v5
	v_max_f32_e32 v5, v27, v27
	v_max_f32_e32 v5, 0xda24260, v5
	v_rcp_f32_e32 v29, v5
	v_max_f32_e32 v5, v26, v26
	v_max_f32_e32 v5, 0xda24260, v5
	v_mov_b32_e32 v61, v25
	v_mul_f32_e32 v42, v42, v28
	v_mul_f32_e32 v43, v43, v29
	v_rcp_f32_e32 v28, v5
	v_max_f32_e32 v5, v21, v21
	v_max_f32_e32 v5, 0xda24260, v5
	v_rcp_f32_e32 v29, v5
	v_max_f32_e32 v5, v20, v20
	v_max_f32_e32 v5, 0xda24260, v5
	v_mul_f32_e32 v36, v36, v16
	v_mul_f32_e32 v37, v37, v17
	v_mul_f32_e32 v66, v34, v28
	v_mul_f32_e32 v67, v35, v29
	v_rcp_f32_e32 v28, v5
	v_max_f32_e32 v5, v51, v51
	v_max_f32_e32 v5, 0xda24260, v5
	v_rcp_f32_e32 v29, v5
	v_max_f32_e32 v5, v22, v22
	v_max_f32_e32 v5, 0xda24260, v5
	v_mul_f32_e32 v56, v56, v18
	v_mul_f32_e32 v57, v57, v19
	v_mul_f32_e32 v46, v46, v28
	v_mul_f32_e32 v47, v47, v29
	v_rcp_f32_e32 v28, v5
	v_max_f32_e32 v5, v68, v68
	v_max_f32_e32 v5, 0xda24260, v5
	v_rcp_f32_e32 v29, v5
	v_mul_f32_e32 v38, v38, v14
	v_mul_f32_e32 v39, v39, v15
	v_mul_f32_e32 v48, v48, v60
	v_mul_f32_e32 v49, v49, v61
	v_mov_b32_e32 v25, v27
	v_mov_b32_e32 v27, v21
	v_mov_b32_e32 v21, v51
	v_mov_b32_e32 v23, v68
	v_mul_f32_e32 v52, v52, v24
	v_mul_f32_e32 v53, v53, v25
	v_mul_f32_e32 v58, v58, v26
	v_mul_f32_e32 v59, v59, v27
	v_mul_f32_e32 v44, v44, v20
	v_mul_f32_e32 v45, v45, v21
	v_mul_f32_e32 v50, v54, v22
	v_mul_f32_e32 v51, v55, v23
	v_mul_f32_e32 v54, v32, v28
	v_mul_f32_e32 v55, v33, v29
	v_cvt_pk_bf16_f32 v28, v36, v37
	v_cvt_pk_bf16_f32 v29, v56, v57
	v_cvt_pk_bf16_f32 v30, v38, v39
	v_cvt_pk_bf16_f32 v31, v48, v49
	v_cvt_pk_bf16_f32 v33, v2, v3
	v_add_u32_e32 v2, v91, v78
	v_cvt_pk_bf16_f32 v32, v62, v63
	v_cvt_pk_bf16_f32 v34, v40, v41
	v_cvt_pk_bf16_f32 v35, v64, v65
	ds_write_b128 v2, v[28:31]
	ds_write_b128 v2, v[32:35] offset:4608
	ds_write_b16 v150, v32 offset:9216
	ds_write_b16_d16_hi v150, v32 offset:9296
	ds_write_b16 v150, v33 offset:9376
	ds_write_b16_d16_hi v150, v33 offset:9456
	ds_write_b16 v150, v34 offset:9536
	ds_write_b16_d16_hi v150, v34 offset:9616
	ds_write_b16 v150, v35 offset:9696
	ds_write_b16_d16_hi v150, v35 offset:9776
	v_cvt_pk_bf16_f32 v28, v52, v53
	v_cvt_pk_bf16_f32 v29, v58, v59
	v_cvt_pk_bf16_f32 v30, v44, v45
	v_cvt_pk_bf16_f32 v31, v50, v51
	v_cvt_pk_bf16_f32 v32, v42, v43
	v_cvt_pk_bf16_f32 v33, v66, v67
	v_cvt_pk_bf16_f32 v34, v46, v47
	v_cvt_pk_bf16_f32 v35, v54, v55
	ds_write_b128 v151, v[28:31]
	ds_write_b128 v151, v[32:35] offset:4608
	ds_write_b16 v150, v32 offset:9856
	ds_write_b16_d16_hi v150, v32 offset:9936
	ds_write_b16 v150, v33 offset:10016
	ds_write_b16_d16_hi v150, v33 offset:10096
	ds_write_b16 v150, v34 offset:10176
	ds_write_b16_d16_hi v150, v34 offset:10256
	ds_write_b16 v150, v35 offset:10336
	ds_write_b16_d16_hi v150, v35 offset:10416
	s_waitcnt vmcnt(1)
	ds_write_b16 v150, v10 offset:14336
	ds_write_b16_d16_hi v150, v10 offset:14416
	ds_write_b16 v150, v11 offset:14496
	ds_write_b16_d16_hi v150, v11 offset:14576
	ds_write_b16 v150, v12 offset:14656
	ds_write_b16_d16_hi v150, v12 offset:14736
	ds_write_b16 v150, v13 offset:14816
	ds_write_b16_d16_hi v150, v13 offset:14896
	s_waitcnt vmcnt(0)
	ds_write_b16 v150, v6 offset:14976
	ds_write_b16_d16_hi v150, v6 offset:15056
	ds_write_b16 v150, v7 offset:15136
	ds_write_b16_d16_hi v150, v7 offset:15216
	ds_write_b16 v150, v8 offset:15296
	ds_write_b16_d16_hi v150, v8 offset:15376
	ds_write_b16 v150, v9 offset:15456
	ds_write_b16_d16_hi v150, v9 offset:15536
	s_and_saveexec_b64 s[2:3], s[38:39]
	s_cbranch_execz .LBB0_510
	v_add_u32_e32 v2, v85, v87
	ds_write_b128 v2, v[16:19] offset:19456
	v_mov_b32_e32 v16, v60
	v_mov_b32_e32 v17, v61
	ds_write_b128 v152, v[14:17] offset:19456
	ds_write_b128 v153, v[24:27] offset:19456
	ds_write_b128 v155, v[20:23] offset:19456

; #define LAS __attribute__((address_space(3)))
; template <int K>
; __device__ __forceinline__ void s2_gh_unit(LAS unsigned char* U, f32x4 (&S)[K / 16], const int cs, const int lane) {
;     typedef GHL<K> G; constexpr int NS = K / 32, KT = K / 16;
;     const int q = lane >> 4, r16 = lane & 15, c = 16 * cs + r16;
;     const f32x4 z4 = {0.f, 0.f, 0.f, 0.f};
;     const LAS unsigned char* vrow = U + G::OFF_VT + c * 80;
;     bf16x8 kf0[NS], kf1[NS], qf0[NS], qf1[NS], qp0[NS], qp1[NS], ktf[KT]; f32x4 e4[KT];
; #pragma unroll
;     for (int kt = 0; kt < KT; ++kt) { ktf[kt] = frag16(U + G::OFF_KT + (16 * kt + r16) * 80 + (8 * q) * 2); e4[kt] = *(const LAS f32x4*)(U + G::OFF_E + (16 * kt + 4 * q) * 4); }
;     const bf16x8 vn = frag16(vrow + (8 * q) * 2);
; #pragma unroll
;     for (int s = 0; s < NS; ++s) {
;         const LAS unsigned char* qr0 = U + G::OFF_Q + r16 * G::RS + (32 * s + 4 * q) * 2; const LAS unsigned char* qr1 = qr0 + 16 * G::RS;
;         qp0[s] = frag8x2(qr0, qr0 + 32); qp1[s] = frag8x2(qr1, qr1 + 32);
;     }
; #pragma unroll
;     for (int s = 0; s < NS; ++s) {
;         const int kb = (32 * s + 8 * q) * 2;
;         kf0[s] = frag16(U + G::OFF_K + r16 * G::RS + kb); kf1[s] = frag16(U + G::OFF_K + (16 + r16) * G::RS + kb);
;         qf0[s] = frag16(U + G::OFF_Q + r16 * G::RS + kb); qf1[s] = frag16(U + G::OFF_Q + (16 + r16) * G::RS + kb);
;     }
;     const bf16x8 vb = frag8x2(vrow + (4 * q) * 2, vrow + (16 + 4 * q) * 2);
;     bf16x8 sb[NS];
; #pragma unroll
;     for (int s = 0; s < NS; ++s) sb[s] = pack_frag(S[2 * s], S[2 * s + 1]);
; #pragma unroll
;     for (int kt = 0; kt < KT; ++kt) { S[kt] = MFMA16(ktf[kt], vn, S[kt]); S[kt] = S[kt] * e4[kt]; }
;     f32x4 X00 = z4, X01 = z4, X11 = z4;
; #pragma unroll
;     for (int s = 0; s < NS; ++s) { X00 = MFMA16(kf0[s], qf0[s], X00); X01 = MFMA16(kf0[s], qf1[s], X01); X11 = MFMA16(kf1[s], qf1[s], X11); }
;     f32x4 o0 = z4, o1 = z4;
; #pragma unroll
;     for (int s = 0; s < NS; ++s) { o0 = MFMA16(qp0[s], sb[s], o0); o1 = MFMA16(qp1[s], sb[s], o1); }
; #pragma unroll
;     for (int r = 0; r < 4; ++r) if (4 * q + r > r16) { X00[r] = 0.f; X11[r] = 0.f; }
;     const bf16x8 a0 = pack_frag(X00, z4), a1 = pack_frag(X01, X11);
;     o0 = MFMA16(a0, vb, o0); o1 = MFMA16(a1, vb, o1);
;     LAS float* ob = (LAS float*)(U + G::OFF_O);
; #pragma unroll
.LBB0_513:
	v_add_u32_e32 v63, s2, v147
	v_add_u32_e32 v72, s2, v144
	v_add_u32_e32 v129, s2, v148
	ds_read_b128 v[64:67], v63
	ds_read_b128 v[68:71], v63 offset:1280
	ds_read_b128 v[72:75], v72
	ds_read_b128 v[156:159], v129
	v_cvt_pk_bf16_f32 v54, v50, v51
	v_cvt_pk_bf16_f32 v55, v52, v53
	s_waitcnt lgkmcnt(1)
	v_mfma_f32_16x16x32_bf16 v[50:53], v[64:67], v[72:75], v[50:53]
	ds_read_b128 v[64:67], v63 offset:2560
	v_add_u32_e32 v76, s2, v146
	v_cvt_pk_bf16_f32 v56, v46, v47
	v_cvt_pk_bf16_f32 v57, v48, v49
	v_mfma_f32_16x16x32_bf16 v[46:49], v[68:71], v[72:75], v[46:49]
	ds_read_b128 v[68:71], v76
	v_cvt_pk_bf16_f32 v58, v42, v43
	v_cvt_pk_bf16_f32 v59, v44, v45
	s_waitcnt lgkmcnt(1)
	v_mfma_f32_16x16x32_bf16 v[42:45], v[64:67], v[72:75], v[42:45]
	ds_read_b128 v[64:67], v129 offset:6912
	v_add_u32_e32 v77, s2, v149
	v_add_u32_e32 v63, 0x800, v77
	v_add_u32_e32 v3, s2, v145
	v_cvt_pk_bf16_f32 v60, v38, v39
	v_cvt_pk_bf16_f32 v61, v40, v41
	s_waitcnt lgkmcnt(1)
	v_mfma_f32_16x16x32_bf16 v[38:41], v[68:71], v[72:75], v[38:41]
	ds_read_b128 v[68:71], v129 offset:2304
	ds_read_b128 v[72:75], v129 offset:4672
	ds_read_b128 v[160:163], v129 offset:64
	ds_read_b128 v[164:167], v129 offset:4608
	ds_read_b128 v[168:171], v129 offset:2368
	ds_read2_b64 v[172:175], v77 offset1:4
	ds_read_b128 v[176:179], v3 offset:19456
	ds_read2_b64 v[184:187], v63 offset0:32 offset1:36
	s_waitcnt lgkmcnt(7)
	v_mfma_f32_16x16x32_bf16 v[64:67], v[64:67], v[68:71], 0
	ds_read_b128 v[180:183], v129 offset:6976
	v_mov_b32_e32 v2, s63
	v_mov_b32_e32 v62, s63
	s_waitcnt lgkmcnt(5)
	v_mfma_f32_16x16x32_bf16 v[156:159], v[164:167], v[156:159], 0
	v_add_u32_e32 v192, s2, v143
	v_mov_b32_e32 v5, v4
	v_add_u32_e32 v193, s2, v79
	v_mfma_f32_16x16x32_bf16 v[68:71], v[164:167], v[68:71], 0
	ds_read_b128 v[164:167], v3 offset:19520
	v_add_u32_e32 v202, s2, v142
	s_addk_i32 s2, 0x6f00
	s_waitcnt lgkmcnt(4)
	v_mfma_f32_16x16x32_bf16 v[172:175], v[172:175], v[54:57], 0
	s_cmp_eq_u32 s2, 0x1bc00
	s_waitcnt lgkmcnt(3)
	v_mul_f32_e32 v52, v178, v52
	v_mul_f32_e32 v53, v179, v53
	v_mul_f32_e32 v50, v176, v50
	v_mul_f32_e32 v51, v177, v51
	s_waitcnt lgkmcnt(2)
	v_mfma_f32_16x16x32_bf16 v[54:57], v[184:187], v[54:57], 0
	ds_read_b128 v[184:187], v3 offset:19584
	ds_read_b128 v[188:191], v3 offset:19648
	ds_read2_b64 v[198:201], v77 offset0:8 offset1:12
	s_waitcnt lgkmcnt(3)
	v_mul_f32_e32 v48, v166, v48
	v_mul_f32_e32 v49, v167, v49
	v_mul_f32_e32 v46, v164, v46
	v_mul_f32_e32 v47, v165, v47
	v_mfma_f32_16x16x32_bf16 v[156:159], v[72:75], v[160:163], v[156:159]
	ds_read2_b64 v[160:163], v63 offset0:40 offset1:44
	s_waitcnt lgkmcnt(3)
	v_mul_f32_e32 v44, v186, v44
	v_mul_f32_e32 v45, v187, v45
	v_mul_f32_e32 v42, v184, v42
	v_mul_f32_e32 v43, v185, v43
	v_mfma_f32_16x16x32_bf16 v[64:67], v[180:183], v[168:171], v[64:67]
	ds_read2_b64 v[180:183], v192 offset1:4
	s_nop 1
	v_cndmask_b32_e64 v2, v156, v2, s[40:41]
	v_cndmask_b32_e64 v63, v159, 0, s[46:47]
	v_mfma_f32_16x16x32_bf16 v[68:71], v[72:75], v[168:171], v[68:71]
	v_cndmask_b32_e64 v2, v2, v156, s[42:43]
	s_nop 0
	v_cndmask_b32_e64 v3, v64, v62, s[40:41]
	v_cndmask_b32_e64 v77, 0, v65, s[42:43]
	s_waitcnt lgkmcnt(2)
	v_mfma_f32_16x16x32_bf16 v[72:75], v[198:201], v[58:61], v[172:175]
	v_cndmask_b32_e64 v62, v66, 0, s[44:45]
	v_cndmask_b32_e64 v65, v67, 0, s[46:47]
	v_cndmask_b32_e64 v66, v3, v64, s[42:43]
	s_waitcnt lgkmcnt(1)
	v_mfma_f32_16x16x32_bf16 v[54:57], v[160:163], v[58:61], v[54:57]
	v_cndmask_b32_e64 v60, 0, v157, s[42:43]
	v_cndmask_b32_e64 v61, v158, 0, s[44:45]
	v_cvt_pk_bf16_f32 v3, v61, v63
	v_cvt_pk_bf16_f32 v2, v2, v60
	v_cvt_pk_bf16_f32 v58, v68, v69
	v_cvt_pk_bf16_f32 v59, v70, v71
	v_cvt_pk_bf16_f32 v61, v62, v65
	v_cvt_pk_bf16_f32 v60, v66, v77
	s_waitcnt lgkmcnt(0)
	v_mfma_f32_16x16x32_bf16 v[62:65], v[2:5], v[180:183], v[72:75]
	v_mul_f32_e64 v40, v190, v40
	v_mul_f32_e64 v41, v191, v41
	v_mul_f32_e32 v38, v188, v38
	v_mul_f32_e32 v39, v189, v39
	v_add_u32_e32 v76, 0x1000, v193
	v_mfma_f32_16x16x32_bf16 v[54:57], v[58:61], v[180:183], v[54:57]
	s_nop 2
	ds_write_b32 v193, v62
	s_nop 3
	ds_write_b32 v202, v54
	ds_write2_b32 v193, v63, v64 offset0:68 offset1:136
	ds_write2_b32 v76, v55, v56 offset0:132 offset1:200
	ds_write_b32 v193, v65 offset:816
	ds_write_b32 v193, v57 offset:5168
	s_cbranch_scc0 .LBB0_513

; template <int K>
; __device__ __forceinline__ void s2_gh_unit(LAS unsigned char* U, f32x4 (&S)[K / 16], const int cs, const int lane) {
;     typedef GHL<K> G; constexpr int NS = K / 32, KT = K / 16;
;     const int q = lane >> 4, r16 = lane & 15, c = 16 * cs + r16;
;     const f32x4 z4 = {0.f, 0.f, 0.f, 0.f};
;     const LAS unsigned char* vrow = U + G::OFF_VT + c * 80;
;     bf16x8 kf0[NS], kf1[NS], qf0[NS], qf1[NS], qp0[NS], qp1[NS], ktf[KT]; f32x4 e4[KT];
; #pragma unroll
;     for (int kt = 0; kt < KT; ++kt) { ktf[kt] = frag16(U + G::OFF_KT + (16 * kt + r16) * 80 + (8 * q) * 2); e4[kt] = *(const LAS f32x4*)(U + G::OFF_E + (16 * kt + 4 * q) * 4); }
;     const bf16x8 vn = frag16(vrow + (8 * q) * 2);
; #pragma unroll
;     for (int s = 0; s < NS; ++s) {
;         const LAS unsigned char* qr0 = U + G::OFF_Q + r16 * G::RS + (32 * s + 4 * q) * 2; const LAS unsigned char* qr1 = qr0 + 16 * G::RS;
;         qp0[s] = frag8x2(qr0, qr0 + 32); qp1[s] = frag8x2(qr1, qr1 + 32);
;     }
; #pragma unroll
;     for (int s = 0; s < NS; ++s) {
;         const int kb = (32 * s + 8 * q) * 2;
;         kf0[s] = frag16(U + G::OFF_K + r16 * G::RS + kb); kf1[s] = frag16(U + G::OFF_K + (16 + r16) * G::RS + kb);
;         qf0[s] = frag16(U + G::OFF_Q + r16 * G::RS + kb); qf1[s] = frag16(U + G::OFF_Q + (16 + r16) * G::RS + kb);
;     }
;     const bf16x8 vb = frag8x2(vrow + (4 * q) * 2, vrow + (16 + 4 * q) * 2);
;     bf16x8 sb[NS];
; template <int MT>
; __device__ __forceinline__ void chain_gh(LAS unsigned char* L, const MixP& C, const int h, const int b0, const bool smp, const int tid) {
;     ...
; #pragma unroll 1
;             for (int job = w; job < 16; job += 8) {
;                 const int u = job >> 2, cs = job & 3, q = lane >> 4, c = 16 * cs + (lane & 15);
;                 const size_t sb = ((size_t)(b0 + u) * 4 + h) * K * 64;
; #pragma unroll
;                 for (int kt = 0; kt < KT; ++kt)
; #pragma unroll
;                     for (int r = 0; r < 4; ++r) S[kt][r] = sin[sb + (size_t)(16 * kt + 4 * q + r) * 64 + c];
;                 s2_gh_unit<K>(L + u * G::UNIT, S, cs, lane);
;                 float* so = C.out + o_s + (((size_t)C.l * BS + b0 + u) * 4 + h) * K * 64;
; #pragma unroll
;                 for (int kt = 0; kt < KT; ++kt)
; #pragma unroll
;                     for (int r = 0; r < 4; ++r) so[(size_t)(16 * kt + 4 * q + r) * 64 + c] = S[kt][r];
;             }
.LBB0_517:
	s_ashr_i32 s2, s21, 2
	s_add_i32 s22, s2, s4
	s_ashr_i32 s23, s22, 31
	s_lshl_b64 s[22:23], s[22:23], 16
	v_and_or_b32 v129, s20, 48, v93
	s_add_u32 s22, s14, s22
	s_addc_u32 s23, s15, s23
	v_lshlrev_b32_e32 v2, 2, v129
	v_mov_b32_e32 v3, v4
	v_lshl_add_u64 v[2:3], s[22:23], 0, v[2:3]
	v_lshlrev_b32_e32 v38, 2, v80
	v_mov_b32_e32 v39, v4
	v_lshl_add_u64 v[38:39], v[2:3], 0, v[38:39]
	global_load_dword v42, v[38:39], off
	global_load_dword v43, v[38:39], off offset:256
	global_load_dword v44, v[38:39], off offset:512
	global_load_dword v45, v[38:39], off offset:768
	v_lshlrev_b32_e32 v38, 2, v84
	v_mov_b32_e32 v39, v4
	v_lshl_add_u64 v[38:39], v[2:3], 0, v[38:39]
	global_load_dword v70, v[38:39], off
	v_lshlrev_b32_e32 v38, 2, v86
	v_mov_b32_e32 v39, v4
	v_lshl_add_u64 v[38:39], v[2:3], 0, v[38:39]
	global_load_dword v71, v[38:39], off
	v_lshlrev_b32_e32 v38, 2, v88
	v_mov_b32_e32 v39, v4
	v_lshl_add_u64 v[38:39], v[2:3], 0, v[38:39]
	global_load_dword v72, v[38:39], off
	v_lshlrev_b32_e32 v38, 2, v90
	v_mov_b32_e32 v39, v4
	v_lshl_add_u64 v[38:39], v[2:3], 0, v[38:39]
	global_load_dword v73, v[38:39], off
	v_lshlrev_b32_e32 v38, 2, v92
	v_mov_b32_e32 v39, v4
	v_lshl_add_u64 v[38:39], v[2:3], 0, v[38:39]
	global_load_dword v74, v[38:39], off
	v_lshlrev_b32_e32 v38, 2, v94
	v_mov_b32_e32 v39, v4
	v_lshl_add_u64 v[38:39], v[2:3], 0, v[38:39]
	global_load_dword v75, v[38:39], off
	v_lshlrev_b32_e32 v38, 2, v96
	v_mov_b32_e32 v39, v4
	v_lshl_add_u64 v[38:39], v[2:3], 0, v[38:39]
	global_load_dword v76, v[38:39], off
	v_lshlrev_b32_e32 v38, 2, v98
	v_mov_b32_e32 v39, v4
	v_lshl_add_u64 v[38:39], v[2:3], 0, v[38:39]
	global_load_dword v77, v[38:39], off
	v_lshlrev_b32_e32 v38, 2, v82
	v_mov_b32_e32 v39, v4
	v_lshl_add_u64 v[38:39], v[2:3], 0, v[38:39]
	global_load_dword v124, v[38:39], off
	v_lshlrev_b32_e32 v38, 2, v100
	v_mov_b32_e32 v39, v4
	v_lshl_add_u64 v[38:39], v[2:3], 0, v[38:39]
	global_load_dword v125, v[38:39], off
	v_lshlrev_b32_e32 v38, 2, v102
	v_mov_b32_e32 v39, v4
	v_lshl_add_u64 v[38:39], v[2:3], 0, v[38:39]
	global_load_dword v126, v[38:39], off
	v_lshlrev_b32_e32 v38, 2, v104
	v_mov_b32_e32 v39, v4
	v_lshl_add_u64 v[2:3], v[2:3], 0, v[38:39]
	global_load_dword v127, v[2:3], off
	s_mul_i32 s3, s2, 0x6f00
	s_add_i32 s3, s3, 0
	v_add_u32_e32 v2, s3, v99
	v_add_u32_e32 v3, v2, v101
	ds_read_b128 v[112:115], v3 offset:9216
	ds_read_b128 v[116:119], v2 offset:19456
	ds_read_b128 v[120:123], v3 offset:10496
	ds_read_b128 v[156:159], v2 offset:19520
	ds_read_b128 v[160:163], v3 offset:11776
	ds_read_b128 v[164:167], v2 offset:19584
	v_add_u32_e32 v3, v2, v103
	ds_read_b128 v[168:171], v3 offset:9216
	ds_read_b128 v[172:175], v2 offset:19648
	v_mov_b32_e32 v2, s3
	v_mad_u32_u24 v192, v129, s64, v2
	v_add_u32_e32 v2, v192, v99
	ds_read_b128 v[176:179], v2 offset:14336
	v_add_u32_e32 v2, s3, v105
	v_add_u32_e32 v3, v2, v134
	v_add_u32_e32 v5, 0x800, v3
	v_add_u32_e32 v2, v2, v99
	ds_read2_b64 v[46:49], v3 offset1:4
	ds_read2_b64 v[58:61], v5 offset0:32 offset1:36
	ds_read2_b64 v[54:57], v3 offset0:8 offset1:12
	ds_read2_b64 v[50:53], v5 offset0:40 offset1:44
	ds_read_b128 v[180:183], v2 offset:4608
	ds_read_b128 v[184:187], v2 offset:6912
	ds_read_b128 v[188:191], v2
	ds_read_b128 v[198:201], v2 offset:2304
	ds_read_b128 v[202:205], v2 offset:4672
	ds_read_b128 v[206:209], v2 offset:6976
	ds_read_b128 v[210:213], v2 offset:64
	ds_read_b128 v[214:217], v2 offset:2368
	v_add_u32_e32 v2, v192, v134
	v_add_u32_e32 v3, v192, v135
	ds_read_b64 v[38:39], v2 offset:14336
	ds_read_b64 v[40:41], v3 offset:14336
	v_mov_b32_e32 v2, s63
	s_ashr_i32 s3, s2, 31
	s_add_u32 s2, s16, s2
	s_addc_u32 s3, s17, s3
	s_lshl_b64 s[2:3], s[2:3], 16
	s_add_u32 s2, s18, s2
	s_addc_u32 s3, s19, s3
	s_addk_i32 s20, 0x80
	s_waitcnt vmcnt(14)
	v_cvt_pk_bf16_f32 v62, v42, v43
	s_waitcnt vmcnt(12)
	v_cvt_pk_bf16_f32 v63, v44, v45
	s_waitcnt lgkmcnt(14)
	v_mfma_f32_16x16x32_bf16 v[42:45], v[112:115], v[176:179], v[42:45]
	s_waitcnt vmcnt(10)
	v_cvt_pk_bf16_f32 v64, v70, v71
	s_waitcnt vmcnt(8)
	v_cvt_pk_bf16_f32 v65, v72, v73
	s_nop 3
	v_mul_f32_e32 v114, v118, v44
	v_mul_f32_e32 v115, v119, v45
	v_mul_f32_e32 v112, v116, v42
	v_mul_f32_e32 v113, v117, v43
	v_mfma_f32_16x16x32_bf16 v[42:45], v[120:123], v[176:179], v[70:73]
	s_waitcnt vmcnt(6)
; #define LAS __attribute__((address_space(3)))
; #define MFMA16(a, b, c) __builtin_amdgcn_mfma_f32_16x16x32_bf16((a), (b), (c), 0, 0, 0)
; __device__ __forceinline__ bf16x8 pack_frag(const f32x4 a, const f32x4 b) { v4u w; w.x = cvtpk(a[0], a[1]); w.y = cvtpk(a[2], a[3]); w.z = cvtpk(b[0], b[1]); w.w = cvtpk(b[2], b[3]); return __builtin_bit_cast(bf16x8, w); }
; template <int K>
; __device__ __forceinline__ void s2_gh_unit(LAS unsigned char* U, f32x4 (&S)[K / 16], const int cs, const int lane) {
;     ...
;     for (int kt = 0; kt < KT; ++kt) { S[kt] = MFMA16(ktf[kt], vn, S[kt]); S[kt] = S[kt] * e4[kt]; }
;     f32x4 X00 = z4, X01 = z4, X11 = z4;
; #pragma unroll
;     for (int s = 0; s < NS; ++s) { X00 = MFMA16(kf0[s], qf0[s], X00); X01 = MFMA16(kf0[s], qf1[s], X01); X11 = MFMA16(kf1[s], qf1[s], X11); }
;     f32x4 o0 = z4, o1 = z4;
; #pragma unroll
;     for (int s = 0; s < NS; ++s) { o0 = MFMA16(qp0[s], sb[s], o0); o1 = MFMA16(qp1[s], sb[s], o1); }
; #pragma unroll
;     for (int r = 0; r < 4; ++r) if (4 * q + r > r16) { X00[r] = 0.f; X11[r] = 0.f; }
;     const bf16x8 a0 = pack_frag(X00, z4), a1 = pack_frag(X01, X11);
;     o0 = MFMA16(a0, vb, o0); o1 = MFMA16(a1, vb, o1);
;     LAS float* ob = (LAS float*)(U + G::OFF_O);
; #pragma unroll
;     for (int r = 0; r < 4; ++r) { ob[(4 * q + r) * 68 + c] = o0[r]; ob[(16 + 4 * q + r) * 68 + c] = o1[r]; }
; }
; template <int MT>
; __device__ __forceinline__ void chain_gh(LAS unsigned char* L, const MixP& C, const int h, const int b0, const bool smp, const int tid) {
;     ...
; #pragma unroll
;                 for (int kt = 0; kt < KT; ++kt)
; #pragma unroll
;                     for (int r = 0; r < 4; ++r) so[(size_t)(16 * kt + 4 * q + r) * 64 + c] = S[kt][r];
;             }
	v_cvt_pk_bf16_f32 v66, v74, v75
	s_waitcnt lgkmcnt(13)
	v_mfma_f32_16x16x32_bf16 v[46:49], v[46:49], v[62:65], 0
	s_nop 3
	v_mul_f32_e64 v118, v158, v44
	v_mul_f32_e64 v119, v159, v45
	v_mul_f32_e32 v116, v156, v42
	v_mul_f32_e32 v117, v157, v43
	s_waitcnt vmcnt(4)
	v_cvt_pk_bf16_f32 v67, v76, v77
	v_mfma_f32_16x16x32_bf16 v[42:45], v[160:163], v[176:179], v[74:77]
	s_waitcnt vmcnt(2)
	v_cvt_pk_bf16_f32 v68, v124, v125
	s_waitcnt lgkmcnt(6)
	v_mfma_f32_16x16x32_bf16 v[156:159], v[180:183], v[198:201], 0
	s_nop 3
	v_mul_f32_e64 v122, v166, v44
	v_mul_f32_e64 v123, v167, v45
	v_mul_f32_e32 v120, v164, v42
	v_mul_f32_e32 v121, v165, v43
	s_waitcnt vmcnt(0)
	v_cvt_pk_bf16_f32 v69, v126, v127
	v_mfma_f32_16x16x32_bf16 v[42:45], v[168:171], v[176:179], v[124:127]
	v_mfma_f32_16x16x32_bf16 v[58:61], v[58:61], v[62:65], 0
	v_mfma_f32_16x16x32_bf16 v[46:49], v[54:57], v[66:69], v[46:49]
	s_nop 5
	v_mul_f32_e64 v126, v174, v44
	v_mul_f32_e64 v127, v175, v45
	v_mul_f32_e32 v124, v172, v42
	v_mul_f32_e32 v125, v173, v43
	v_mfma_f32_16x16x32_bf16 v[42:45], v[184:187], v[198:201], 0
	s_waitcnt lgkmcnt(2)
	v_mfma_f32_16x16x32_bf16 v[70:73], v[206:209], v[214:217], v[42:45]
	v_mfma_f32_16x16x32_bf16 v[42:45], v[180:183], v[188:191], 0
	v_mfma_f32_16x16x32_bf16 v[74:77], v[202:205], v[210:213], v[42:45]
	s_nop 5
	v_cndmask_b32_e64 v71, 0, v71, s[42:43]
	v_cndmask_b32_e64 v72, v72, 0, s[44:45]
	v_cndmask_b32_e64 v73, v73, 0, s[46:47]
	v_mfma_f32_16x16x32_bf16 v[42:45], v[202:205], v[214:217], v[156:159]
	s_nop 2
	v_mov_b32_e32 v156, s63
	v_cndmask_b32_e64 v2, v74, v2, s[40:41]
	v_cndmask_b32_e64 v3, v70, v156, s[40:41]
	v_cndmask_b32_e64 v2, v2, v74, s[42:43]
	v_cndmask_b32_e64 v5, 0, v75, s[42:43]
	v_cndmask_b32_e64 v70, v3, v70, s[42:43]
	v_cndmask_b32_e64 v3, v76, 0, s[44:45]
	v_cndmask_b32_e64 v74, v77, 0, s[46:47]
	v_cvt_pk_bf16_f32 v2, v2, v5
	v_cvt_pk_bf16_f32 v3, v3, v74
	v_mov_b32_e32 v5, v4
	v_cvt_pk_bf16_f32 v42, v42, v43
	v_cvt_pk_bf16_f32 v43, v44, v45
	v_cvt_pk_bf16_f32 v44, v70, v71
	v_cvt_pk_bf16_f32 v45, v72, v73
	v_mfma_f32_16x16x32_bf16 v[50:53], v[50:53], v[66:69], v[58:61]
	s_waitcnt lgkmcnt(0)
	v_mfma_f32_16x16x32_bf16 v[46:49], v[2:5], v[38:41], v[46:49]
	v_mad_i32_i24 v2, v129, s97, v192
	v_add_u32_e32 v3, v2, v136
	v_add_u32_e32 v2, v2, v137
	v_mfma_f32_16x16x32_bf16 v[38:41], v[42:45], v[38:41], v[50:53]
	s_nop 3
	ds_write_b32 v3, v46 offset:19712
	s_nop 2
	ds_write_b32 v2, v38 offset:19712
	v_add_u32_e32 v2, 0x4c00, v3
	ds_write2_b32 v2, v47, v48 offset0:132 offset1:200
	v_add_u32_e32 v2, 0x5e00, v3
	ds_write2_b32 v2, v39, v40 offset0:68 offset1:136
	ds_write_b32 v3, v49 offset:20528
	ds_write_b32 v3, v41 offset:24880
	v_or_b32_e32 v2, v129, v80
	v_lshlrev_b32_e32 v2, 2, v2
	global_store_dword v2, v112, s[2:3]
	v_add_lshl_u32 v2, v129, v80, 2
	global_store_dword v2, v113, s[2:3] offset:256
	global_store_dword v2, v114, s[2:3] offset:512
	global_store_dword v2, v115, s[2:3] offset:768
	v_or_b32_e32 v2, v129, v84
	v_lshlrev_b32_e32 v2, 2, v2
	global_store_dword v2, v116, s[2:3]
	v_or_b32_e32 v2, v129, v86
	v_lshlrev_b32_e32 v2, 2, v2
	global_store_dword v2, v117, s[2:3]
	v_or_b32_e32 v2, v129, v88
	v_lshlrev_b32_e32 v2, 2, v2
	global_store_dword v2, v118, s[2:3]
	v_or_b32_e32 v2, v129, v90
	v_lshlrev_b32_e32 v2, 2, v2
	global_store_dword v2, v119, s[2:3]
	v_or_b32_e32 v2, v129, v92
	v_lshlrev_b32_e32 v2, 2, v2
	global_store_dword v2, v120, s[2:3]
	v_or_b32_e32 v2, v129, v94
	v_lshlrev_b32_e32 v2, 2, v2
	global_store_dword v2, v121, s[2:3]
	v_or_b32_e32 v2, v129, v96
	v_lshlrev_b32_e32 v2, 2, v2
	global_store_dword v2, v122, s[2:3]
	v_or_b32_e32 v2, v129, v98
	v_lshlrev_b32_e32 v2, 2, v2
	global_store_dword v2, v123, s[2:3]
	v_or_b32_e32 v2, v129, v82
	v_lshlrev_b32_e32 v2, 2, v2
	global_store_dword v2, v124, s[2:3]
	v_or_b32_e32 v2, v129, v100
	v_lshlrev_b32_e32 v2, 2, v2
	global_store_dword v2, v125, s[2:3]
	v_or_b32_e32 v2, v129, v102
	v_lshlrev_b32_e32 v2, 2, v2
	global_store_dword v2, v126, s[2:3]
	v_or_b32_e32 v2, v129, v104
	v_lshlrev_b32_e32 v2, 2, v2
	global_store_dword v2, v127, s[2:3]
	s_add_i32 s2, s21, 8
	s_cmp_gt_i32 s21, 7
	s_mov_b32 s21, s2
	s_cbranch_scc0 .LBB0_517

; #define LAS __attribute__((address_space(3)))
; __device__ __forceinline__ unsigned cvtpk(float lo, float hi) { const f32x2v v = {lo, hi}; return __builtin_bit_cast(unsigned, __builtin_convertvector(v, bf16x2v)); }
; __device__ __forceinline__ float quad_sum(float v) { v += dpp_sel<0xB1, 0xf>(0.f, v); v += dpp_sel<0x4E, 0xf>(0.f, v); return v; }
; template <int MT>
; __device__ __forceinline__ void chain_gh(LAS unsigned char* L, const MixP& C, const int h, const int b0, const bool smp, const int tid) {
;     ...
;             const LAS float* ob = (const LAS float*)(L + u3 * G::UNIT + G::OFF_O) + i3 * 68 + 16 * cq3;
;             f32x4 o[4]; float ss = 0.f;
; #pragma unroll
;             for (int j = 0; j < 4; ++j) { o[j] = *(const LAS f32x4*)(ob + 4 * j); ss += (o[j][0] * o[j][0] + o[j][1] * o[j][1]) + (o[j][2] * o[j][2] + o[j][3] * o[j][3]); }
;             ss = quad_sum(ss);
;             const float r = rsqrtf(ss * (1.0f / 64.0f) + 1e-6f);
;             float res[16], nwv[16];
; #pragma unroll
;             for (int j = 0; j < 4; ++j) { const f32x4 t = *(const LAS f32x4*)(cst + 600 + 16 * cq3 + 4 * j); nwv[4 * j] = t[0]; nwv[4 * j + 1] = t[1]; nwv[4 * j + 2] = t[2]; nwv[4 * j + 3] = t[3]; }
; #pragma unroll
;             for (int e = 0; e < 16; ++e) { const float gv = (e < 8) ? bfe(gg0, e) : bfe(gg1, e - 8); res[e] = o[e >> 2][e & 3] * r * nwv[e] * gv; }
;             if (valid3) {
;                 v4u w0, w1;
;                 w0.x = cvtpk(res[0], res[1]); w0.y = cvtpk(res[2], res[3]); w0.z = cvtpk(res[4], res[5]); w0.w = cvtpk(res[6], res[7]);
;                 w1.x = cvtpk(res[8], res[9]); w1.y = cvtpk(res[10], res[11]); w1.z = cvtpk(res[12], res[13]); w1.w = cvtpk(res[14], res[15]);
;                 bf16* mo = C.mixb + (size_t)row3 * D + ((MT == 0) ? MC_GLA : MC_HGRN) + h * 64 + 16 * cq3;
;                 *(v4u*)mo = w0; *(v4u*)(mo + 8) = w1;
;             }
.LBB0_519:
	s_waitcnt lgkmcnt(0)
	s_barrier
	ds_read_b128 v[58:61], v138 offset:19712
	ds_read_b128 v[62:65], v138 offset:19728
	ds_read_b128 v[66:69], v138 offset:19744
	ds_read_b128 v[54:57], v138 offset:19760
	s_waitcnt lgkmcnt(3)
	v_mul_f32_e32 v2, v59, v59
	v_mul_f32_e32 v3, v61, v61
	v_fmac_f32_e32 v2, v58, v58
	v_fmac_f32_e32 v3, v60, v60
	v_add_f32_e32 v2, v2, v3
	s_waitcnt lgkmcnt(2)
	v_mul_f32_e32 v3, v63, v63
	v_mul_f32_e32 v5, v65, v65
	v_fmac_f32_e32 v3, v62, v62
	v_fmac_f32_e32 v5, v64, v64
	v_add_f32_e32 v3, v3, v5
	v_add_f32_e32 v2, v2, v3
	s_waitcnt lgkmcnt(1)
	v_mul_f32_e32 v3, v67, v67
	v_mul_f32_e32 v5, v69, v69
	v_fmac_f32_e32 v3, v66, v66
	v_fmac_f32_e32 v5, v68, v68
	v_add_f32_e32 v3, v3, v5
	v_add_f32_e32 v2, v2, v3
	s_waitcnt lgkmcnt(0)
	v_mul_f32_e32 v3, v55, v55
	v_mul_f32_e32 v5, v57, v57
	v_fmac_f32_e32 v3, v54, v54
	v_fmac_f32_e32 v5, v56, v56
	v_add_f32_e32 v3, v3, v5
	v_add_f32_e32 v2, v2, v3
	v_mov_b32_e32 v3, v4
	s_nop 0
	v_add_f32_dpp v2, v2, v2 quad_perm:[1,0,3,2] row_mask:0xf bank_mask:0xf bound_ctrl:1
	s_nop 1
	v_mov_b32_dpp v3, v2 quad_perm:[2,3,0,1] row_mask:0xf bank_mask:0xf
	s_and_saveexec_b64 s[2:3], s[48:49]
	s_cbranch_execz .LBB0_521
	v_add_f32_e32 v2, v2, v3
	v_fmamk_f32 v2, v2, 0x3c800000, v231
	s_mov_b32 s20, 0x800000
	v_mul_f32_e32 v3, 0x4b800000, v2
	v_cmp_gt_f32_e32 vcc, s20, v2
	ds_read_b128 v[70:73], v139 offset:32
	ds_read_b128 v[74:77], v139 offset:48
	ds_read_b128 v[112:115], v139
	ds_read_b128 v[116:119], v139 offset:16
	v_cndmask_b32_e32 v2, v2, v3, vcc
	v_rsq_f32_e32 v2, v2
	v_ashrrev_i32_e32 v129, 31, v128
	v_mul_f32_e32 v3, 0x45800000, v2
	v_cndmask_b32_e32 v2, v2, v3, vcc
	v_mul_f32_e32 v68, v68, v2
	v_mul_f32_e32 v69, v69, v2
	v_mul_f32_e32 v66, v66, v2
	v_mul_f32_e32 v67, v67, v2
	s_waitcnt lgkmcnt(3)
	v_mul_f32_e32 v68, v68, v72
	v_mul_f32_e32 v69, v69, v73
	s_waitcnt vmcnt(7)
	v_lshlrev_b32_e32 v72, 16, v31
	v_and_b32_e32 v73, 0xffff0000, v31
	v_mul_f32_e32 v66, v66, v70
	v_mul_f32_e32 v67, v67, v71
	v_lshlrev_b32_e32 v70, 16, v30
	v_and_b32_e32 v71, 0xffff0000, v30
	v_mul_f32_e32 v30, v64, v2
	v_mul_f32_e32 v31, v65, v2
	s_waitcnt vmcnt(6)
	v_lshlrev_b32_e32 v64, 16, v37
	s_waitcnt lgkmcnt(0)
	v_mul_f32_e32 v30, v30, v118
	v_mul_f32_e32 v31, v31, v119
	v_and_b32_e32 v65, 0xffff0000, v37
	v_mul_f32_e32 v64, v30, v64
	v_mul_f32_e32 v65, v31, v65
	v_mul_f32_e32 v30, v62, v2
	v_mul_f32_e32 v31, v63, v2
	v_lshlrev_b32_e32 v62, 16, v36
	v_mul_f32_e32 v30, v30, v116
	v_mul_f32_e32 v31, v31, v117
	v_and_b32_e32 v63, 0xffff0000, v36
	v_mul_f32_e32 v36, v30, v62
	v_mul_f32_e32 v37, v31, v63
	v_mul_f32_e32 v30, v60, v2
	v_mul_f32_e32 v31, v61, v2
	v_lshlrev_b32_e32 v60, 16, v35
	v_mul_f32_e32 v30, v30, v114
	v_mul_f32_e32 v31, v31, v115
	v_and_b32_e32 v61, 0xffff0000, v35
	v_mul_f32_e32 v54, v54, v2
	v_mul_f32_e32 v55, v55, v2
	v_mul_f32_e32 v60, v30, v60
	v_mul_f32_e32 v61, v31, v61
	v_mul_f32_e32 v30, v58, v2
	v_mul_f32_e32 v31, v59, v2
	v_mul_f32_e32 v3, v57, v2
	v_mul_f32_e32 v2, v56, v2
	v_mul_f32_e32 v54, v54, v74
	v_mul_f32_e32 v55, v55, v75
	v_lshlrev_b32_e32 v74, 16, v32
	v_and_b32_e32 v75, 0xffff0000, v32
	v_mul_f32_e32 v30, v30, v112
	v_mul_f32_e32 v31, v31, v113
	v_lshlrev_b32_e32 v58, 16, v34
	v_and_b32_e32 v59, 0xffff0000, v34
	v_mul_f32_e32 v2, v2, v76
	v_mul_f32_e32 v3, v3, v77
	v_lshlrev_b32_e32 v32, 16, v33
	v_and_b32_e32 v33, 0xffff0000, v33
	v_mul_f32_e32 v30, v30, v58
	v_mul_f32_e32 v31, v31, v59
	v_lshlrev_b64 v[58:59], 11, v[128:129]
	v_mul_f32_e32 v2, v2, v32
	v_mul_f32_e32 v3, v3, v33
	v_mul_f32_e32 v54, v54, v74
	v_mul_f32_e32 v55, v55, v75
	v_mul_f32_e32 v68, v68, v72
	v_mul_f32_e32 v69, v69, v73
	v_mul_f32_e32 v66, v66, v70
	v_mul_f32_e32 v67, v67, v71
	v_cvt_pk_bf16_f32 v30, v30, v31
	v_cvt_pk_bf16_f32 v31, v60, v61
	v_cvt_pk_bf16_f32 v32, v36, v37
	v_cvt_pk_bf16_f32 v33, v64, v65
	v_cvt_pk_bf16_f32 v37, v2, v3
	v_lshl_add_u64 v[2:3], v[110:111], 0, v[58:59]
	v_cvt_pk_bf16_f32 v34, v66, v67
	v_cvt_pk_bf16_f32 v35, v68, v69
	v_cvt_pk_bf16_f32 v36, v54, v55
	global_store_dwordx4 v[2:3], v[30:33], off offset:1024
	global_store_dwordx4 v[2:3], v[34:37], off offset:1040

; __device__ __forceinline__ void ssd_scan(const MixP& C, const int wg, const int nwgs, const int tid) {
;     constexpr int NSC = TP / 64, NQ = BP * 2 * 2 * 2048;
;     const int per = (((NQ + nwgs - 1) / nwgs) + 63) & ~63;
;     const int qi = wg * per + tid;
;     if (tid < per && qi < NQ) {
;         const int e = (qi & 2047) * 4, bgh = __builtin_amdgcn_readfirstlane(qi >> 11), hh = bgh & 1, bg = bgh >> 1;
;         float* dp = C.DS + ((size_t)bg * NSC * 2 + hh) * 8192 + e;
;         const float* ep = C.ESC + (size_t)bg * NSC * 2 + hh;
;         f32x4 s = {0.f, 0.f, 0.f, 0.f};
; #pragma unroll 1
;         for (int h0 = 0; h0 < NSC; h0 += NSC / 2) {
;             f32x4 d[NSC / 2]; float E[NSC / 2];
; #pragma unroll
;             for (int k = 0; k < NSC / 2; ++k) { d[k] = *(const f32x4*)(dp + (size_t)(h0 + k) * 2 * 8192); E[k] = ep[(h0 + k) * 2]; }
.LBB0_569:
	s_lshl_b32 s62, s13, 1
	s_lshl_b32 s92, s13, 14
	s_lshl_b64 s[0:1], s[62:63], 2
	s_add_u32 s94, s9, s0
	s_addc_u32 s95, s3, s1
	s_or_b32 s0, s13, 1
	s_lshl_b32 s62, s0, 1
	s_lshl_b32 s88, s0, 14
	s_lshl_b64 s[0:1], s[62:63], 2
	s_add_u32 s90, s9, s0
	s_addc_u32 s91, s3, s1
	s_or_b32 s0, s13, 2
	s_lshl_b32 s62, s0, 1
	s_lshl_b32 s84, s0, 14
	s_lshl_b64 s[0:1], s[62:63], 2
	s_add_u32 s86, s9, s0
	s_addc_u32 s87, s3, s1
	s_or_b32 s0, s13, 3
	s_lshl_b32 s62, s0, 1
	s_lshl_b32 s80, s0, 14
	s_lshl_b64 s[0:1], s[62:63], 2
	s_add_u32 s82, s9, s0
	s_addc_u32 s83, s3, s1
	s_or_b32 s0, s13, 4
	s_lshl_b32 s62, s0, 1
	s_lshl_b32 s22, s0, 14
	s_lshl_b64 s[0:1], s[62:63], 2
	s_add_u32 s0, s9, s0
	v_cndmask_b32_e64 v3, 0, 1, s[10:11]
	s_addc_u32 s1, s3, s1
	s_or_b32 s10, s13, 5
	s_lshl_b32 s62, s10, 1
	s_lshl_b32 vcc_lo, s10, 14
	s_lshl_b64 s[10:11], s[62:63], 2
	s_add_u32 s30, s9, s10
	s_addc_u32 s31, s3, s11
	s_or_b32 s10, s13, 6
	s_lshl_b32 s62, s10, 1
	s_lshl_b32 s56, s10, 14
	s_lshl_b64 s[10:11], s[62:63], 2
	s_add_u32 s60, s9, s10
	s_addc_u32 s61, s3, s11
	s_or_b32 s10, s13, 7
	s_lshl_b32 s62, s10, 1
	s_lshl_b32 s26, s10, 14
	s_lshl_b64 s[10:11], s[62:63], 2
	s_add_u32 s54, s9, s10
	s_addc_u32 s55, s3, s11
	s_or_b32 s10, s13, 8
	s_lshl_b32 s62, s10, 1
	s_lshl_b32 s16, s10, 14
	s_lshl_b64 s[10:11], s[62:63], 2
	s_add_u32 s18, s9, s10
	s_addc_u32 s19, s3, s11
	s_or_b32 s10, s13, 9
	s_lshl_b32 s62, s10, 1
	s_lshl_b32 s12, s10, 14
	s_lshl_b64 s[10:11], s[62:63], 2
	s_add_u32 s14, s9, s10
	s_addc_u32 s15, s3, s11
	s_or_b32 s10, s13, 10
	s_lshl_b32 s62, s10, 1
	s_mov_b32 s93, s63
	s_lshl_b32 s50, s10, 14
	s_lshl_b64 s[10:11], s[62:63], 2
	v_lshl_add_u64 v[16:17], s[92:93], 2, v[14:15]
	s_add_u32 s52, s9, s10
	global_load_dwordx4 v[10:13], v[16:17], off
	global_load_dword v18, v4, s[94:95]
	s_addc_u32 s53, s3, s11
	s_or_b32 s10, s13, 11
	s_mov_b32 s89, s63
	s_lshl_b32 s62, s10, 1
	v_lshl_add_u64 v[20:21], s[88:89], 2, v[14:15]
	s_lshl_b32 s46, s10, 14
	s_lshl_b64 s[10:11], s[62:63], 2
	global_load_dwordx4 v[20:23], v[20:21], off
	s_nop 0
	global_load_dword v80, v4, s[90:91]
	s_mov_b32 s85, s63
	s_add_u32 s48, s9, s10
	v_lshl_add_u64 v[24:25], s[84:85], 2, v[14:15]
	s_addc_u32 s49, s3, s11
	s_or_b32 s10, s13, 12
	global_load_dwordx4 v[24:27], v[24:25], off
	s_nop 0
	global_load_dword v82, v4, s[86:87]
	s_mov_b32 s81, s63
	s_lshl_b32 s62, s10, 1
	v_lshl_add_u64 v[28:29], s[80:81], 2, v[14:15]
	s_lshl_b32 s42, s10, 14
	s_lshl_b64 s[10:11], s[62:63], 2
	global_load_dwordx4 v[28:31], v[28:29], off
	s_nop 0
	global_load_dword v84, v4, s[82:83]
	s_mov_b32 s23, s63
	s_add_u32 s44, s9, s10
	v_lshl_add_u64 v[32:33], s[22:23], 2, v[14:15]
	s_addc_u32 s45, s3, s11
	s_or_b32 s10, s13, 13
	global_load_dwordx4 v[32:35], v[32:33], off
	s_nop 0
	global_load_dword v86, v4, s[0:1]
	s_mov_b32 vcc_hi, s63
	s_lshl_b32 s62, s10, 1
	v_lshl_add_u64 v[36:37], vcc, 2, v[14:15]
	s_lshl_b32 s38, s10, 14
	s_lshl_b64 s[10:11], s[62:63], 2
	global_load_dwordx4 v[36:39], v[36:37], off
	s_nop 0
	global_load_dword v88, v4, s[30:31]
	s_mov_b32 s57, s63
	s_add_u32 s40, s9, s10
	v_lshl_add_u64 v[40:41], s[56:57], 2, v[14:15]
	s_addc_u32 s41, s3, s11
	s_or_b32 s10, s13, 14
	global_load_dwordx4 v[40:43], v[40:41], off
	s_nop 0
	global_load_dword v90, v4, s[60:61]
	s_mov_b32 s27, s63
	s_lshl_b32 s62, s10, 1
	v_lshl_add_u64 v[44:45], s[26:27], 2, v[14:15]
	s_lshl_b32 s24, s10, 14
	s_lshl_b64 s[10:11], s[62:63], 2
	global_load_dwordx4 v[44:47], v[44:45], off
	s_nop 0
	global_load_dword v92, v4, s[54:55]
	s_mov_b32 s17, s63
	s_add_u32 s34, s9, s10
	v_lshl_add_u64 v[48:49], s[16:17], 2, v[14:15]
	s_addc_u32 s35, s3, s11
	s_or_b32 s11, s13, 15
	global_load_dwordx4 v[48:51], v[48:49], off
	s_nop 0
	global_load_dword v94, v4, s[18:19]
	s_mov_b32 s13, s63
	v_lshl_add_u64 v[52:53], s[12:13], 2, v[14:15]
	global_load_dwordx4 v[52:55], v[52:53], off
	s_nop 0
	global_load_dword v96, v4, s[14:15]
	s_mov_b32 s51, s63
	v_lshl_add_u64 v[56:57], s[50:51], 2, v[14:15]
	global_load_dwordx4 v[56:59], v[56:57], off
	s_nop 0
	global_load_dword v98, v4, s[52:53]
	s_mov_b32 s47, s63
	v_lshl_add_u64 v[60:61], s[46:47], 2, v[14:15]
	global_load_dwordx4 v[60:63], v[60:61], off
	s_nop 0
	global_load_dword v100, v4, s[48:49]
	s_mov_b32 s43, s63
	v_lshl_add_u64 v[64:65], s[42:43], 2, v[14:15]
	global_load_dwordx4 v[64:67], v[64:65], off
	s_nop 0
	global_load_dword v102, v4, s[44:45]
	s_mov_b32 s39, s63
	v_lshl_add_u64 v[68:69], s[38:39], 2, v[14:15]
	s_lshl_b32 s62, s11, 1
	global_load_dwordx4 v[68:71], v[68:69], off
	s_nop 0
	global_load_dword v104, v4, s[40:41]
	s_mov_b32 s25, s63
	s_lshl_b32 s10, s11, 14
	s_lshl_b64 s[20:21], s[62:63], 2
	v_lshl_add_u64 v[72:73], s[24:25], 2, v[14:15]
	s_mov_b32 s11, s63
	s_add_u32 s20, s9, s20
	global_load_dwordx4 v[72:75], v[72:73], off
	s_nop 0
	global_load_dword v106, v4, s[34:35]
	v_lshl_add_u64 v[76:77], s[10:11], 2, v[14:15]
	s_addc_u32 s21, s3, s21
	global_load_dwordx4 v[76:79], v[76:77], off
	s_nop 0
	global_load_dword v108, v4, s[20:21]
	s_mov_b32 s22, 0x10000
	global_store_dwordx4 v[16:17], v[6:9], off
	s_mov_b32 s0, 0xb0000
	v_cmp_ne_u32_e64 s[36:37], 1, v3
	s_waitcnt vmcnt(31)
; __device__ __forceinline__ void ssd_scan(const MixP& C, const int wg, const int nwgs, const int tid) {
;     ...
;             for (int k = 0; k < NSC / 2; ++k) { d[k] = *(const f32x4*)(dp + (size_t)(h0 + k) * 2 * 8192); E[k] = ep[(h0 + k) * 2]; }
; #pragma unroll
;             for (int k = 0; k < NSC / 2; ++k) { *(f32x4*)(dp + (size_t)(h0 + k) * 2 * 8192) = s; s = s * E[k] + d[k]; }
;         }
;         const int b = bg >> 1, g = bg & 1;
;         *(f32x4*)(C.out + O_SSMP + (((size_t)C.l * BP + b) * 4 + 2 * g + hh) * 8192 + e) = s;
	v_fma_f32 v6, v6, v18, v10
	v_fma_f32 v7, v7, v18, v11
	v_add_co_u32_e32 v10, vcc, s22, v16
	v_fma_f32 v8, v8, v18, v12
	v_fma_f32 v9, v9, v18, v13
	s_nop 0
	v_addc_co_u32_e32 v11, vcc, 0, v17, vcc
	global_store_dwordx4 v[10:11], v[6:9], off
	v_add_co_u32_e32 v10, vcc, s79, v16
	s_waitcnt vmcnt(30)
	v_fma_f32 v8, v8, v80, v22
	v_fma_f32 v9, v9, v80, v23
	v_fma_f32 v6, v6, v80, v20
	v_fma_f32 v7, v7, v80, v21
	v_addc_co_u32_e32 v11, vcc, 0, v17, vcc
	global_store_dwordx4 v[10:11], v[6:9], off
	v_add_co_u32_e32 v10, vcc, s6, v16
	s_waitcnt vmcnt(29)
	v_fma_f32 v8, v8, v82, v26
	v_fma_f32 v9, v9, v82, v27
	v_fma_f32 v6, v6, v82, v24
	v_fma_f32 v7, v7, v82, v25
	v_addc_co_u32_e32 v11, vcc, 0, v17, vcc
	global_store_dwordx4 v[10:11], v[6:9], off
	v_add_co_u32_e32 v10, vcc, s7, v16
	s_waitcnt vmcnt(28)
	v_fma_f32 v8, v8, v84, v30
	v_fma_f32 v9, v9, v84, v31
	v_fma_f32 v6, v6, v84, v28
	v_fma_f32 v7, v7, v84, v29
	v_addc_co_u32_e32 v11, vcc, 0, v17, vcc
	global_store_dwordx4 v[10:11], v[6:9], off
	v_add_co_u32_e32 v10, vcc, s68, v16
	s_waitcnt vmcnt(27)
	v_fma_f32 v8, v8, v86, v34
	v_fma_f32 v9, v9, v86, v35
	v_fma_f32 v6, v6, v86, v32
	v_fma_f32 v7, v7, v86, v33
	v_addc_co_u32_e32 v11, vcc, 0, v17, vcc
	global_store_dwordx4 v[10:11], v[6:9], off
	v_add_co_u32_e32 v10, vcc, s97, v16
	s_waitcnt vmcnt(26)
	v_fma_f32 v8, v8, v88, v38
	v_fma_f32 v9, v9, v88, v39
	v_fma_f32 v6, v6, v88, v36
	v_fma_f32 v7, v7, v88, v37
	v_addc_co_u32_e32 v11, vcc, 0, v17, vcc
	global_store_dwordx4 v[10:11], v[6:9], off
	v_add_co_u32_e32 v10, vcc, s8, v16
	s_waitcnt vmcnt(25)
	v_fma_f32 v8, v8, v90, v42
	v_fma_f32 v9, v9, v90, v43
	v_fma_f32 v6, v6, v90, v40
	v_fma_f32 v7, v7, v90, v41
	v_addc_co_u32_e32 v11, vcc, 0, v17, vcc
	global_store_dwordx4 v[10:11], v[6:9], off
	v_add_co_u32_e32 v10, vcc, s66, v16
	s_waitcnt vmcnt(24)
	v_fma_f32 v8, v8, v92, v46
	v_fma_f32 v9, v9, v92, v47
	v_fma_f32 v6, v6, v92, v44
	v_fma_f32 v7, v7, v92, v45
	v_addc_co_u32_e32 v11, vcc, 0, v17, vcc
	global_store_dwordx4 v[10:11], v[6:9], off
	v_add_co_u32_e32 v10, vcc, s65, v16
	s_waitcnt vmcnt(23)
	v_fma_f32 v8, v8, v94, v50
	v_fma_f32 v9, v9, v94, v51
	v_fma_f32 v6, v6, v94, v48
	v_fma_f32 v7, v7, v94, v49
	v_addc_co_u32_e32 v11, vcc, 0, v17, vcc
	global_store_dwordx4 v[10:11], v[6:9], off
	v_add_co_u32_e32 v10, vcc, s67, v16
	s_waitcnt vmcnt(22)
	v_fma_f32 v8, v8, v96, v54
	v_fma_f32 v9, v9, v96, v55
	v_fma_f32 v6, v6, v96, v52
	v_fma_f32 v7, v7, v96, v53
	v_addc_co_u32_e32 v11, vcc, 0, v17, vcc
	global_store_dwordx4 v[10:11], v[6:9], off
	v_add_co_u32_e32 v10, vcc, s0, v16
	s_waitcnt vmcnt(21)
	v_fma_f32 v8, v8, v98, v58
	v_fma_f32 v9, v9, v98, v59
	v_fma_f32 v6, v6, v98, v56
	v_fma_f32 v7, v7, v98, v57
	v_addc_co_u32_e32 v11, vcc, 0, v17, vcc
	s_mov_b32 s0, 0xc0000
	global_store_dwordx4 v[10:11], v[6:9], off
	v_add_co_u32_e32 v10, vcc, s0, v16
	s_waitcnt vmcnt(20)
	v_fma_f32 v8, v8, v100, v62
	v_fma_f32 v9, v9, v100, v63
	v_fma_f32 v6, v6, v100, v60
	v_fma_f32 v7, v7, v100, v61
	v_addc_co_u32_e32 v11, vcc, 0, v17, vcc
	s_mov_b32 s0, 0xd0000
	global_store_dwordx4 v[10:11], v[6:9], off
	v_add_co_u32_e32 v10, vcc, s0, v16
	s_waitcnt vmcnt(19)
	v_fma_f32 v8, v8, v102, v66
	v_fma_f32 v9, v9, v102, v67
	v_fma_f32 v6, v6, v102, v64
	v_fma_f32 v7, v7, v102, v65
	v_addc_co_u32_e32 v11, vcc, 0, v17, vcc
	s_mov_b32 s0, 0xe0000
	global_store_dwordx4 v[10:11], v[6:9], off
	v_add_co_u32_e32 v10, vcc, s0, v16
	s_waitcnt vmcnt(18)
	v_fma_f32 v8, v8, v104, v70
	v_fma_f32 v9, v9, v104, v71
	v_fma_f32 v6, v6, v104, v68
	v_fma_f32 v7, v7, v104, v69
	v_addc_co_u32_e32 v11, vcc, 0, v17, vcc
	s_mov_b32 s0, 0xf0000
	global_store_dwordx4 v[10:11], v[6:9], off
	v_add_co_u32_e32 v10, vcc, s0, v16
	s_waitcnt vmcnt(17)
	v_fma_f32 v8, v8, v106, v74
	v_fma_f32 v9, v9, v106, v75
	v_fma_f32 v6, v6, v106, v72
	v_fma_f32 v7, v7, v106, v73
	v_addc_co_u32_e32 v11, vcc, 0, v17, vcc
	global_store_dwordx4 v[10:11], v[6:9], off
	s_mov_b32 s13, 16
	s_mov_b64 s[10:11], 0
	s_waitcnt vmcnt(16)
	v_fma_f32 v8, v8, v108, v78
	v_fma_f32 v9, v9, v108, v79
	v_fma_f32 v6, v6, v108, v76
	v_fma_f32 v7, v7, v108, v77
	s_and_b64 vcc, exec, s[36:37]
	s_cbranch_vccz .LBB0_569
	s_ashr_i32 s0, s78, 13
	s_ashr_i32 s1, s0, 31
	s_lshl_b64 s[10:11], s[70:71], 5
	s_lshl_b64 s[0:1], s[0:1], 2
	s_add_u32 s0, s0, s10
	v_readlane_b32 s6, v255, 44
	s_addc_u32 s1, s1, s11
	s_lshl_b32 s3, s6, 1
	s_and_b32 s3, s3, 2
	s_or_b32 s0, s0, s3
	v_readlane_b32 s7, v255, 45
	s_or_b64 s[0:1], s[0:1], s[76:77]
	s_lshl_b64 s[0:1], s[0:1], 15
	v_readlane_b32 s6, v252, 33
	v_readlane_b32 s8, v254, 19
	v_readlane_b32 s7, v252, 34
	s_add_u32 s0, s6, s0
	v_readlane_b32 s9, v254, 20
	v_readlane_b32 s84, v254, 24
	v_readlane_b32 s86, v254, 28
	v_readlane_b32 s92, v254, 34
	v_readlane_b32 s94, v254, 36
	v_readlane_b32 s34, v254, 50
	s_addc_u32 s1, s7, s1
	v_lshlrev_b32_e32 v2, 2, v2
	s_mov_b64 s[60:61], s[8:9]
	v_readlane_b32 s90, v254, 63
	v_readlane_b32 s91, v254, 23
	v_readlane_b32 s85, v254, 25
	v_readlane_b32 s87, v254, 29
	v_readlane_b32 s88, v254, 30
	v_readlane_b32 s89, v254, 31
	v_readlane_b32 s93, v254, 35
	v_readlane_b32 s95, v254, 37
	v_readlane_b32 s35, v254, 51
	s_movk_i32 s31, 0x2000
	s_movk_i32 s55, 0x1a00
	s_movk_i32 s97, 0xffb4
	global_store_dwordx4 v2, v[6:9], s[0:1]
	v_readlane_b32 s10, v254, 21
	v_readlane_b32 s11, v254, 22

; __device__ __forceinline__ void ssd_scan(const MixP& C, const int wg, const int nwgs, const int tid) {
;     constexpr int NSC = TP / 64, NQ = BP * 2 * 2 * 2048;
;     const int per = (((NQ + nwgs - 1) / nwgs) + 63) & ~63;
;     const int qi = wg * per + tid;
;     if (tid < per && qi < NQ) {
;         const int e = (qi & 2047) * 4, bgh = __builtin_amdgcn_readfirstlane(qi >> 11), hh = bgh & 1, bg = bgh >> 1;
;         float* dp = C.DS + ((size_t)bg * NSC * 2 + hh) * 8192 + e;
;         const float* ep = C.ESC + (size_t)bg * NSC * 2 + hh;
;         f32x4 s = {0.f, 0.f, 0.f, 0.f};
; #pragma unroll 1
;         for (int h0 = 0; h0 < NSC; h0 += NSC / 2) {
;             f32x4 d[NSC / 2]; float E[NSC / 2];
; #pragma unroll
;             for (int k = 0; k < NSC / 2; ++k) { d[k] = *(const f32x4*)(dp + (size_t)(h0 + k) * 2 * 8192); E[k] = ep[(h0 + k) * 2]; }
.LBB0_604:
	s_lshl_b32 s62, s13, 1
	s_lshl_b32 s92, s13, 14
	s_lshl_b64 s[0:1], s[62:63], 2
	s_add_u32 s94, s9, s0
	s_addc_u32 s95, s3, s1
	s_or_b32 s0, s13, 1
	s_lshl_b32 s62, s0, 1
	s_lshl_b32 s88, s0, 14
	s_lshl_b64 s[0:1], s[62:63], 2
	s_add_u32 s90, s9, s0
	s_addc_u32 s91, s3, s1
	s_or_b32 s0, s13, 2
	s_lshl_b32 s62, s0, 1
	s_lshl_b32 s84, s0, 14
	s_lshl_b64 s[0:1], s[62:63], 2
	s_add_u32 s86, s9, s0
	s_addc_u32 s87, s3, s1
	s_or_b32 s0, s13, 3
	s_lshl_b32 s62, s0, 1
	s_lshl_b32 s80, s0, 14
	s_lshl_b64 s[0:1], s[62:63], 2
	s_add_u32 s82, s9, s0
	s_addc_u32 s83, s3, s1
	s_or_b32 s0, s13, 4
	s_lshl_b32 s62, s0, 1
	s_lshl_b32 s22, s0, 14
	s_lshl_b64 s[0:1], s[62:63], 2
	s_add_u32 s0, s9, s0
	v_cndmask_b32_e64 v3, 0, 1, s[10:11]
	s_addc_u32 s1, s3, s1
	s_or_b32 s10, s13, 5
	s_lshl_b32 s62, s10, 1
	s_lshl_b32 vcc_lo, s10, 14
	s_lshl_b64 s[10:11], s[62:63], 2
	s_add_u32 s30, s9, s10
	s_addc_u32 s31, s3, s11
	s_or_b32 s10, s13, 6
	s_lshl_b32 s62, s10, 1
	s_lshl_b32 s56, s10, 14
	s_lshl_b64 s[10:11], s[62:63], 2
	s_add_u32 s60, s9, s10
	s_addc_u32 s61, s3, s11
	s_or_b32 s10, s13, 7
	s_lshl_b32 s62, s10, 1
	s_lshl_b32 s26, s10, 14
	s_lshl_b64 s[10:11], s[62:63], 2
	s_add_u32 s54, s9, s10
	s_addc_u32 s55, s3, s11
	s_or_b32 s10, s13, 8
	s_lshl_b32 s62, s10, 1
	s_lshl_b32 s16, s10, 14
	s_lshl_b64 s[10:11], s[62:63], 2
	s_add_u32 s18, s9, s10
	s_addc_u32 s19, s3, s11
	s_or_b32 s10, s13, 9
	s_lshl_b32 s62, s10, 1
	s_lshl_b32 s12, s10, 14
	s_lshl_b64 s[10:11], s[62:63], 2
	s_add_u32 s14, s9, s10
	s_addc_u32 s15, s3, s11
	s_or_b32 s10, s13, 10
	s_lshl_b32 s62, s10, 1
	s_mov_b32 s93, s63
	s_lshl_b32 s50, s10, 14
	s_lshl_b64 s[10:11], s[62:63], 2
	v_lshl_add_u64 v[16:17], s[92:93], 2, v[14:15]
	s_add_u32 s52, s9, s10
	global_load_dwordx4 v[10:13], v[16:17], off
	global_load_dword v18, v4, s[94:95]
	s_addc_u32 s53, s3, s11
	s_or_b32 s10, s13, 11
	s_mov_b32 s89, s63
	s_lshl_b32 s62, s10, 1
	v_lshl_add_u64 v[20:21], s[88:89], 2, v[14:15]
	s_lshl_b32 s46, s10, 14
	s_lshl_b64 s[10:11], s[62:63], 2
	global_load_dwordx4 v[20:23], v[20:21], off
	s_nop 0
	global_load_dword v80, v4, s[90:91]
	s_mov_b32 s85, s63
	s_add_u32 s48, s9, s10
	v_lshl_add_u64 v[24:25], s[84:85], 2, v[14:15]
	s_addc_u32 s49, s3, s11
	s_or_b32 s10, s13, 12
	global_load_dwordx4 v[24:27], v[24:25], off
	s_nop 0
	global_load_dword v82, v4, s[86:87]
	s_mov_b32 s81, s63
	s_lshl_b32 s62, s10, 1
	v_lshl_add_u64 v[28:29], s[80:81], 2, v[14:15]
	s_lshl_b32 s42, s10, 14
	s_lshl_b64 s[10:11], s[62:63], 2
	global_load_dwordx4 v[28:31], v[28:29], off
	s_nop 0
	global_load_dword v84, v4, s[82:83]
	s_mov_b32 s23, s63
	s_add_u32 s44, s9, s10
	v_lshl_add_u64 v[32:33], s[22:23], 2, v[14:15]
	s_addc_u32 s45, s3, s11
	s_or_b32 s10, s13, 13
	global_load_dwordx4 v[32:35], v[32:33], off
	s_nop 0
	global_load_dword v86, v4, s[0:1]
	s_mov_b32 vcc_hi, s63
	s_lshl_b32 s62, s10, 1
	v_lshl_add_u64 v[36:37], vcc, 2, v[14:15]
	s_lshl_b32 s38, s10, 14
	s_lshl_b64 s[10:11], s[62:63], 2
	global_load_dwordx4 v[36:39], v[36:37], off
	s_nop 0
	global_load_dword v88, v4, s[30:31]
	s_mov_b32 s57, s63
	s_add_u32 s40, s9, s10
	v_lshl_add_u64 v[40:41], s[56:57], 2, v[14:15]
	s_addc_u32 s41, s3, s11
	s_or_b32 s10, s13, 14
	global_load_dwordx4 v[40:43], v[40:41], off
	s_nop 0
	global_load_dword v90, v4, s[60:61]
	s_mov_b32 s27, s63
	s_lshl_b32 s62, s10, 1
	v_lshl_add_u64 v[44:45], s[26:27], 2, v[14:15]
	s_lshl_b32 s24, s10, 14
	s_lshl_b64 s[10:11], s[62:63], 2
	global_load_dwordx4 v[44:47], v[44:45], off
	s_nop 0
	global_load_dword v92, v4, s[54:55]
	s_mov_b32 s17, s63
	s_add_u32 s34, s9, s10
	v_lshl_add_u64 v[48:49], s[16:17], 2, v[14:15]
	s_addc_u32 s35, s3, s11
	s_or_b32 s11, s13, 15
	global_load_dwordx4 v[48:51], v[48:49], off
	s_nop 0
	global_load_dword v94, v4, s[18:19]
	s_mov_b32 s13, s63
	v_lshl_add_u64 v[52:53], s[12:13], 2, v[14:15]
	global_load_dwordx4 v[52:55], v[52:53], off
	s_nop 0
	global_load_dword v96, v4, s[14:15]
	s_mov_b32 s51, s63
	v_lshl_add_u64 v[56:57], s[50:51], 2, v[14:15]
	global_load_dwordx4 v[56:59], v[56:57], off
	s_nop 0
	global_load_dword v98, v4, s[52:53]
	s_mov_b32 s47, s63
	v_lshl_add_u64 v[60:61], s[46:47], 2, v[14:15]
	global_load_dwordx4 v[60:63], v[60:61], off
	s_nop 0
	global_load_dword v100, v4, s[48:49]
	s_mov_b32 s43, s63
	v_lshl_add_u64 v[64:65], s[42:43], 2, v[14:15]
	global_load_dwordx4 v[64:67], v[64:65], off
	s_nop 0
	global_load_dword v102, v4, s[44:45]
	s_mov_b32 s39, s63
	v_lshl_add_u64 v[68:69], s[38:39], 2, v[14:15]
	s_lshl_b32 s62, s11, 1
	global_load_dwordx4 v[68:71], v[68:69], off
	s_nop 0
	global_load_dword v104, v4, s[40:41]
	s_mov_b32 s25, s63
	s_lshl_b32 s10, s11, 14
	s_lshl_b64 s[20:21], s[62:63], 2
	v_lshl_add_u64 v[72:73], s[24:25], 2, v[14:15]
	s_mov_b32 s11, s63
	s_add_u32 s20, s9, s20
	global_load_dwordx4 v[72:75], v[72:73], off
	s_nop 0
	global_load_dword v106, v4, s[34:35]
	v_lshl_add_u64 v[76:77], s[10:11], 2, v[14:15]
	s_addc_u32 s21, s3, s21
	global_load_dwordx4 v[76:79], v[76:77], off
	s_nop 0
	global_load_dword v108, v4, s[20:21]
	s_mov_b32 s0, 0x10000
	global_store_dwordx4 v[16:17], v[6:9], off
	v_cmp_ne_u32_e64 s[36:37], 1, v3
	s_mov_b32 s13, 16
	s_waitcnt vmcnt(31)
; __device__ __forceinline__ void ssd_scan(const MixP& C, const int wg, const int nwgs, const int tid) {
;     ...
;             for (int k = 0; k < NSC / 2; ++k) { d[k] = *(const f32x4*)(dp + (size_t)(h0 + k) * 2 * 8192); E[k] = ep[(h0 + k) * 2]; }
; #pragma unroll
;             for (int k = 0; k < NSC / 2; ++k) { *(f32x4*)(dp + (size_t)(h0 + k) * 2 * 8192) = s; s = s * E[k] + d[k]; }
;         }
;         const int b = bg >> 1, g = bg & 1;
;         *(f32x4*)(C.out + O_SSMP + (((size_t)C.l * BP + b) * 4 + 2 * g + hh) * 8192 + e) = s;
	v_fma_f32 v6, v6, v18, v10
	v_fma_f32 v7, v7, v18, v11
	v_add_co_u32_e32 v10, vcc, s0, v16
	v_fma_f32 v8, v8, v18, v12
	v_fma_f32 v9, v9, v18, v13
	s_nop 0
	v_addc_co_u32_e32 v11, vcc, 0, v17, vcc
	global_store_dwordx4 v[10:11], v[6:9], off
	v_add_co_u32_e32 v10, vcc, s79, v16
	s_waitcnt vmcnt(30)
	v_fma_f32 v8, v8, v80, v22
	v_fma_f32 v9, v9, v80, v23
	v_fma_f32 v6, v6, v80, v20
	v_fma_f32 v7, v7, v80, v21
	v_addc_co_u32_e32 v11, vcc, 0, v17, vcc
	global_store_dwordx4 v[10:11], v[6:9], off
	v_add_co_u32_e32 v10, vcc, s4, v16
	s_waitcnt vmcnt(29)
	v_fma_f32 v8, v8, v82, v26
	v_fma_f32 v9, v9, v82, v27
	v_fma_f32 v6, v6, v82, v24
	v_fma_f32 v7, v7, v82, v25
	v_addc_co_u32_e32 v11, vcc, 0, v17, vcc
	global_store_dwordx4 v[10:11], v[6:9], off
	v_add_co_u32_e32 v10, vcc, s5, v16
	s_waitcnt vmcnt(28)
	v_fma_f32 v8, v8, v84, v30
	v_fma_f32 v9, v9, v84, v31
	v_fma_f32 v6, v6, v84, v28
	v_fma_f32 v7, v7, v84, v29
	v_addc_co_u32_e32 v11, vcc, 0, v17, vcc
	global_store_dwordx4 v[10:11], v[6:9], off
	v_add_co_u32_e32 v10, vcc, s68, v16
	s_waitcnt vmcnt(27)
	v_fma_f32 v8, v8, v86, v34
	v_fma_f32 v9, v9, v86, v35
	v_fma_f32 v6, v6, v86, v32
	v_fma_f32 v7, v7, v86, v33
	v_addc_co_u32_e32 v11, vcc, 0, v17, vcc
	global_store_dwordx4 v[10:11], v[6:9], off
	v_add_co_u32_e32 v10, vcc, s97, v16
	s_waitcnt vmcnt(26)
	v_fma_f32 v8, v8, v88, v38
	v_fma_f32 v9, v9, v88, v39
	v_fma_f32 v6, v6, v88, v36
	v_fma_f32 v7, v7, v88, v37
	v_addc_co_u32_e32 v11, vcc, 0, v17, vcc
	global_store_dwordx4 v[10:11], v[6:9], off
	v_add_co_u32_e32 v10, vcc, s8, v16
	s_waitcnt vmcnt(25)
	v_fma_f32 v8, v8, v90, v42
	v_fma_f32 v9, v9, v90, v43
	v_fma_f32 v6, v6, v90, v40
	v_fma_f32 v7, v7, v90, v41
	v_addc_co_u32_e32 v11, vcc, 0, v17, vcc
	global_store_dwordx4 v[10:11], v[6:9], off
	v_add_co_u32_e32 v10, vcc, s66, v16
	s_waitcnt vmcnt(24)
	v_fma_f32 v8, v8, v92, v46
	v_fma_f32 v9, v9, v92, v47
	v_fma_f32 v6, v6, v92, v44
	v_fma_f32 v7, v7, v92, v45
	v_addc_co_u32_e32 v11, vcc, 0, v17, vcc
	global_store_dwordx4 v[10:11], v[6:9], off
	v_add_co_u32_e32 v10, vcc, s65, v16
	s_waitcnt vmcnt(23)
	v_fma_f32 v8, v8, v94, v50
	v_fma_f32 v9, v9, v94, v51
	v_fma_f32 v6, v6, v94, v48
	v_fma_f32 v7, v7, v94, v49
	v_addc_co_u32_e32 v11, vcc, 0, v17, vcc
	global_store_dwordx4 v[10:11], v[6:9], off
	v_add_co_u32_e32 v10, vcc, s67, v16
	s_waitcnt vmcnt(22)
	v_fma_f32 v8, v8, v96, v54
	v_fma_f32 v9, v9, v96, v55
	v_fma_f32 v6, v6, v96, v52
	v_fma_f32 v7, v7, v96, v53
	v_addc_co_u32_e32 v11, vcc, 0, v17, vcc
	s_mov_b32 s0, 0xb0000
	global_store_dwordx4 v[10:11], v[6:9], off
	v_add_co_u32_e32 v10, vcc, s0, v16
	s_waitcnt vmcnt(21)
	v_fma_f32 v8, v8, v98, v58
	v_fma_f32 v9, v9, v98, v59
	v_fma_f32 v6, v6, v98, v56
	v_fma_f32 v7, v7, v98, v57
	v_addc_co_u32_e32 v11, vcc, 0, v17, vcc
	s_mov_b32 s0, 0xc0000
	global_store_dwordx4 v[10:11], v[6:9], off
	v_add_co_u32_e32 v10, vcc, s0, v16
	s_waitcnt vmcnt(20)
	v_fma_f32 v8, v8, v100, v62
	v_fma_f32 v9, v9, v100, v63
	v_fma_f32 v6, v6, v100, v60
	v_fma_f32 v7, v7, v100, v61
	v_addc_co_u32_e32 v11, vcc, 0, v17, vcc
	s_mov_b32 s0, 0xd0000
	global_store_dwordx4 v[10:11], v[6:9], off
	v_add_co_u32_e32 v10, vcc, s0, v16
	s_waitcnt vmcnt(19)
	v_fma_f32 v8, v8, v102, v66
	v_fma_f32 v9, v9, v102, v67
	v_fma_f32 v6, v6, v102, v64
	v_fma_f32 v7, v7, v102, v65
	v_addc_co_u32_e32 v11, vcc, 0, v17, vcc
	s_mov_b32 s0, 0xe0000
	global_store_dwordx4 v[10:11], v[6:9], off
	v_add_co_u32_e32 v10, vcc, s0, v16
	s_waitcnt vmcnt(18)
	v_fma_f32 v8, v8, v104, v70
	v_fma_f32 v9, v9, v104, v71
	v_fma_f32 v6, v6, v104, v68
	v_fma_f32 v7, v7, v104, v69
	v_addc_co_u32_e32 v11, vcc, 0, v17, vcc
	s_mov_b32 s0, 0xf0000
	global_store_dwordx4 v[10:11], v[6:9], off
	v_add_co_u32_e32 v10, vcc, s0, v16
	s_waitcnt vmcnt(17)
	v_fma_f32 v8, v8, v106, v74
	v_fma_f32 v9, v9, v106, v75
	v_fma_f32 v6, v6, v106, v72
	v_fma_f32 v7, v7, v106, v73
	v_addc_co_u32_e32 v11, vcc, 0, v17, vcc
	global_store_dwordx4 v[10:11], v[6:9], off
	s_mov_b64 s[10:11], 0
	s_and_b64 vcc, exec, s[36:37]
	s_waitcnt vmcnt(16)
	v_fma_f32 v8, v8, v108, v78
	v_fma_f32 v9, v9, v108, v79
	v_fma_f32 v6, v6, v108, v76
	v_fma_f32 v7, v7, v108, v77
	s_cbranch_vccz .LBB0_604
	s_ashr_i32 s0, s75, 13
	s_ashr_i32 s1, s0, 31
	s_lshl_b64 s[10:11], s[70:71], 5
	s_lshl_b64 s[0:1], s[0:1], 2
	s_add_u32 s0, s0, s10
	s_addc_u32 s1, s1, s11
	s_lshl_b32 s3, s78, 1
	s_and_b32 s3, s3, 2
	s_or_b32 s0, s0, s3
	s_or_b64 s[0:1], s[0:1], s[76:77]
	s_lshl_b64 s[0:1], s[0:1], 15
	v_readlane_b32 s4, v252, 33
	v_readlane_b32 s8, v254, 19
	v_readlane_b32 s5, v252, 34
	s_add_u32 s0, s4, s0
	v_readlane_b32 s9, v254, 20
	v_readlane_b32 s84, v254, 24
	v_readlane_b32 s86, v254, 28
	v_readlane_b32 s92, v254, 34
	v_readlane_b32 s94, v254, 36
	v_readlane_b32 s34, v254, 50
	s_addc_u32 s1, s5, s1
	v_lshlrev_b32_e32 v2, 2, v2
	s_mov_b64 s[60:61], s[8:9]
	v_readlane_b32 s90, v254, 63
	v_readlane_b32 s91, v254, 23
	v_readlane_b32 s85, v254, 25
	v_readlane_b32 s87, v254, 29
	v_readlane_b32 s88, v254, 30
	v_readlane_b32 s89, v254, 31
	v_readlane_b32 s93, v254, 35
	v_readlane_b32 s95, v254, 37
	v_readlane_b32 s35, v254, 51
	s_movk_i32 s31, 0x2000
	s_movk_i32 s55, 0x1a00
	s_movk_i32 s97, 0xffb4
	global_store_dwordx4 v2, v[6:9], s[0:1]
	v_readlane_b32 s10, v254, 21
	v_readlane_b32 s11, v254, 22

; __device__ __forceinline__ float silu_f(float x) { return x * __builtin_amdgcn_rcpf(1.0f + __expf(-x)); }
; __device__ __forceinline__ float silu_f(float x) { return x * __builtin_amdgcn_rcpf(1.0f + __expf(-x)); }
; __device__ __forceinline__ void conv_phase(const MixP& C, const int G, const int tid) {
;     ...
;             for (int i = 0; i < 11; ++i) { int r = row0 - 3 + i; if (head && i < 3) r = row0; xr[i] = *(const v4u*)(C.P + (size_t)r * NINP + PC_XBC + ch0); }
;             f32x4 st[3][2];
; #pragma unroll
;             for (int r = 0; r < 3; ++r) { st[r][0] = (f32x4){0.f, 0.f, 0.f, 0.f}; st[r][1] = st[r][0]; }
;             if (smp) {
; #pragma unroll
;                 for (int r = 0; r < 3; ++r) { st[r][0] = *(const f32x4*)(C.s_conv + ((size_t)bsm * 3 + r) * 768 + ch0); st[r][1] = *(const f32x4*)(C.s_conv + ((size_t)bsm * 3 + r) * 768 + ch0 + 4); }
;             }
;             float wt[4][8], bs[8];
; #pragma unroll
;             for (int j = 0; j < 4; ++j) { const f32x4 wa = *(const f32x4*)(C.conv_w + j * 768 + ch0), wb = *(const f32x4*)(C.conv_w + j * 768 + ch0 + 4);
; #pragma unroll
;                 for (int c = 0; c < 4; ++c) { wt[j][c] = wa[c]; wt[j][4 + c] = wb[c]; } }
;             { const f32x4 wa = *(const f32x4*)(C.conv_b + ch0), wb = *(const f32x4*)(C.conv_b + ch0 + 4);
; #pragma unroll
;               for (int c = 0; c < 4; ++c) { bs[c] = wa[c]; bs[4 + c] = wb[c]; } }
;             float p3[8], p2[8], p1[8];
; #pragma unroll
;             for (int c = 0; c < 8; ++c) { p3[c] = head ? st[0][c >> 2][c & 3] : bfe(xr[0], c); p2[c] = head ? st[1][c >> 2][c & 3] : bfe(xr[1], c); p1[c] = head ? st[2][c >> 2][c & 3] : bfe(xr[2], c); }
; #pragma unroll
;             for (int et = 0; et < 8; ++et) {
;                 float val[8];
; #pragma unroll
;                 for (int c = 0; c < 8; ++c) { const float cur = bfe(xr[et + 3], c);
;                     val[c] = silu_f(bs[c] + wt[0][c] * p3[c] + wt[1][c] * p2[c] + wt[2][c] * p1[c] + wt[3][c] * cur); p3[c] = p2[c]; p2[c] = p1[c]; p1[c] = cur; }
;                 v4u wv; wv.x = cvtpk(val[0], val[1]); wv.y = cvtpk(val[2], val[3]); wv.z = cvtpk(val[4], val[5]); wv.w = cvtpk(val[6], val[7]);
;                 *(v4u*)(C.XC + (size_t)(row0 + et) * 768 + ch0) = wv;
.LBB0_627:
	s_or_b64 exec, exec, s[10:11]
	v_lshlrev_b64 v[26:27], 2, v[10:11]
	v_lshl_add_u64 v[22:23], s[8:9], 0, v[26:27]
	s_movk_i32 s3, 0x1000
	s_mov_b64 s[10:11], 0x1800
	v_add_co_u32_e32 v20, vcc, s3, v22
	v_lshl_add_u64 v[18:19], v[22:23], 0, s[10:11]
	s_nop 0
	v_addc_co_u32_e32 v21, vcc, 0, v23, vcc
	s_mov_b64 s[10:11], 0x2400
	global_load_dwordx4 v[10:13], v[22:23], off offset:16
	global_load_dwordx4 v[34:37], v[22:23], off
	global_load_dwordx4 v[14:17], v[22:23], off offset:3088
	global_load_dwordx4 v[38:41], v[22:23], off offset:3072
	v_lshl_add_u64 v[24:25], v[22:23], 0, s[10:11]
	v_add_co_u32_e32 v22, vcc, s31, v22
	v_lshl_add_u64 v[50:51], s[20:21], 0, v[26:27]
	s_nop 0
	v_addc_co_u32_e32 v23, vcc, 0, v23, vcc
	global_load_dwordx4 v[42:45], v[20:21], off offset:2048
	s_nop 0
	global_load_dwordx4 v[18:21], v[18:19], off offset:16
	s_nop 0
	global_load_dwordx4 v[46:49], v[22:23], off offset:1024
	s_nop 0
	global_load_dwordx4 v[22:25], v[24:25], off offset:16
	s_nop 0
	global_load_dwordx4 v[26:29], v[50:51], off offset:16
	s_nop 0
	global_load_dwordx4 v[50:53], v[50:51], off
	s_waitcnt vmcnt(20)
	v_lshlrev_b32_e32 v116, 16, v78
	v_and_b32_e32 v78, 0xffff0000, v78
	s_waitcnt vmcnt(15)
	v_cndmask_b32_e64 v127, v103, v78, s[0:1]
	v_lshlrev_b32_e32 v78, 16, v74
	v_and_b32_e32 v74, 0xffff0000, v74
	v_cndmask_b32_e64 v126, v102, v116, s[0:1]
	s_waitcnt vmcnt(13)
	v_cndmask_b32_e64 v117, v107, v74, s[0:1]
	v_cndmask_b32_e64 v116, v106, v78, s[0:1]
	v_lshlrev_b32_e32 v74, 16, v86
	v_and_b32_e32 v78, 0xffff0000, v86
	s_waitcnt vmcnt(11)
	v_cndmask_b32_e64 v107, v111, v78, s[0:1]
	v_cndmask_b32_e64 v106, v110, v74, s[0:1]
	v_lshlrev_b32_e32 v102, 16, v82
	v_and_b32_e32 v103, 0xffff0000, v82
	v_and_b32_e32 v78, 0xffff0000, v79
	v_cndmask_b32_e64 v105, v105, v78, s[0:1]
	v_lshlrev_b32_e32 v78, 16, v83
	v_add_u32_e32 v3, s14, v3
	v_add_u32_e32 v2, s15, v2
	s_waitcnt vmcnt(0)
	v_fma_f32 v110, v126, v34, v50
	v_fma_f32 v111, v127, v35, v51
	s_nop 0
	v_fma_f32 v110, v116, v38, v110
	v_fma_f32 v111, v117, v39, v111
	s_nop 0
	v_fma_f32 v110, v106, v42, v110
	v_fma_f32 v111, v107, v43, v111
	s_nop 0
	v_fma_f32 v110, v46, v102, v110
	v_fma_f32 v111, v47, v103, v111
	s_nop 0
	v_mul_f32_e32 v74, 0xbfb8aa3b, v110
	v_exp_f32_e32 v74, v74
	s_nop 0
	v_add_f32_e32 v74, 1.0, v74
	v_rcp_f32_e32 v126, v74
	v_mul_f32_e32 v74, 0xbfb8aa3b, v111
	v_exp_f32_e32 v74, v74
	s_nop 0
	v_add_f32_e32 v74, 1.0, v74
	v_rcp_f32_e32 v127, v74
	v_lshlrev_b32_e32 v74, 16, v79
	v_cndmask_b32_e64 v104, v104, v74, s[0:1]
	v_lshlrev_b32_e32 v74, 16, v75
	v_and_b32_e32 v75, 0xffff0000, v75
	v_cndmask_b32_e64 v109, v109, v75, s[0:1]
	v_cndmask_b32_e64 v108, v108, v74, s[0:1]
	v_lshlrev_b32_e32 v74, 16, v87
	v_and_b32_e32 v75, 0xffff0000, v87
	v_cndmask_b32_e64 v87, v113, v75, s[0:1]
	v_cndmask_b32_e64 v86, v112, v74, s[0:1]
	v_fma_f32 v74, v104, v36, v52
	v_fma_f32 v75, v105, v37, v53
	v_and_b32_e32 v79, 0xffff0000, v83
	v_fma_f32 v74, v108, v40, v74
	v_fma_f32 v75, v109, v41, v75
	v_mul_f32_e32 v110, v110, v126
	v_mul_f32_e32 v111, v111, v127
	v_fma_f32 v74, v86, v44, v74
	v_fma_f32 v75, v87, v45, v75
	s_nop 0
	v_fma_f32 v74, v48, v78, v74
	v_fma_f32 v75, v49, v79, v75
	s_nop 0
	v_mul_f32_e32 v82, 0xbfb8aa3b, v74
	v_mul_f32_e32 v83, 0xbfb8aa3b, v75
	v_exp_f32_e32 v82, v82
	v_exp_f32_e32 v83, v83
	v_add_f32_e32 v82, 1.0, v82
	v_add_f32_e32 v83, 1.0, v83
	v_rcp_f32_e32 v82, v82
	v_rcp_f32_e32 v83, v83
	s_nop 0
	v_mul_f32_e32 v74, v74, v82
	v_mul_f32_e32 v75, v75, v83
	v_lshlrev_b32_e32 v82, 16, v80
	v_and_b32_e32 v80, 0xffff0000, v80
	v_cndmask_b32_e64 v113, v91, v80, s[0:1]
	v_cndmask_b32_e64 v112, v90, v82, s[0:1]
	v_lshlrev_b32_e32 v80, 16, v76
	v_and_b32_e32 v76, 0xffff0000, v76
	v_cndmask_b32_e64 v91, v95, v76, s[0:1]
	v_cndmask_b32_e64 v90, v94, v80, s[0:1]
	v_lshlrev_b32_e32 v76, 16, v88
	v_and_b32_e32 v80, 0xffff0000, v88
	v_fma_f32 v94, v112, v10, v26
	v_fma_f32 v95, v113, v11, v27
	v_cndmask_b32_e64 v105, v99, v80, s[0:1]
	v_cndmask_b32_e64 v104, v98, v76, s[0:1]
	v_fma_f32 v94, v90, v14, v94
	v_fma_f32 v95, v91, v15, v95
	v_lshlrev_b32_e32 v82, 16, v84
	v_and_b32_e32 v83, 0xffff0000, v84
	v_fma_f32 v94, v104, v18, v94
	v_fma_f32 v95, v105, v19, v95
	v_and_b32_e32 v80, 0xffff0000, v81
	v_fma_f32 v94, v22, v82, v94
	v_fma_f32 v95, v23, v83, v95
	v_cndmask_b32_e64 v93, v93, v80, s[0:1]
	v_mul_f32_e32 v76, 0xbfb8aa3b, v94
	v_exp_f32_e32 v76, v76
	s_nop 0
	v_add_f32_e32 v76, 1.0, v76
	v_rcp_f32_e32 v98, v76
	v_mul_f32_e32 v76, 0xbfb8aa3b, v95
	v_exp_f32_e32 v76, v76
	s_nop 0
	v_add_f32_e32 v76, 1.0, v76
	v_rcp_f32_e32 v99, v76
	v_lshlrev_b32_e32 v76, 16, v81
	v_cndmask_b32_e64 v92, v92, v76, s[0:1]
	v_lshlrev_b32_e32 v76, 16, v77
	v_and_b32_e32 v77, 0xffff0000, v77
	v_cndmask_b32_e64 v113, v97, v77, s[0:1]
	v_cndmask_b32_e64 v112, v96, v76, s[0:1]
	v_lshlrev_b32_e32 v76, 16, v89
	v_and_b32_e32 v77, 0xffff0000, v89
	v_cndmask_b32_e64 v81, v101, v77, s[0:1]
	v_cndmask_b32_e64 v80, v100, v76, s[0:1]
	v_lshlrev_b32_e32 v76, 16, v85
	v_and_b32_e32 v77, 0xffff0000, v85
	v_fma_f32 v84, v92, v12, v28
	v_fma_f32 v85, v93, v13, v29
	v_mul_f32_e32 v94, v94, v98
	v_mul_f32_e32 v95, v95, v99
	v_fma_f32 v84, v112, v16, v84
	v_fma_f32 v85, v113, v17, v85
	v_cvt_pk_bf16_f32 v93, v74, v75
	v_fma_f32 v84, v80, v20, v84
	v_fma_f32 v85, v81, v21, v85
	v_mov_b64_e32 v[74:75], s[60:61]
	v_fma_f32 v84, v24, v76, v84
	v_fma_f32 v85, v25, v77, v85
	v_cvt_pk_bf16_f32 v94, v94, v95
	v_mul_f32_e32 v88, 0xbfb8aa3b, v84
	v_mul_f32_e32 v89, 0xbfb8aa3b, v85
	v_exp_f32_e32 v88, v88
	v_exp_f32_e32 v89, v89
	v_cvt_pk_bf16_f32 v92, v110, v111
	v_lshlrev_b32_e32 v98, 16, v70
	v_add_f32_e32 v88, 1.0, v88
; __device__ __forceinline__ float silu_f(float x) { return x * __builtin_amdgcn_rcpf(1.0f + __expf(-x)); }
; __device__ __forceinline__ float silu_f(float x) { return x * __builtin_amdgcn_rcpf(1.0f + __expf(-x)); }
; __device__ __forceinline__ unsigned cvtpk(float lo, float hi) { const f32x2v v = {lo, hi}; return __builtin_bit_cast(unsigned, __builtin_convertvector(v, bf16x2v)); }
; __device__ __forceinline__ void conv_phase(const MixP& C, const int G, const int tid) {
;     ...
; #pragma unroll
;             for (int c = 0; c < 8; ++c) { p3[c] = head ? st[0][c >> 2][c & 3] : bfe(xr[0], c); p2[c] = head ? st[1][c >> 2][c & 3] : bfe(xr[1], c); p1[c] = head ? st[2][c >> 2][c & 3] : bfe(xr[2], c); }
; #pragma unroll
;             for (int et = 0; et < 8; ++et) {
;                 float val[8];
; #pragma unroll
;                 for (int c = 0; c < 8; ++c) { const float cur = bfe(xr[et + 3], c);
;                     val[c] = silu_f(bs[c] + wt[0][c] * p3[c] + wt[1][c] * p2[c] + wt[2][c] * p1[c] + wt[3][c] * cur); p3[c] = p2[c]; p2[c] = p1[c]; p1[c] = cur; }
;                 v4u wv; wv.x = cvtpk(val[0], val[1]); wv.y = cvtpk(val[2], val[3]); wv.z = cvtpk(val[4], val[5]); wv.w = cvtpk(val[6], val[7]);
;                 *(v4u*)(C.XC + (size_t)(row0 + et) * 768 + ch0) = wv;
;             }
	v_add_f32_e32 v89, 1.0, v89
	v_rcp_f32_e32 v88, v88
	v_rcp_f32_e32 v89, v89
	v_and_b32_e32 v99, 0xffff0000, v70
	v_lshlrev_b32_e32 v96, 16, v71
	v_and_b32_e32 v97, 0xffff0000, v71
	v_mul_f32_e32 v84, v84, v88
	v_mul_f32_e32 v85, v85, v89
	s_nop 0
	v_cvt_pk_bf16_f32 v95, v84, v85
	v_mad_i64_i32 v[84:85], s[0:1], v124, s18, v[74:75]
	v_lshl_add_u64 v[84:85], v[84:85], 0, v[114:115]
	global_store_dwordx4 v[84:85], v[92:95], off
	v_fma_f32 v84, v116, v34, v50
	v_fma_f32 v85, v117, v35, v51
	s_nop 0
	v_fma_f32 v84, v106, v38, v84
	v_fma_f32 v85, v107, v39, v85
	v_lshlrev_b32_e32 v94, 16, v72
	v_fma_f32 v84, v42, v102, v84
	v_fma_f32 v85, v43, v103, v85
	v_and_b32_e32 v95, 0xffff0000, v72
	v_fma_f32 v84, v46, v98, v84
	v_fma_f32 v85, v47, v99, v85
	v_lshlrev_b32_e32 v92, 16, v73
	v_mul_f32_e32 v70, 0xbfb8aa3b, v84
	v_exp_f32_e32 v70, v70
	v_and_b32_e32 v93, 0xffff0000, v73
	v_add_f32_e32 v70, 1.0, v70
	v_rcp_f32_e32 v88, v70
	v_mul_f32_e32 v70, 0xbfb8aa3b, v85
	v_exp_f32_e32 v70, v70
	s_nop 0
	v_add_f32_e32 v70, 1.0, v70
	v_rcp_f32_e32 v89, v70
	v_fma_f32 v70, v108, v36, v52
	v_fma_f32 v71, v109, v37, v53
	v_mul_f32_e32 v84, v84, v88
	v_mul_f32_e32 v85, v85, v89
	v_fma_f32 v70, v86, v40, v70
	v_fma_f32 v71, v87, v41, v71
	s_nop 0
	v_fma_f32 v70, v44, v78, v70
	v_fma_f32 v71, v45, v79, v71
	s_nop 0
	v_fma_f32 v70, v48, v96, v70
	v_fma_f32 v71, v49, v97, v71
	s_nop 0
	v_mul_f32_e32 v88, 0xbfb8aa3b, v70
	v_mul_f32_e32 v89, 0xbfb8aa3b, v71
	v_exp_f32_e32 v88, v88
	v_exp_f32_e32 v89, v89
	v_add_f32_e32 v88, 1.0, v88
	v_add_f32_e32 v89, 1.0, v89
	v_rcp_f32_e32 v88, v88
	v_rcp_f32_e32 v89, v89
	s_nop 0
	v_mul_f32_e32 v88, v70, v88
	v_mul_f32_e32 v89, v71, v89
	v_fma_f32 v70, v90, v10, v26
	v_fma_f32 v71, v91, v11, v27
	s_nop 0
	v_fma_f32 v70, v104, v14, v70
	v_fma_f32 v71, v105, v15, v71
	s_nop 0
	v_fma_f32 v70, v18, v82, v70
	v_fma_f32 v71, v19, v83, v71
	s_nop 0
	v_fma_f32 v70, v22, v94, v70
	v_fma_f32 v71, v23, v95, v71
	s_nop 0
	v_mul_f32_e32 v72, 0xbfb8aa3b, v70
	v_exp_f32_e32 v72, v72
	s_nop 0
	v_add_f32_e32 v72, 1.0, v72
	v_rcp_f32_e32 v90, v72
	v_mul_f32_e32 v72, 0xbfb8aa3b, v71
	v_exp_f32_e32 v72, v72
	s_nop 0
	v_add_f32_e32 v72, 1.0, v72
	v_rcp_f32_e32 v91, v72
	s_nop 0
	v_mul_f32_e32 v90, v70, v90
	v_mul_f32_e32 v91, v71, v91
	v_fma_f32 v70, v112, v12, v28
	v_fma_f32 v71, v113, v13, v29
	s_nop 0
	v_fma_f32 v70, v80, v16, v70
	v_fma_f32 v71, v81, v17, v71
	s_nop 0
	v_fma_f32 v70, v20, v76, v70
	v_fma_f32 v71, v21, v77, v71
	s_nop 0
	v_fma_f32 v70, v24, v92, v70
	v_fma_f32 v71, v25, v93, v71
	s_nop 0
	v_mul_f32_e32 v72, 0xbfb8aa3b, v70
	v_mul_f32_e32 v73, 0xbfb8aa3b, v71
	v_exp_f32_e32 v72, v72
	v_exp_f32_e32 v73, v73
	v_add_f32_e32 v72, 1.0, v72
	v_add_f32_e32 v73, 1.0, v73
	v_rcp_f32_e32 v72, v72
	v_rcp_f32_e32 v73, v73
	s_nop 0
	v_mul_f32_e32 v100, v70, v72
	v_mul_f32_e32 v101, v71, v73
	v_cvt_pk_bf16_f32 v70, v84, v85
	v_mad_i64_i32 v[84:85], s[0:1], v123, s18, v[74:75]
	v_cvt_pk_bf16_f32 v71, v88, v89
	v_cvt_pk_bf16_f32 v72, v90, v91
	v_cvt_pk_bf16_f32 v73, v100, v101
	v_lshl_add_u64 v[84:85], v[84:85], 0, v[114:115]
	global_store_dwordx4 v[84:85], v[70:73], off
	v_lshlrev_b32_e32 v90, 16, v66
	v_and_b32_e32 v91, 0xffff0000, v66
	v_fma_f32 v70, v106, v34, v50
	v_fma_f32 v71, v107, v35, v51
	v_lshlrev_b32_e32 v88, 16, v67
	v_fma_f32 v70, v38, v102, v70
	v_fma_f32 v71, v39, v103, v71
	v_and_b32_e32 v89, 0xffff0000, v67
	v_fma_f32 v70, v42, v98, v70
	v_fma_f32 v71, v43, v99, v71
	s_nop 0
	v_fma_f32 v70, v46, v90, v70
	v_fma_f32 v71, v47, v91, v71
	s_nop 0
	v_mul_f32_e32 v66, 0xbfb8aa3b, v70
	v_exp_f32_e32 v66, v66
	s_nop 0
	v_add_f32_e32 v66, 1.0, v66
	v_rcp_f32_e32 v72, v66
	v_mul_f32_e32 v66, 0xbfb8aa3b, v71
	v_exp_f32_e32 v66, v66
	s_nop 0
	v_add_f32_e32 v66, 1.0, v66
	v_rcp_f32_e32 v73, v66
	v_fma_f32 v66, v86, v36, v52
	v_fma_f32 v67, v87, v37, v53
	v_lshlrev_b32_e32 v86, 16, v68
	v_fma_f32 v66, v40, v78, v66
	v_fma_f32 v67, v41, v79, v67
	v_mul_f32_e32 v70, v70, v72
	v_mul_f32_e32 v71, v71, v73
	v_fma_f32 v66, v44, v96, v66
	v_fma_f32 v67, v45, v97, v67
	v_and_b32_e32 v87, 0xffff0000, v68
	v_fma_f32 v66, v48, v88, v66
	v_fma_f32 v67, v49, v89, v67
	s_nop 0
	v_mul_f32_e32 v72, 0xbfb8aa3b, v66
	v_mul_f32_e32 v73, 0xbfb8aa3b, v67
	v_exp_f32_e32 v72, v72
	v_exp_f32_e32 v73, v73
	v_add_f32_e32 v72, 1.0, v72
	v_add_f32_e32 v73, 1.0, v73
	v_rcp_f32_e32 v72, v72
	v_rcp_f32_e32 v73, v73
	s_nop 0
	v_mul_f32_e32 v72, v66, v72
	v_mul_f32_e32 v73, v67, v73
	v_fma_f32 v66, v104, v10, v26
	v_fma_f32 v67, v105, v11, v27
	s_nop 0
	v_fma_f32 v66, v14, v82, v66
	v_fma_f32 v67, v15, v83, v67
	s_nop 0
	v_fma_f32 v66, v18, v94, v66
	v_fma_f32 v67, v19, v95, v67
	s_nop 0
	v_fma_f32 v66, v22, v86, v66
	v_fma_f32 v67, v23, v87, v67
	s_nop 0
	v_mul_f32_e32 v68, 0xbfb8aa3b, v66
	v_exp_f32_e32 v68, v68
	s_nop 0
	v_add_f32_e32 v68, 1.0, v68
	v_rcp_f32_e32 v84, v68
	v_mul_f32_e32 v68, 0xbfb8aa3b, v67
	v_exp_f32_e32 v68, v68
	s_nop 0
	v_add_f32_e32 v68, 1.0, v68
	v_rcp_f32_e32 v85, v68
	s_nop 0
	v_mul_f32_e32 v100, v66, v84
	v_mul_f32_e32 v101, v67, v85
	v_fma_f32 v66, v80, v12, v28
	v_fma_f32 v67, v81, v13, v29
	v_lshlrev_b32_e32 v84, 16, v69
	v_fma_f32 v66, v16, v76, v66
	v_fma_f32 v67, v17, v77, v67
	v_and_b32_e32 v85, 0xffff0000, v69
	v_fma_f32 v66, v20, v92, v66
	v_fma_f32 v67, v21, v93, v67
	s_nop 0
	v_fma_f32 v66, v24, v84, v66
	v_fma_f32 v67, v25, v85, v67
	s_nop 0
	v_mul_f32_e32 v68, 0xbfb8aa3b, v66
	v_mul_f32_e32 v69, 0xbfb8aa3b, v67
	v_exp_f32_e32 v68, v68
	v_exp_f32_e32 v69, v69
	v_add_f32_e32 v68, 1.0, v68
	v_add_f32_e32 v69, 1.0, v69
	v_rcp_f32_e32 v68, v68
	v_rcp_f32_e32 v69, v69
	s_nop 0
	v_mul_f32_e32 v80, v66, v68
	v_mul_f32_e32 v81, v67, v69
; __device__ __forceinline__ float silu_f(float x) { return x * __builtin_amdgcn_rcpf(1.0f + __expf(-x)); }
; __device__ __forceinline__ float silu_f(float x) { return x * __builtin_amdgcn_rcpf(1.0f + __expf(-x)); }
; __device__ __forceinline__ unsigned cvtpk(float lo, float hi) { const f32x2v v = {lo, hi}; return __builtin_bit_cast(unsigned, __builtin_convertvector(v, bf16x2v)); }
; __device__ __forceinline__ void conv_phase(const MixP& C, const int G, const int tid) {
;     ...
;             for (int c = 0; c < 8; ++c) { p3[c] = head ? st[0][c >> 2][c & 3] : bfe(xr[0], c); p2[c] = head ? st[1][c >> 2][c & 3] : bfe(xr[1], c); p1[c] = head ? st[2][c >> 2][c & 3] : bfe(xr[2], c); }
; #pragma unroll
;             for (int et = 0; et < 8; ++et) {
;                 float val[8];
; #pragma unroll
;                 for (int c = 0; c < 8; ++c) { const float cur = bfe(xr[et + 3], c);
;                     val[c] = silu_f(bs[c] + wt[0][c] * p3[c] + wt[1][c] * p2[c] + wt[2][c] * p1[c] + wt[3][c] * cur); p3[c] = p2[c]; p2[c] = p1[c]; p1[c] = cur; }
;                 v4u wv; wv.x = cvtpk(val[0], val[1]); wv.y = cvtpk(val[2], val[3]); wv.z = cvtpk(val[4], val[5]); wv.w = cvtpk(val[6], val[7]);
;                 *(v4u*)(C.XC + (size_t)(row0 + et) * 768 + ch0) = wv;
;             }
	v_cvt_pk_bf16_f32 v66, v70, v71
	v_mad_i64_i32 v[70:71], s[0:1], v122, s18, v[74:75]
	v_cvt_pk_bf16_f32 v67, v72, v73
	v_cvt_pk_bf16_f32 v68, v100, v101
	v_cvt_pk_bf16_f32 v69, v80, v81
	v_lshl_add_u64 v[70:71], v[70:71], 0, v[114:115]
	global_store_dwordx4 v[70:71], v[66:69], off
	v_lshlrev_b32_e32 v80, 16, v62
	v_and_b32_e32 v81, 0xffff0000, v62
	v_fma_f32 v66, v34, v102, v50
	v_fma_f32 v67, v35, v103, v51
	v_lshlrev_b32_e32 v72, 16, v63
	v_fma_f32 v66, v38, v98, v66
	v_fma_f32 v67, v39, v99, v67
	v_and_b32_e32 v73, 0xffff0000, v63
	v_fma_f32 v66, v42, v90, v66
	v_fma_f32 v67, v43, v91, v67
	v_lshlrev_b32_e32 v70, 16, v64
	v_fma_f32 v66, v46, v80, v66
	v_fma_f32 v67, v47, v81, v67
	v_and_b32_e32 v71, 0xffff0000, v64
	v_mul_f32_e32 v62, 0xbfb8aa3b, v66
	v_exp_f32_e32 v62, v62
	s_nop 0
	v_add_f32_e32 v62, 1.0, v62
	v_rcp_f32_e32 v68, v62
	v_mul_f32_e32 v62, 0xbfb8aa3b, v67
	v_exp_f32_e32 v62, v62
	s_nop 0
	v_add_f32_e32 v62, 1.0, v62
	v_rcp_f32_e32 v69, v62
	v_fma_f32 v62, v36, v78, v52
	v_fma_f32 v63, v37, v79, v53
	v_mul_f32_e32 v66, v66, v68
	v_mul_f32_e32 v67, v67, v69
	v_fma_f32 v62, v40, v96, v62
	v_fma_f32 v63, v41, v97, v63
	s_nop 0
	v_fma_f32 v62, v44, v88, v62
	v_fma_f32 v63, v45, v89, v63
	s_nop 0
	v_fma_f32 v62, v48, v72, v62
	v_fma_f32 v63, v49, v73, v63
	s_nop 0
	v_mul_f32_e32 v68, 0xbfb8aa3b, v62
	v_mul_f32_e32 v69, 0xbfb8aa3b, v63
	v_exp_f32_e32 v68, v68
	v_exp_f32_e32 v69, v69
	v_add_f32_e32 v68, 1.0, v68
	v_add_f32_e32 v69, 1.0, v69
	v_rcp_f32_e32 v68, v68
	v_rcp_f32_e32 v69, v69
	s_nop 0
	v_mul_f32_e32 v78, v62, v68
	v_mul_f32_e32 v79, v63, v69
	v_fma_f32 v62, v10, v82, v26
	v_fma_f32 v63, v11, v83, v27
	s_nop 0
	v_fma_f32 v62, v14, v94, v62
	v_fma_f32 v63, v15, v95, v63
	s_nop 0
	v_fma_f32 v62, v18, v86, v62
	v_fma_f32 v63, v19, v87, v63
	s_nop 0
	v_fma_f32 v62, v22, v70, v62
	v_fma_f32 v63, v23, v71, v63
	s_nop 0
	v_mul_f32_e32 v64, 0xbfb8aa3b, v62
	v_exp_f32_e32 v64, v64
	s_nop 0
	v_add_f32_e32 v64, 1.0, v64
	v_rcp_f32_e32 v68, v64
	v_mul_f32_e32 v64, 0xbfb8aa3b, v63
	v_exp_f32_e32 v64, v64
	s_nop 0
	v_add_f32_e32 v64, 1.0, v64
	v_rcp_f32_e32 v69, v64
	s_nop 0
	v_mul_f32_e32 v82, v62, v68
	v_mul_f32_e32 v83, v63, v69
	v_fma_f32 v62, v12, v76, v28
	v_fma_f32 v63, v13, v77, v29
	v_lshlrev_b32_e32 v68, 16, v65
	v_fma_f32 v62, v16, v92, v62
	v_fma_f32 v63, v17, v93, v63
	v_and_b32_e32 v69, 0xffff0000, v65
	v_fma_f32 v62, v20, v84, v62
	v_fma_f32 v63, v21, v85, v63
	s_nop 0
	v_fma_f32 v62, v24, v68, v62
	v_fma_f32 v63, v25, v69, v63
	s_nop 0
	v_mul_f32_e32 v64, 0xbfb8aa3b, v62
	v_mul_f32_e32 v65, 0xbfb8aa3b, v63
	v_exp_f32_e32 v64, v64
	v_exp_f32_e32 v65, v65
	v_add_f32_e32 v64, 1.0, v64
	v_add_f32_e32 v65, 1.0, v65
	v_rcp_f32_e32 v64, v64
	v_rcp_f32_e32 v65, v65
	s_nop 0
	v_mul_f32_e32 v76, v62, v64
	v_mul_f32_e32 v77, v63, v65
	v_cvt_pk_bf16_f32 v62, v66, v67
	v_mad_i64_i32 v[66:67], s[0:1], v121, s18, v[74:75]
	v_cvt_pk_bf16_f32 v63, v78, v79
	v_cvt_pk_bf16_f32 v64, v82, v83
	v_cvt_pk_bf16_f32 v65, v76, v77
	v_lshl_add_u64 v[66:67], v[66:67], 0, v[114:115]
	global_store_dwordx4 v[66:67], v[62:65], off
	v_lshlrev_b32_e32 v66, 16, v58
	v_and_b32_e32 v67, 0xffff0000, v58
	v_fma_f32 v62, v34, v98, v50
	v_fma_f32 v63, v35, v99, v51
	s_nop 0
	v_fma_f32 v62, v38, v90, v62
	v_fma_f32 v63, v39, v91, v63
	s_nop 0
	v_fma_f32 v62, v42, v80, v62
	v_fma_f32 v63, v43, v81, v63
	s_nop 0
	v_fma_f32 v62, v46, v66, v62
	v_fma_f32 v63, v47, v67, v63
	s_nop 0
	v_mul_f32_e32 v58, 0xbfb8aa3b, v62
	v_exp_f32_e32 v58, v58
	s_nop 0
	v_add_f32_e32 v58, 1.0, v58
	v_rcp_f32_e32 v64, v58
	v_mul_f32_e32 v58, 0xbfb8aa3b, v63
	v_exp_f32_e32 v58, v58
	s_nop 0
	v_add_f32_e32 v58, 1.0, v58
	v_rcp_f32_e32 v65, v58
	s_nop 0
	v_mul_f32_e32 v76, v62, v64
	v_mul_f32_e32 v77, v63, v65
	v_lshlrev_b32_e32 v64, 16, v59
	v_and_b32_e32 v65, 0xffff0000, v59
	v_fma_f32 v58, v36, v96, v52
	v_fma_f32 v59, v37, v97, v53
	v_cvt_pk_bf16_f32 v76, v76, v77
	v_fma_f32 v58, v40, v88, v58
	v_fma_f32 v59, v41, v89, v59
	s_nop 0
	v_fma_f32 v58, v44, v72, v58
	v_fma_f32 v59, v45, v73, v59
	s_nop 0
	v_fma_f32 v58, v48, v64, v58
	v_fma_f32 v59, v49, v65, v59
	s_nop 0
	v_mul_f32_e32 v62, 0xbfb8aa3b, v58
	v_mul_f32_e32 v63, 0xbfb8aa3b, v59
	v_exp_f32_e32 v62, v62
	v_exp_f32_e32 v63, v63
	v_add_f32_e32 v62, 1.0, v62
	v_add_f32_e32 v63, 1.0, v63
	v_rcp_f32_e32 v62, v62
	v_rcp_f32_e32 v63, v63
	s_nop 0
	v_mul_f32_e32 v78, v58, v62
	v_mul_f32_e32 v79, v59, v63
	v_fma_f32 v58, v10, v94, v26
	v_fma_f32 v59, v11, v95, v27
	v_lshlrev_b32_e32 v62, 16, v60
	v_fma_f32 v58, v14, v86, v58
	v_fma_f32 v59, v15, v87, v59
	v_and_b32_e32 v63, 0xffff0000, v60
	v_fma_f32 v58, v18, v70, v58
	v_fma_f32 v59, v19, v71, v59
	v_cvt_pk_bf16_f32 v77, v78, v79
	v_fma_f32 v58, v22, v62, v58
	v_fma_f32 v59, v23, v63, v59
	s_nop 0
	v_mul_f32_e32 v60, 0xbfb8aa3b, v58
	v_exp_f32_e32 v60, v60
	s_nop 0
	v_add_f32_e32 v60, 1.0, v60
	v_rcp_f32_e32 v82, v60
	v_mul_f32_e32 v60, 0xbfb8aa3b, v59
	v_exp_f32_e32 v60, v60
	s_nop 0
	v_add_f32_e32 v60, 1.0, v60
	v_rcp_f32_e32 v83, v60
	s_nop 0
	v_mul_f32_e32 v82, v58, v82
	v_mul_f32_e32 v83, v59, v83
	v_lshlrev_b32_e32 v58, 16, v61
	v_and_b32_e32 v59, 0xffff0000, v61
	v_fma_f32 v60, v12, v92, v28
	v_fma_f32 v61, v13, v93, v29
	v_cvt_pk_bf16_f32 v78, v82, v83
	v_fma_f32 v60, v16, v84, v60
	v_fma_f32 v61, v17, v85, v61
	s_nop 0
	v_fma_f32 v60, v20, v68, v60
	v_fma_f32 v61, v21, v69, v61
	s_nop 0
	v_fma_f32 v60, v24, v58, v60
	v_fma_f32 v61, v25, v59, v61
	s_nop 0
	v_mul_f32_e32 v92, 0xbfb8aa3b, v60
	v_mul_f32_e32 v93, 0xbfb8aa3b, v61
	v_exp_f32_e32 v92, v92
	v_exp_f32_e32 v93, v93
	v_add_f32_e32 v92, 1.0, v92
	v_add_f32_e32 v93, 1.0, v93
	v_rcp_f32_e32 v92, v92
	v_rcp_f32_e32 v93, v93
; __device__ __forceinline__ float silu_f(float x) { return x * __builtin_amdgcn_rcpf(1.0f + __expf(-x)); }
; __device__ __forceinline__ float silu_f(float x) { return x * __builtin_amdgcn_rcpf(1.0f + __expf(-x)); }
; __device__ __forceinline__ unsigned cvtpk(float lo, float hi) { const f32x2v v = {lo, hi}; return __builtin_bit_cast(unsigned, __builtin_convertvector(v, bf16x2v)); }
; __device__ __forceinline__ void conv_phase(const MixP& C, const int G, const int tid) {
;     ...
;             for (int c = 0; c < 8; ++c) { p3[c] = head ? st[0][c >> 2][c & 3] : bfe(xr[0], c); p2[c] = head ? st[1][c >> 2][c & 3] : bfe(xr[1], c); p1[c] = head ? st[2][c >> 2][c & 3] : bfe(xr[2], c); }
; #pragma unroll
;             for (int et = 0; et < 8; ++et) {
;                 float val[8];
; #pragma unroll
;                 for (int c = 0; c < 8; ++c) { const float cur = bfe(xr[et + 3], c);
;                     val[c] = silu_f(bs[c] + wt[0][c] * p3[c] + wt[1][c] * p2[c] + wt[2][c] * p1[c] + wt[3][c] * cur); p3[c] = p2[c]; p2[c] = p1[c]; p1[c] = cur; }
;                 v4u wv; wv.x = cvtpk(val[0], val[1]); wv.y = cvtpk(val[2], val[3]); wv.z = cvtpk(val[4], val[5]); wv.w = cvtpk(val[6], val[7]);
;                 *(v4u*)(C.XC + (size_t)(row0 + et) * 768 + ch0) = wv;
;             }
	s_nop 0
	v_mul_f32_e32 v60, v60, v92
	v_mul_f32_e32 v61, v61, v93
	s_nop 0
	v_cvt_pk_bf16_f32 v79, v60, v61
	v_mad_i64_i32 v[60:61], s[0:1], v120, s18, v[74:75]
	v_lshl_add_u64 v[60:61], v[60:61], 0, v[114:115]
	global_store_dwordx4 v[60:61], v[76:79], off
	v_fma_f32 v60, v34, v90, v50
	v_fma_f32 v61, v35, v91, v51
	s_nop 0
	v_fma_f32 v60, v38, v80, v60
	v_fma_f32 v61, v39, v81, v61
	v_lshlrev_b32_e32 v78, 16, v54
	v_and_b32_e32 v79, 0xffff0000, v54
	v_fma_f32 v60, v42, v66, v60
	v_fma_f32 v61, v43, v67, v61
	v_fma_f32 v80, v34, v80, v50
	v_fma_f32 v81, v35, v81, v51
	v_fma_f32 v60, v46, v78, v60
	v_fma_f32 v61, v47, v79, v61
	v_fma_f32 v80, v38, v66, v80
	v_fma_f32 v81, v39, v67, v81
	v_mul_f32_e32 v54, 0xbfb8aa3b, v60
	v_exp_f32_e32 v54, v54
	v_fma_f32 v80, v42, v78, v80
	v_fma_f32 v81, v43, v79, v81
	v_add_f32_e32 v54, 1.0, v54
	v_rcp_f32_e32 v76, v54
	v_mul_f32_e32 v54, 0xbfb8aa3b, v61
	v_exp_f32_e32 v54, v54
	s_nop 0
	v_add_f32_e32 v54, 1.0, v54
	v_rcp_f32_e32 v77, v54
	s_nop 0
	v_mul_f32_e32 v82, v60, v76
	v_mul_f32_e32 v83, v61, v77
	v_lshlrev_b32_e32 v76, 16, v55
	v_and_b32_e32 v77, 0xffff0000, v55
	v_fma_f32 v54, v36, v88, v52
	v_fma_f32 v55, v37, v89, v53
	v_cvt_pk_bf16_f32 v82, v82, v83
	v_fma_f32 v54, v40, v72, v54
	v_fma_f32 v55, v41, v73, v55
	s_nop 0
	v_fma_f32 v54, v44, v64, v54
	v_fma_f32 v55, v45, v65, v55
	s_nop 0
	v_fma_f32 v54, v48, v76, v54
	v_fma_f32 v55, v49, v77, v55
	s_nop 0
	v_mul_f32_e32 v60, 0xbfb8aa3b, v54
	v_mul_f32_e32 v61, 0xbfb8aa3b, v55
	v_exp_f32_e32 v60, v60
	v_exp_f32_e32 v61, v61
	v_add_f32_e32 v60, 1.0, v60
	v_add_f32_e32 v61, 1.0, v61
	v_rcp_f32_e32 v60, v60
	v_rcp_f32_e32 v61, v61
	s_nop 0
	v_mul_f32_e32 v88, v54, v60
	v_mul_f32_e32 v89, v55, v61
	v_fma_f32 v54, v10, v86, v26
	v_fma_f32 v55, v11, v87, v27
	v_lshlrev_b32_e32 v60, 16, v56
	v_fma_f32 v54, v14, v70, v54
	v_fma_f32 v55, v15, v71, v55
	v_and_b32_e32 v61, 0xffff0000, v56
	v_fma_f32 v54, v18, v62, v54
	v_fma_f32 v55, v19, v63, v55
	v_cvt_pk_bf16_f32 v83, v88, v89
	v_fma_f32 v54, v22, v60, v54
	v_fma_f32 v55, v23, v61, v55
	s_nop 0
	v_mul_f32_e32 v56, 0xbfb8aa3b, v54
	v_exp_f32_e32 v56, v56
	s_nop 0
	v_add_f32_e32 v56, 1.0, v56
	v_rcp_f32_e32 v86, v56
	v_mul_f32_e32 v56, 0xbfb8aa3b, v55
	v_exp_f32_e32 v56, v56
	s_nop 0
	v_add_f32_e32 v56, 1.0, v56
	v_rcp_f32_e32 v87, v56
	s_nop 0
	v_mul_f32_e32 v86, v54, v86
	v_mul_f32_e32 v87, v55, v87
	v_lshlrev_b32_e32 v54, 16, v57
	v_and_b32_e32 v55, 0xffff0000, v57
	v_fma_f32 v56, v12, v84, v28
	v_fma_f32 v57, v13, v85, v29
	s_nop 0
	v_fma_f32 v56, v16, v68, v56
	v_fma_f32 v57, v17, v69, v57
	s_nop 0
	v_fma_f32 v56, v20, v58, v56
	v_fma_f32 v57, v21, v59, v57
	s_nop 0
	v_fma_f32 v56, v24, v54, v56
	v_fma_f32 v57, v25, v55, v57
	s_nop 0
	v_mul_f32_e32 v84, 0xbfb8aa3b, v56
	v_mul_f32_e32 v85, 0xbfb8aa3b, v57
	v_exp_f32_e32 v84, v84
	v_exp_f32_e32 v85, v85
	v_add_f32_e32 v84, 1.0, v84
	v_add_f32_e32 v85, 1.0, v85
	v_rcp_f32_e32 v84, v84
	v_rcp_f32_e32 v85, v85
	s_nop 0
	v_mul_f32_e32 v56, v56, v84
	v_mul_f32_e32 v57, v57, v85
	s_nop 0
	v_cvt_pk_bf16_f32 v85, v56, v57
	v_mad_i64_i32 v[56:57], s[0:1], v119, s18, v[74:75]
	v_cvt_pk_bf16_f32 v84, v86, v87
	v_lshl_add_u64 v[56:57], v[56:57], 0, v[114:115]
	global_store_dwordx4 v[56:57], v[82:85], off
	v_lshlrev_b32_e32 v56, 16, v30
	v_and_b32_e32 v57, 0xffff0000, v30
	v_fma_f32 v80, v46, v56, v80
	v_fma_f32 v81, v47, v57, v81
	v_lshlrev_b32_e32 v84, 16, v32
	v_mul_f32_e32 v30, 0xbfb8aa3b, v80
	v_exp_f32_e32 v30, v30
	v_and_b32_e32 v85, 0xffff0000, v32
	v_lshlrev_b32_e32 v86, 16, v33
	v_and_b32_e32 v87, 0xffff0000, v33
	v_add_f32_e32 v30, 1.0, v30
	v_rcp_f32_e32 v82, v30
	v_mul_f32_e32 v30, 0xbfb8aa3b, v81
	v_exp_f32_e32 v30, v30
	s_nop 0
	v_add_f32_e32 v30, 1.0, v30
	v_rcp_f32_e32 v83, v30
	s_nop 0
	v_mul_f32_e32 v80, v80, v82
	v_mul_f32_e32 v81, v81, v83
	v_lshlrev_b32_e32 v82, 16, v31
	v_and_b32_e32 v83, 0xffff0000, v31
	v_fma_f32 v30, v36, v72, v52
	v_fma_f32 v31, v37, v73, v53
	s_nop 0
	v_fma_f32 v30, v40, v64, v30
	v_fma_f32 v31, v41, v65, v31
	s_nop 0
	v_fma_f32 v30, v44, v76, v30
	v_fma_f32 v31, v45, v77, v31
	s_nop 0
	v_fma_f32 v30, v48, v82, v30
	v_fma_f32 v31, v49, v83, v31
	s_nop 0
	v_mul_f32_e32 v72, 0xbfb8aa3b, v30
	v_mul_f32_e32 v73, 0xbfb8aa3b, v31
	v_exp_f32_e32 v72, v72
	v_exp_f32_e32 v73, v73
	v_add_f32_e32 v72, 1.0, v72
	v_add_f32_e32 v73, 1.0, v73
	v_rcp_f32_e32 v72, v72
	v_rcp_f32_e32 v73, v73
; __device__ __forceinline__ float silu_f(float x) { return x * __builtin_amdgcn_rcpf(1.0f + __expf(-x)); }
; __device__ __forceinline__ float silu_f(float x) { return x * __builtin_amdgcn_rcpf(1.0f + __expf(-x)); }
; __device__ __forceinline__ unsigned cvtpk(float lo, float hi) { const f32x2v v = {lo, hi}; return __builtin_bit_cast(unsigned, __builtin_convertvector(v, bf16x2v)); }
; __device__ __forceinline__ void conv_phase(const MixP& C, const int G, const int tid) {
;     ...
;     for (int task = blockIdx.x * NTHREADS + tid; task < NTASK; task += G * NTHREADS) {
;         const int g8 = task / 96, bl = task - g8 * 96, ch0 = 8 * bl, row0 = 8 * g8;
;     ...
;             for (int et = 0; et < 8; ++et) {
;                 float val[8];
; #pragma unroll
;                 for (int c = 0; c < 8; ++c) { const float cur = bfe(xr[et + 3], c);
;                     val[c] = silu_f(bs[c] + wt[0][c] * p3[c] + wt[1][c] * p2[c] + wt[2][c] * p1[c] + wt[3][c] * cur); p3[c] = p2[c]; p2[c] = p1[c]; p1[c] = cur; }
;                 v4u wv; wv.x = cvtpk(val[0], val[1]); wv.y = cvtpk(val[2], val[3]); wv.z = cvtpk(val[4], val[5]); wv.w = cvtpk(val[6], val[7]);
;                 *(v4u*)(C.XC + (size_t)(row0 + et) * 768 + ch0) = wv;
;             }
	s_nop 0
	v_mul_f32_e32 v72, v30, v72
	v_mul_f32_e32 v73, v31, v73
	v_fma_f32 v30, v10, v70, v26
	v_fma_f32 v31, v11, v71, v27
	v_fma_f32 v10, v10, v62, v26
	v_fma_f32 v11, v11, v63, v27
	v_fma_f32 v30, v14, v62, v30
	v_fma_f32 v31, v15, v63, v31
	v_fma_f32 v10, v14, v60, v10
	v_fma_f32 v11, v15, v61, v11
	v_fma_f32 v30, v18, v60, v30
	v_fma_f32 v31, v19, v61, v31
	v_fma_f32 v10, v18, v84, v10
	v_fma_f32 v11, v19, v85, v11
	v_fma_f32 v30, v22, v84, v30
	v_fma_f32 v31, v23, v85, v31
	s_nop 0
	v_mul_f32_e32 v32, 0xbfb8aa3b, v30
	v_exp_f32_e32 v32, v32
	s_nop 0
	v_add_f32_e32 v32, 1.0, v32
	v_rcp_f32_e32 v70, v32
	v_mul_f32_e32 v32, 0xbfb8aa3b, v31
	v_exp_f32_e32 v32, v32
	s_nop 0
	v_add_f32_e32 v32, 1.0, v32
	v_rcp_f32_e32 v71, v32
	s_nop 0
	v_mul_f32_e32 v70, v30, v70
	v_mul_f32_e32 v71, v31, v71
	v_fma_f32 v30, v12, v68, v28
	v_fma_f32 v31, v13, v69, v29
	s_nop 0
	v_fma_f32 v30, v16, v58, v30
	v_fma_f32 v31, v17, v59, v31
	s_nop 0
	v_fma_f32 v30, v20, v54, v30
	v_fma_f32 v31, v21, v55, v31
	s_nop 0
	v_fma_f32 v30, v24, v86, v30
	v_fma_f32 v31, v25, v87, v31
	s_nop 0
	v_mul_f32_e32 v32, 0xbfb8aa3b, v30
	v_mul_f32_e32 v33, 0xbfb8aa3b, v31
	v_exp_f32_e32 v32, v32
	v_exp_f32_e32 v33, v33
	v_add_f32_e32 v32, 1.0, v32
	v_add_f32_e32 v33, 1.0, v33
	v_rcp_f32_e32 v32, v32
	v_rcp_f32_e32 v33, v33
	s_nop 0
	v_mul_f32_e32 v68, v30, v32
	v_mul_f32_e32 v69, v31, v33
	s_nop 0
	v_cvt_pk_bf16_f32 v33, v68, v69
	v_mad_i64_i32 v[68:69], s[0:1], v118, s18, v[74:75]
	v_cvt_pk_bf16_f32 v30, v80, v81
	v_cvt_pk_bf16_f32 v31, v72, v73
	v_cvt_pk_bf16_f32 v32, v70, v71
	v_lshl_add_u64 v[68:69], v[68:69], 0, v[114:115]
	global_store_dwordx4 v[68:69], v[30:33], off
	s_nop 1
	v_fma_f32 v32, v34, v66, v50
	v_fma_f32 v33, v35, v67, v51
	v_lshlrev_b32_e32 v30, 16, v6
	v_fma_f32 v32, v38, v78, v32
	v_fma_f32 v33, v39, v79, v33
	v_and_b32_e32 v31, 0xffff0000, v6
	v_fma_f32 v32, v42, v56, v32
	v_fma_f32 v33, v43, v57, v33
	s_nop 0
	v_fma_f32 v30, v46, v30, v32
	v_fma_f32 v31, v47, v31, v33
	s_nop 0
	v_mul_f32_e32 v6, 0xbfb8aa3b, v30
	v_exp_f32_e32 v6, v6
	s_nop 0
	v_add_f32_e32 v6, 1.0, v6
	v_rcp_f32_e32 v32, v6
	v_mul_f32_e32 v6, 0xbfb8aa3b, v31
	v_exp_f32_e32 v6, v6
	s_nop 0
	v_add_f32_e32 v6, 1.0, v6
	v_rcp_f32_e32 v33, v6
	v_lshlrev_b32_e32 v6, 16, v7
	v_and_b32_e32 v7, 0xffff0000, v7
	v_mul_f32_e32 v30, v30, v32
	v_mul_f32_e32 v31, v31, v33
	v_fma_f32 v32, v36, v64, v52
	v_fma_f32 v33, v37, v65, v53
	s_nop 0
	v_fma_f32 v32, v40, v76, v32
	v_fma_f32 v33, v41, v77, v33
	s_nop 0
	v_fma_f32 v32, v44, v82, v32
	v_fma_f32 v33, v45, v83, v33
	s_nop 0
	v_fma_f32 v6, v48, v6, v32
	v_fma_f32 v7, v49, v7, v33
	s_nop 0
	v_mul_f32_e32 v32, 0xbfb8aa3b, v6
	v_mul_f32_e32 v33, 0xbfb8aa3b, v7
	v_exp_f32_e32 v32, v32
	v_exp_f32_e32 v33, v33
	v_add_f32_e32 v32, 1.0, v32
	v_add_f32_e32 v33, 1.0, v33
	v_rcp_f32_e32 v32, v32
	v_rcp_f32_e32 v33, v33
	s_nop 0
	v_mul_f32_e32 v32, v6, v32
	v_mul_f32_e32 v33, v7, v33
	v_lshlrev_b32_e32 v6, 16, v8
	v_and_b32_e32 v7, 0xffff0000, v8
	v_fma_f32 v6, v22, v6, v10
	v_fma_f32 v7, v23, v7, v11
	s_nop 0
	v_mul_f32_e32 v8, 0xbfb8aa3b, v6
	v_exp_f32_e32 v8, v8
	s_nop 0
	v_add_f32_e32 v8, 1.0, v8
	v_rcp_f32_e32 v10, v8
	v_mul_f32_e32 v8, 0xbfb8aa3b, v7
	v_exp_f32_e32 v8, v8
	s_nop 0
	v_add_f32_e32 v8, 1.0, v8
	v_rcp_f32_e32 v11, v8
	s_nop 0
	v_mul_f32_e32 v10, v6, v10
	v_mul_f32_e32 v11, v7, v11
	v_lshlrev_b32_e32 v6, 16, v9
	v_and_b32_e32 v7, 0xffff0000, v9
	v_fma_f32 v8, v12, v58, v28
	v_fma_f32 v9, v13, v59, v29
	s_nop 0
	v_fma_f32 v8, v16, v54, v8
	v_fma_f32 v9, v17, v55, v9
	s_nop 0
	v_fma_f32 v8, v20, v86, v8
	v_fma_f32 v9, v21, v87, v9
	s_nop 0
	v_fma_f32 v6, v24, v6, v8
	v_fma_f32 v7, v25, v7, v9
	s_nop 0
	v_mul_f32_e32 v8, 0xbfb8aa3b, v6
	v_mul_f32_e32 v9, 0xbfb8aa3b, v7
	v_exp_f32_e32 v8, v8
	v_exp_f32_e32 v9, v9
	v_add_f32_e32 v8, 1.0, v8
	v_add_f32_e32 v9, 1.0, v9
	v_rcp_f32_e32 v8, v8
	v_rcp_f32_e32 v9, v9
	s_nop 0
	v_mul_f32_e32 v12, v6, v8
	v_mul_f32_e32 v13, v7, v9
	v_cvt_pk_bf16_f32 v8, v10, v11
	v_mad_i64_i32 v[10:11], s[0:1], v5, s18, v[74:75]
	s_mov_b32 s0, 0x32fff
	s_nop 0
	v_cmp_lt_i32_e32 vcc, s0, v3
	v_cvt_pk_bf16_f32 v6, v30, v31
	v_cvt_pk_bf16_f32 v7, v32, v33
	v_cvt_pk_bf16_f32 v9, v12, v13
	v_lshl_add_u64 v[10:11], v[10:11], 0, v[114:115]
	s_or_b64 s[24:25], vcc, s[24:25]
	global_store_dwordx4 v[10:11], v[6:9], off
	s_andn2_b64 exec, exec, s[24:25]
	s_cbranch_execz .LBB0_630

; #define LAS __attribute__((address_space(3)))
; __device__ __forceinline__ void cvt_finish(const CvtItem& c, const int lane, LAS float* scr, const f32x4 (&vv)[8], const float (&gv)[8]) {
;     ...
;         const int kr = lane >> 3, nq = lane & 7;
; #pragma unroll
;         for (int i = 0; i < 8; ++i) { LAS float* sp = scr + (8 * i + kr) * 33 + 4 * nq; const f32x4 v = vv[i] * gv[i]; sp[0] = v[0]; sp[1] = v[1]; sp[2] = v[2]; sp[3] = v[3]; }
.LBB0_707:
	s_xor_b64 s[12:13], s[8:9], -1
	s_mov_b64 s[0:1], -1
	s_and_b64 vcc, exec, s[12:13]
	s_cbranch_vccz .LBB0_709
	v_mul_f32_e32 v92, v24, v6
	v_mul_f32_e32 v93, v25, v6
	v_mul_f32_e32 v94, v22, v6
	v_mul_f32_e32 v95, v23, v6
	ds_write2_b32 v102, v94, v95 offset1:1
	ds_write2_b32 v102, v92, v93 offset0:2 offset1:3
	v_pk_mul_f32 v[92:93], v[28:29], v[6:7] op_sel:[0,1]
	v_pk_mul_f32 v[94:95], v[26:27], v[6:7] op_sel:[0,1]
	ds_write2_b32 v103, v94, v95 offset1:1
	ds_write2_b32 v103, v92, v93 offset0:2 offset1:3
	v_mul_f32_e32 v92, v32, v8
	v_mul_f32_e32 v93, v33, v8
	v_mul_f32_e32 v94, v30, v8
	v_mul_f32_e32 v95, v31, v8
	ds_write2_b32 v104, v94, v95 offset1:1
	ds_write2_b32 v104, v92, v93 offset0:2 offset1:3
	v_mov_b32_e32 v92, v9
	v_mul_f32_e32 v94, v36, v92
	v_mul_f32_e32 v95, v37, v92
	v_mul_f32_e32 v93, v35, v92
	v_mul_f32_e32 v92, v34, v92
	ds_write2_b32 v105, v92, v93 offset1:1
	ds_write2_b32 v105, v94, v95 offset0:2 offset1:3
	v_mul_f32_e32 v94, v38, v10
	v_mul_f32_e32 v95, v39, v10
	v_add_u32_e32 v89, 0x1080, v102
	v_mul_f32_e32 v92, v40, v10
	v_mul_f32_e32 v93, v41, v10
	ds_write2_b32 v89, v94, v95 offset1:1
	v_add_u32_e32 v89, 0x1088, v102
	ds_write2_b32 v89, v92, v93 offset1:1
	v_mov_b32_e32 v92, v11
	v_mul_f32_e32 v94, v44, v92
	v_mul_f32_e32 v95, v45, v92
	v_mul_f32_e32 v93, v43, v92
	v_mul_f32_e32 v92, v42, v92
	v_add_u32_e32 v89, 0x14a0, v102
	ds_write2_b32 v89, v92, v93 offset1:1
	v_add_u32_e32 v89, 0x14a8, v102
	ds_write2_b32 v89, v94, v95 offset1:1
	v_mul_f32_e32 v94, v46, v12
	v_mul_f32_e32 v95, v47, v12
	v_add_u32_e32 v89, 0x18c0, v102
	v_mul_f32_e32 v92, v48, v12
	v_mul_f32_e32 v93, v49, v12
	ds_write2_b32 v89, v94, v95 offset1:1
	v_add_u32_e32 v89, 0x18c8, v102
	ds_write2_b32 v89, v92, v93 offset1:1
	v_mov_b32_e32 v92, v13
	v_mul_f32_e32 v94, v52, v92
	v_mul_f32_e32 v95, v53, v92
	v_mul_f32_e32 v93, v51, v92
	v_mul_f32_e32 v92, v50, v92
	v_add_u32_e32 v89, 0x1ce0, v102
	ds_write2_b32 v89, v92, v93 offset1:1
	v_add_u32_e32 v89, 0x1ce8, v102
	ds_write2_b32 v89, v94, v95 offset1:1
	s_mov_b64 s[0:1], 0

; __device__ __forceinline__ void final_phase(const Args& A, int wave, int lane, int G) {
;     ...
;     for (int m0 = gw; m0 < M; m0 += 2 * NGW) {
;         const int m1 = m0 + NGW; const bool two = m1 < M; const int m1c = two ? m1 : m0;
;         const float q0 = rss[m0], q1 = rss[m1c];
;         const v2u* x0 = (const v2u*)(xb + (size_t)m0 * D) + lane; const v2u* x1 = (const v2u*)(xb + (size_t)m1c * D) + lane;
;         v2u w0[4], w1[4];
; #pragma unroll
;         for (int j = 0; j < 4; ++j) { w0[j] = x0[64 * j]; w1[j] = x1[64 * j]; }
;         const float r0 = rsqrtf(q0 * (1.0f / 1024.0f) + 1e-6f), r1 = rsqrtf(q1 * (1.0f / 1024.0f) + 1e-6f);
;         f32x4* y0 = (f32x4*)(A.out + (size_t)m0 * D) + lane; f32x4* y1 = (f32x4*)(A.out + (size_t)m1c * D) + lane;
; #pragma unroll
;         for (int j = 0; j < 4; ++j) { const v2u w = w0[j]; const f32x4 v = {__builtin_bit_cast(float, w.x << 16), __builtin_bit_cast(float, w.x & 0xffff0000u), __builtin_bit_cast(float, w.y << 16), __builtin_bit_cast(float, w.y & 0xffff0000u)};
;             y0[64 * j] = v * r0 * g4[j]; }
;         if (two) {
; #pragma unroll
;             for (int j = 0; j < 4; ++j) { const v2u w = w1[j]; const f32x4 v = {__builtin_bit_cast(float, w.x << 16), __builtin_bit_cast(float, w.x & 0xffff0000u), __builtin_bit_cast(float, w.y << 16), __builtin_bit_cast(float, w.y & 0xffff0000u)};
;                 y1[64 * j] = v * r1 * g4[j]; }
;         }
;     }
.LBB0_943:
	s_add_i32 s3, s4, s96
	s_cmpk_lt_i32 s3, 0x4400
	s_cselect_b32 s0, s3, s4
	s_ashr_i32 s5, s4, 31
	s_lshl_b64 s[6:7], s[4:5], 2
	v_readlane_b32 s10, v252, 48
	s_add_u32 s6, s10, s6
	v_readlane_b32 s11, v252, 49
	s_addc_u32 s7, s11, s7
	global_load_dword v40, v4, s[6:7]
	s_ashr_i32 s1, s0, 31
	s_lshl_b64 s[8:9], s[0:1], 2
	s_add_u32 s6, s10, s8
	s_addc_u32 s7, s11, s9
	s_lshl_b64 s[8:9], s[4:5], 11
	s_waitcnt vmcnt(5)
	v_lshl_add_u64 v[24:25], v[2:3], 0, s[8:9]
	s_lshl_b64 s[8:9], s[0:1], 11
	global_load_dwordx2 v[32:33], v[24:25], off
	global_load_dwordx2 v[34:35], v[24:25], off offset:512
	global_load_dwordx2 v[36:37], v[24:25], off offset:1024
	global_load_dwordx2 v[38:39], v[24:25], off offset:1536
	v_lshl_add_u64 v[24:25], v[2:3], 0, s[8:9]
	global_load_dwordx2 v[28:29], v[24:25], off offset:512
	global_load_dwordx2 v[30:31], v[24:25], off
	global_load_dword v5, v4, s[6:7]
	global_load_dwordx2 v[26:27], v[24:25], off offset:1024
	s_nop 0
	global_load_dwordx2 v[24:25], v[24:25], off offset:1536
	s_lshl_b64 s[4:5], s[4:5], 12
	v_lshl_add_u64 v[48:49], v[22:23], 0, s[4:5]
	s_mov_b32 s4, 0x800000
	s_cmpk_gt_i32 s3, 0x43ff
	s_waitcnt vmcnt(9)
	v_fmamk_f32 v40, v40, 0x3a800000, v231
	v_mul_f32_e32 v41, 0x4b800000, v40
	v_cmp_gt_f32_e32 vcc, s4, v40
	s_waitcnt vmcnt(7)
	v_lshlrev_b32_e32 v42, 16, v34
	v_cndmask_b32_e32 v40, v40, v41, vcc
	v_rsq_f32_e32 v50, v40
	v_lshlrev_b32_e32 v40, 16, v32
	v_and_b32_e32 v41, 0xffff0000, v32
	v_lshlrev_b32_e32 v32, 16, v33
	v_mul_f32_e32 v51, 0x45800000, v50
	v_and_b32_e32 v33, 0xffff0000, v33
	v_cndmask_b32_e32 v50, v50, v51, vcc
	v_and_b32_e32 v43, 0xffff0000, v34
	v_lshlrev_b32_e32 v34, 16, v35
	v_and_b32_e32 v35, 0xffff0000, v35
	s_waitcnt vmcnt(6)
	v_lshlrev_b32_e32 v44, 16, v36
	v_and_b32_e32 v45, 0xffff0000, v36
	v_lshlrev_b32_e32 v36, 16, v37
	v_and_b32_e32 v37, 0xffff0000, v37
	s_waitcnt vmcnt(5)
	v_lshlrev_b32_e32 v46, 16, v38
	v_and_b32_e32 v47, 0xffff0000, v38
	v_lshlrev_b32_e32 v38, 16, v39
	v_and_b32_e32 v39, 0xffff0000, v39
	v_mul_f32_e32 v40, v50, v40
	v_mul_f32_e32 v41, v50, v41
	v_mul_f32_e32 v32, v50, v32
	v_mul_f32_e32 v33, v50, v33
	v_mul_f32_e32 v42, v50, v42
	v_mul_f32_e32 v43, v50, v43
	v_mul_f32_e32 v52, v50, v34
	v_mul_f32_e32 v53, v50, v35
	v_mul_f32_e32 v44, v50, v44
	v_mul_f32_e32 v45, v50, v45
	v_mul_f32_e32 v54, v50, v36
	v_mul_f32_e32 v55, v50, v37
	v_mul_f32_e32 v56, v50, v46
	v_mul_f32_e32 v57, v50, v47
	v_mul_f32_e32 v46, v50, v38
	v_mul_f32_e32 v47, v50, v39
	v_mul_f32_e32 v34, v8, v32
	v_mul_f32_e32 v35, v9, v33
	v_mul_f32_e32 v32, v6, v40
	v_mul_f32_e32 v33, v7, v41
	v_mul_f32_e32 v38, v12, v52
	v_mul_f32_e32 v39, v13, v53
	v_mul_f32_e32 v36, v10, v42
	v_mul_f32_e32 v37, v11, v43
	v_mul_f32_e32 v42, v16, v54
	v_mul_f32_e32 v43, v17, v55
	v_mul_f32_e32 v40, v14, v44
	v_mul_f32_e32 v41, v15, v45
	v_mul_f32_e32 v46, v20, v46
	v_mul_f32_e32 v47, v21, v47
	v_mul_f32_e32 v44, v18, v56
	v_mul_f32_e32 v45, v19, v57
	global_store_dwordx4 v[48:49], v[32:35], off
	global_store_dwordx4 v[48:49], v[36:39], off offset:1024
	global_store_dwordx4 v[48:49], v[40:43], off offset:2048
	global_store_dwordx4 v[48:49], v[44:47], off offset:3072
	s_cbranch_scc1 .LBB0_942
	s_waitcnt vmcnt(6)
	v_fmamk_f32 v5, v5, 0x3a800000, v231
	v_mul_f32_e32 v32, 0x4b800000, v5
	v_cmp_gt_f32_e32 vcc, s4, v5
	v_and_b32_e32 v33, 0xffff0000, v30
	s_lshl_b64 s[0:1], s[0:1], 10
	v_cndmask_b32_e32 v5, v5, v32, vcc
	v_rsq_f32_e32 v5, v5
	v_lshl_add_u64 v[34:35], s[0:1], 2, v[22:23]
	v_mul_f32_e32 v32, 0x45800000, v5
	v_cndmask_b32_e32 v36, v5, v32, vcc
	v_lshlrev_b32_e32 v32, 16, v30
	v_lshlrev_b32_e32 v30, 16, v31
	v_and_b32_e32 v31, 0xffff0000, v31
	v_mul_f32_e32 v38, v36, v32
	v_mul_f32_e32 v39, v36, v33
	v_mul_f32_e32 v30, v36, v30
	v_mul_f32_e32 v31, v36, v31
	v_mul_f32_e32 v32, v8, v30
	v_mul_f32_e32 v33, v9, v31
	v_mul_f32_e32 v30, v6, v38
	v_mul_f32_e32 v31, v7, v39
	global_store_dwordx4 v[34:35], v[30:33], off
	s_nop 1
	v_lshlrev_b32_e32 v30, 16, v28
	v_and_b32_e32 v31, 0xffff0000, v28
	v_lshlrev_b32_e32 v28, 16, v29
	v_and_b32_e32 v29, 0xffff0000, v29
	v_mul_f32_e32 v32, v36, v30
	v_mul_f32_e32 v33, v36, v31
	v_mul_f32_e32 v28, v36, v28
	v_mul_f32_e32 v29, v36, v29
	v_mul_f32_e32 v30, v12, v28
	v_mul_f32_e32 v31, v13, v29
	v_mul_f32_e32 v28, v10, v32
	v_mul_f32_e32 v29, v11, v33
	global_store_dwordx4 v[34:35], v[28:31], off offset:1024
	s_waitcnt vmcnt(7)
	s_nop 0
	v_lshlrev_b32_e32 v28, 16, v26
	v_and_b32_e32 v29, 0xffff0000, v26
	v_lshlrev_b32_e32 v26, 16, v27
	v_and_b32_e32 v27, 0xffff0000, v27
	v_mul_f32_e32 v30, v36, v28
	v_mul_f32_e32 v31, v36, v29
	v_mul_f32_e32 v26, v36, v26
	v_mul_f32_e32 v27, v36, v27
	v_mul_f32_e32 v28, v16, v26
	v_mul_f32_e32 v29, v17, v27
	v_mul_f32_e32 v26, v14, v30
	v_mul_f32_e32 v27, v15, v31
	global_store_dwordx4 v[34:35], v[26:29], off offset:2048
	s_waitcnt vmcnt(7)
	s_nop 0
	v_lshlrev_b32_e32 v26, 16, v24
	v_and_b32_e32 v27, 0xffff0000, v24
	v_lshlrev_b32_e32 v24, 16, v25
	v_and_b32_e32 v25, 0xffff0000, v25
	v_mul_f32_e32 v28, v36, v26
	v_mul_f32_e32 v29, v36, v27
	v_mul_f32_e32 v24, v36, v24
	v_mul_f32_e32 v25, v36, v25
	v_mul_f32_e32 v26, v20, v24
	v_mul_f32_e32 v27, v21, v25
	v_mul_f32_e32 v24, v18, v28
	v_mul_f32_e32 v25, v19, v29
	global_store_dwordx4 v[34:35], v[24:27], off offset:3072
	s_branch .LBB0_942

; #define LAS __attribute__((address_space(3)))
; __device__ __forceinline__ void cvt_finish(const CvtItem& c, const int lane, LAS float* scr, const f32x4 (&vv)[8], const float (&gv)[8]) {
;     ...
;         const int kr = lane >> 3, nq = lane & 7;
; #pragma unroll
;         for (int i = 0; i < 8; ++i) { LAS float* sp = scr + (8 * i + kr) * 33 + 4 * nq; const f32x4 v = vv[i] * gv[i]; sp[0] = v[0]; sp[1] = v[1]; sp[2] = v[2]; sp[3] = v[3]; }
.LBB0_1033:
	s_xor_b64 s[12:13], s[20:21], -1
	s_mov_b64 s[0:1], -1
	s_and_b64 vcc, exec, s[12:13]
	s_cbranch_vccz .LBB0_1035
	v_mul_f32_e32 v90, v24, v6
	v_mul_f32_e32 v91, v25, v6
	v_mul_f32_e32 v92, v22, v6
	v_mul_f32_e32 v93, v23, v6
	ds_write2_b32 v99, v92, v93 offset1:1
	ds_write2_b32 v99, v90, v91 offset0:2 offset1:3
	v_pk_mul_f32 v[90:91], v[28:29], v[6:7] op_sel:[0,1]
	v_pk_mul_f32 v[92:93], v[26:27], v[6:7] op_sel:[0,1]
	ds_write2_b32 v100, v92, v93 offset1:1
	ds_write2_b32 v100, v90, v91 offset0:2 offset1:3
	v_mul_f32_e32 v90, v32, v8
	v_mul_f32_e32 v91, v33, v8
	v_mul_f32_e32 v92, v30, v8
	v_mul_f32_e32 v93, v31, v8
	ds_write2_b32 v101, v92, v93 offset1:1
	ds_write2_b32 v101, v90, v91 offset0:2 offset1:3
	v_mov_b32_e32 v90, v9
	v_mul_f32_e32 v92, v36, v90
	v_mul_f32_e32 v93, v37, v90
	v_mul_f32_e32 v91, v35, v90
	v_mul_f32_e32 v90, v34, v90
	ds_write2_b32 v102, v90, v91 offset1:1
	ds_write2_b32 v102, v92, v93 offset0:2 offset1:3
	v_mul_f32_e32 v92, v38, v10
	v_mul_f32_e32 v93, v39, v10
	v_add_u32_e32 v89, 0x1080, v99
	v_mul_f32_e32 v90, v40, v10
	v_mul_f32_e32 v91, v41, v10
	ds_write2_b32 v89, v92, v93 offset1:1
	v_add_u32_e32 v89, 0x1088, v99
	ds_write2_b32 v89, v90, v91 offset1:1
	v_mov_b32_e32 v90, v11
	v_mul_f32_e32 v92, v44, v90
	v_mul_f32_e32 v93, v45, v90
	v_mul_f32_e32 v91, v43, v90
	v_mul_f32_e32 v90, v42, v90
	v_add_u32_e32 v89, 0x14a0, v99
	ds_write2_b32 v89, v90, v91 offset1:1
	v_add_u32_e32 v89, 0x14a8, v99
	ds_write2_b32 v89, v92, v93 offset1:1
	v_mul_f32_e32 v92, v46, v12
	v_mul_f32_e32 v93, v47, v12
	v_add_u32_e32 v89, 0x18c0, v99
	v_mul_f32_e32 v90, v48, v12
	v_mul_f32_e32 v91, v49, v12
	ds_write2_b32 v89, v92, v93 offset1:1
	v_add_u32_e32 v89, 0x18c8, v99
	ds_write2_b32 v89, v90, v91 offset1:1
	v_mov_b32_e32 v90, v13
	v_mul_f32_e32 v92, v52, v90
	v_mul_f32_e32 v93, v53, v90
	v_mul_f32_e32 v91, v51, v90
	v_mul_f32_e32 v90, v50, v90
	v_add_u32_e32 v89, 0x1ce0, v99
	ds_write2_b32 v89, v90, v91 offset1:1
	v_add_u32_e32 v89, 0x1ce8, v99
	ds_write2_b32 v89, v92, v93 offset1:1
	s_mov_b64 s[0:1], 0
